# pooling fast path now covers all prompt rows (truncated windows at sequence start use the IEEE division sequence), window groups alternate per wave for balance; hipcc loop only does the sample rows
# speedup vs baseline: 1.1009x; 1.0095x over previous
.LBB0_1246:
	v_readlane_b32 s4, v254, 2
	v_readlane_b32 s5, v254, 3
	s_cmp_lt_i32 s4, 14
	s_cselect_b64 s[0:1], -1, 0
	s_cmp_gt_i32 s5, 12
	s_cselect_b64 s[2:3], -1, 0
	s_and_b64 s[0:1], s[0:1], s[2:3]
	s_andn2_b64 vcc, exec, s[0:1]
	v_mov_b32_e32 v1, s5
	v_mov_b32_e32 v0, s4
	v_lshl_add_u32 v198, s46, 8, v196
	s_cbranch_vccnz .LBB0_1314
	s_load_dwordx4 s[8:11], s[92:93], 0x150
	s_load_dwordx2 s[12:13], s[92:93], 0xf8
	v_lshrrev_b32_e32 v8, 6, v196
	v_and_b32_e32 v10, 63, v196
	s_mov_b32 s15, s46
	v_readfirstlane_b32 s14, v8
	v_lshlrev_b32_e32 v10, 3, v10
	s_waitcnt lgkmcnt(0)
.Lp13f_loop:
	s_cmp_ge_u32 s15, 1024
	s_cbranch_scc1 .Lp13f_done
	s_lshl_b32 s16, s14, 9
	s_lshr_b32 s17, s15, 7
	s_and_b32 s18, s15, 127
	s_lshl_b32 s20, s15, 4
	v_add_u32_e32 v11, s16, v10
	s_lshl_b32 s21, s20, 11
	v_lshlrev_b32_e32 v12, 1, v11
	s_add_u32 s24, s10, s21
	s_addc_u32 s25, s11, 0
	s_cmp_eq_u32 s18, 0
	s_cbranch_scc1 .Lp13f_first
	s_cmp_eq_u32 s14, 0
	s_cbranch_scc1 .Lp13f_w0
	s_cmp_eq_u32 s14, 1
	s_cbranch_scc1 .Lp13f_w1
	s_cmp_eq_u32 s14, 2
	s_cbranch_scc1 .Lp13f_w2
	s_branch .Lp13f_w3
.Lp13f_first:
	s_cmp_eq_u32 s14, 0
	s_cbranch_scc1 .Lp13f_f0
	s_cmp_eq_u32 s14, 1
	s_cbranch_scc1 .Lp13f_f1
	s_cmp_eq_u32 s14, 2
	s_cbranch_scc1 .Lp13f_f2
	s_branch .Lp13f_f3
.Lp13f_w0:
	s_sub_u32 s26, s20, 1
	s_lshl_b32 s27, s26, 12
	s_lshr_b32 s28, s26, 20
	s_add_u32 s22, s8, s27
	s_addc_u32 s23, s9, s28
	global_load_dwordx2 v[16:17], v11, s[22:23]
	s_add_u32 s22, s22, 0x1000
	s_addc_u32 s23, s23, 0
	global_load_dwordx2 v[20:21], v11, s[22:23]
	s_add_u32 s22, s22, 0x1000
	s_addc_u32 s23, s23, 0
	global_load_dwordx2 v[24:25], v11, s[22:23]
	s_add_u32 s22, s22, 0x1000
	s_addc_u32 s23, s23, 0
	global_load_dwordx2 v[28:29], v11, s[22:23]
	s_add_u32 s22, s22, 0x1000
	s_addc_u32 s23, s23, 0
	global_load_dwordx2 v[32:33], v11, s[22:23]
	s_add_u32 s22, s22, 0x1000
	s_addc_u32 s23, s23, 0
	global_load_dwordx2 v[36:37], v11, s[22:23]
	s_add_u32 s22, s22, 0x1000
	s_addc_u32 s23, s23, 0
	global_load_dwordx2 v[40:41], v11, s[22:23]
	s_add_u32 s22, s22, 0x1000
	s_addc_u32 s23, s23, 0
	global_load_dwordx2 v[44:45], v11, s[22:23]
	s_add_u32 s22, s22, 0x1000
	s_addc_u32 s23, s23, 0
	global_load_dwordx2 v[48:49], v11, s[22:23]
	s_add_u32 s22, s22, 0x1000
	s_addc_u32 s23, s23, 0
	global_load_dwordx2 v[52:53], v11, s[22:23]
	s_add_u32 s22, s22, 0x1000
	s_addc_u32 s23, s23, 0
	global_load_dwordx2 v[56:57], v11, s[22:23]
	s_add_u32 s22, s22, 0x1000
	s_addc_u32 s23, s23, 0
	global_load_dwordx2 v[60:61], v11, s[22:23]
	s_add_u32 s22, s22, 0x1000
	s_addc_u32 s23, s23, 0
	global_load_dwordx2 v[64:65], v11, s[22:23]
	s_add_u32 s22, s22, 0x1000
	s_addc_u32 s23, s23, 0
	global_load_dwordx2 v[68:69], v11, s[22:23]
	s_add_u32 s22, s22, 0x1000
	s_addc_u32 s23, s23, 0
	global_load_dwordx2 v[72:73], v11, s[22:23]
	s_add_u32 s22, s22, 0x1000
	s_addc_u32 s23, s23, 0
	global_load_dwordx2 v[76:77], v11, s[22:23]
	s_add_u32 s22, s22, 0x1000
	s_addc_u32 s23, s23, 0
	global_load_dwordx2 v[80:81], v11, s[22:23]
	s_add_u32 s22, s22, 0x1000
	s_addc_u32 s23, s23, 0
	s_waitcnt vmcnt(15)
	v_and_b32_e32 v19, 0xffff0000, v17
	v_lshlrev_b32_e32 v18, 16, v17
	v_and_b32_e32 v17, 0xffff0000, v16
	v_lshlrev_b32_e32 v16, 16, v16
	v_and_b32_e32 v23, 0xffff0000, v21
	v_lshlrev_b32_e32 v22, 16, v21
	v_and_b32_e32 v21, 0xffff0000, v20
	v_lshlrev_b32_e32 v20, 16, v20
	v_add_f32_e32 v140, v20, v16
	v_add_f32_e32 v141, v21, v17
	v_add_f32_e32 v142, v22, v18
	v_add_f32_e32 v143, v23, v19
	v_mul_f32_e32 v140, 0.5, v140
	v_mul_f32_e32 v141, 0.5, v141
	v_mul_f32_e32 v142, 0.5, v142
	v_mul_f32_e32 v143, 0.5, v143
	v_sub_f32_e32 v140, v140, v20
	v_sub_f32_e32 v141, v141, v21
	v_sub_f32_e32 v142, v142, v22
	v_sub_f32_e32 v143, v143, v23
	v_cvt_pk_bf16_f32 v144, v140, v141
	v_cvt_pk_bf16_f32 v145, v142, v143
	global_store_dwordx2 v11, v[144:145], s[24:25]
	s_add_u32 s24, s24, 0x800
	s_addc_u32 s25, s25, 0
	s_waitcnt vmcnt(14)
	v_and_b32_e32 v27, 0xffff0000, v25
	v_lshlrev_b32_e32 v26, 16, v25
	v_and_b32_e32 v25, 0xffff0000, v24
	v_lshlrev_b32_e32 v24, 16, v24
	v_add_f32_e32 v140, v24, v20
	v_add_f32_e32 v141, v25, v21
	v_add_f32_e32 v142, v26, v22
	v_add_f32_e32 v143, v27, v23
	v_mul_f32_e32 v140, 0.5, v140
	v_mul_f32_e32 v141, 0.5, v141
	v_mul_f32_e32 v142, 0.5, v142
	v_mul_f32_e32 v143, 0.5, v143
	v_sub_f32_e32 v140, v140, v24
	v_sub_f32_e32 v141, v141, v25
	v_sub_f32_e32 v142, v142, v26
	v_sub_f32_e32 v143, v143, v27
	v_cvt_pk_bf16_f32 v144, v140, v141
	v_cvt_pk_bf16_f32 v145, v142, v143
	global_store_dwordx2 v11, v[144:145], s[24:25]
	s_add_u32 s24, s24, 0x800
	s_addc_u32 s25, s25, 0
	s_waitcnt vmcnt(13)
	v_and_b32_e32 v31, 0xffff0000, v29
	v_lshlrev_b32_e32 v30, 16, v29
	v_and_b32_e32 v29, 0xffff0000, v28
	v_lshlrev_b32_e32 v28, 16, v28
	v_add_f32_e32 v140, v28, v24
	v_add_f32_e32 v141, v29, v25
	v_add_f32_e32 v142, v30, v26
	v_add_f32_e32 v143, v31, v27
	v_mul_f32_e32 v140, 0.5, v140
	v_mul_f32_e32 v141, 0.5, v141
	v_mul_f32_e32 v142, 0.5, v142
	v_mul_f32_e32 v143, 0.5, v143
	v_sub_f32_e32 v140, v140, v28
	v_sub_f32_e32 v141, v141, v29
	v_sub_f32_e32 v142, v142, v30
	v_sub_f32_e32 v143, v143, v31
	v_cvt_pk_bf16_f32 v144, v140, v141
	v_cvt_pk_bf16_f32 v145, v142, v143
	global_store_dwordx2 v11, v[144:145], s[24:25]
	s_add_u32 s24, s24, 0x800
	s_addc_u32 s25, s25, 0
	s_waitcnt vmcnt(12)
	v_and_b32_e32 v35, 0xffff0000, v33
	v_lshlrev_b32_e32 v34, 16, v33
	v_and_b32_e32 v33, 0xffff0000, v32
	v_lshlrev_b32_e32 v32, 16, v32
	v_add_f32_e32 v140, v32, v28
	v_add_f32_e32 v141, v33, v29
	v_add_f32_e32 v142, v34, v30
	v_add_f32_e32 v143, v35, v31
	v_mul_f32_e32 v140, 0.5, v140
	v_mul_f32_e32 v141, 0.5, v141
	v_mul_f32_e32 v142, 0.5, v142
	v_mul_f32_e32 v143, 0.5, v143
	v_sub_f32_e32 v140, v140, v32
	v_sub_f32_e32 v141, v141, v33
	v_sub_f32_e32 v142, v142, v34
	v_sub_f32_e32 v143, v143, v35
	v_cvt_pk_bf16_f32 v144, v140, v141
	v_cvt_pk_bf16_f32 v145, v142, v143
	global_store_dwordx2 v11, v[144:145], s[24:25]
	s_add_u32 s24, s24, 0x800
	s_addc_u32 s25, s25, 0
	s_waitcnt vmcnt(11)
	v_and_b32_e32 v39, 0xffff0000, v37
	v_lshlrev_b32_e32 v38, 16, v37
	v_and_b32_e32 v37, 0xffff0000, v36
	v_lshlrev_b32_e32 v36, 16, v36
	v_add_f32_e32 v140, v36, v32
	v_add_f32_e32 v141, v37, v33
	v_add_f32_e32 v142, v38, v34
	v_add_f32_e32 v143, v39, v35
	v_mul_f32_e32 v140, 0.5, v140
	v_mul_f32_e32 v141, 0.5, v141
	v_mul_f32_e32 v142, 0.5, v142
	v_mul_f32_e32 v143, 0.5, v143
	v_sub_f32_e32 v140, v140, v36
	v_sub_f32_e32 v141, v141, v37
	v_sub_f32_e32 v142, v142, v38
	v_sub_f32_e32 v143, v143, v39
	v_cvt_pk_bf16_f32 v144, v140, v141
	v_cvt_pk_bf16_f32 v145, v142, v143
	global_store_dwordx2 v11, v[144:145], s[24:25]
	s_add_u32 s24, s24, 0x800
	s_addc_u32 s25, s25, 0
	s_waitcnt vmcnt(10)
	v_and_b32_e32 v43, 0xffff0000, v41
	v_lshlrev_b32_e32 v42, 16, v41
	v_and_b32_e32 v41, 0xffff0000, v40
	v_lshlrev_b32_e32 v40, 16, v40
	v_add_f32_e32 v140, v40, v36
	v_add_f32_e32 v141, v41, v37
	v_add_f32_e32 v142, v42, v38
	v_add_f32_e32 v143, v43, v39
	v_mul_f32_e32 v140, 0.5, v140
	v_mul_f32_e32 v141, 0.5, v141
	v_mul_f32_e32 v142, 0.5, v142
	v_mul_f32_e32 v143, 0.5, v143
	v_sub_f32_e32 v140, v140, v40
	v_sub_f32_e32 v141, v141, v41
	v_sub_f32_e32 v142, v142, v42
	v_sub_f32_e32 v143, v143, v43
	v_cvt_pk_bf16_f32 v144, v140, v141
	v_cvt_pk_bf16_f32 v145, v142, v143
	global_store_dwordx2 v11, v[144:145], s[24:25]
	s_add_u32 s24, s24, 0x800
	s_addc_u32 s25, s25, 0
	s_waitcnt vmcnt(9)
	v_and_b32_e32 v47, 0xffff0000, v45
	v_lshlrev_b32_e32 v46, 16, v45
	v_and_b32_e32 v45, 0xffff0000, v44
	v_lshlrev_b32_e32 v44, 16, v44
	v_add_f32_e32 v140, v44, v40
	v_add_f32_e32 v141, v45, v41
	v_add_f32_e32 v142, v46, v42
	v_add_f32_e32 v143, v47, v43
	v_mul_f32_e32 v140, 0.5, v140
	v_mul_f32_e32 v141, 0.5, v141
	v_mul_f32_e32 v142, 0.5, v142
	v_mul_f32_e32 v143, 0.5, v143
	v_sub_f32_e32 v140, v140, v44
	v_sub_f32_e32 v141, v141, v45
	v_sub_f32_e32 v142, v142, v46
	v_sub_f32_e32 v143, v143, v47
	v_cvt_pk_bf16_f32 v144, v140, v141
	v_cvt_pk_bf16_f32 v145, v142, v143
	global_store_dwordx2 v11, v[144:145], s[24:25]
	s_add_u32 s24, s24, 0x800
	s_addc_u32 s25, s25, 0
	s_waitcnt vmcnt(8)
	v_and_b32_e32 v51, 0xffff0000, v49
	v_lshlrev_b32_e32 v50, 16, v49
	v_and_b32_e32 v49, 0xffff0000, v48
	v_lshlrev_b32_e32 v48, 16, v48
	v_add_f32_e32 v140, v48, v44
	v_add_f32_e32 v141, v49, v45
	v_add_f32_e32 v142, v50, v46
	v_add_f32_e32 v143, v51, v47
	v_mul_f32_e32 v140, 0.5, v140
	v_mul_f32_e32 v141, 0.5, v141
	v_mul_f32_e32 v142, 0.5, v142
	v_mul_f32_e32 v143, 0.5, v143
	v_sub_f32_e32 v140, v140, v48
	v_sub_f32_e32 v141, v141, v49
	v_sub_f32_e32 v142, v142, v50
	v_sub_f32_e32 v143, v143, v51
	v_cvt_pk_bf16_f32 v144, v140, v141
	v_cvt_pk_bf16_f32 v145, v142, v143
	global_store_dwordx2 v11, v[144:145], s[24:25]
	s_add_u32 s24, s24, 0x800
	s_addc_u32 s25, s25, 0
	s_waitcnt vmcnt(7)
	v_and_b32_e32 v55, 0xffff0000, v53
	v_lshlrev_b32_e32 v54, 16, v53
	v_and_b32_e32 v53, 0xffff0000, v52
	v_lshlrev_b32_e32 v52, 16, v52
	v_add_f32_e32 v140, v52, v48
	v_add_f32_e32 v141, v53, v49
	v_add_f32_e32 v142, v54, v50
	v_add_f32_e32 v143, v55, v51
	v_mul_f32_e32 v140, 0.5, v140
	v_mul_f32_e32 v141, 0.5, v141
	v_mul_f32_e32 v142, 0.5, v142
	v_mul_f32_e32 v143, 0.5, v143
	v_sub_f32_e32 v140, v140, v52
	v_sub_f32_e32 v141, v141, v53
	v_sub_f32_e32 v142, v142, v54
	v_sub_f32_e32 v143, v143, v55
	v_cvt_pk_bf16_f32 v144, v140, v141
	v_cvt_pk_bf16_f32 v145, v142, v143
	global_store_dwordx2 v11, v[144:145], s[24:25]
	s_add_u32 s24, s24, 0x800
	s_addc_u32 s25, s25, 0
	s_waitcnt vmcnt(6)
	v_and_b32_e32 v59, 0xffff0000, v57
	v_lshlrev_b32_e32 v58, 16, v57
	v_and_b32_e32 v57, 0xffff0000, v56
	v_lshlrev_b32_e32 v56, 16, v56
	v_add_f32_e32 v140, v56, v52
	v_add_f32_e32 v141, v57, v53
	v_add_f32_e32 v142, v58, v54
	v_add_f32_e32 v143, v59, v55
	v_mul_f32_e32 v140, 0.5, v140
	v_mul_f32_e32 v141, 0.5, v141
	v_mul_f32_e32 v142, 0.5, v142
	v_mul_f32_e32 v143, 0.5, v143
	v_sub_f32_e32 v140, v140, v56
	v_sub_f32_e32 v141, v141, v57
	v_sub_f32_e32 v142, v142, v58
	v_sub_f32_e32 v143, v143, v59
	v_cvt_pk_bf16_f32 v144, v140, v141
	v_cvt_pk_bf16_f32 v145, v142, v143
	global_store_dwordx2 v11, v[144:145], s[24:25]
	s_add_u32 s24, s24, 0x800
	s_addc_u32 s25, s25, 0
	s_waitcnt vmcnt(5)
	v_and_b32_e32 v63, 0xffff0000, v61
	v_lshlrev_b32_e32 v62, 16, v61
	v_and_b32_e32 v61, 0xffff0000, v60
	v_lshlrev_b32_e32 v60, 16, v60
	v_add_f32_e32 v140, v60, v56
	v_add_f32_e32 v141, v61, v57
	v_add_f32_e32 v142, v62, v58
	v_add_f32_e32 v143, v63, v59
	v_mul_f32_e32 v140, 0.5, v140
	v_mul_f32_e32 v141, 0.5, v141
	v_mul_f32_e32 v142, 0.5, v142
	v_mul_f32_e32 v143, 0.5, v143
	v_sub_f32_e32 v140, v140, v60
	v_sub_f32_e32 v141, v141, v61
	v_sub_f32_e32 v142, v142, v62
	v_sub_f32_e32 v143, v143, v63
	v_cvt_pk_bf16_f32 v144, v140, v141
	v_cvt_pk_bf16_f32 v145, v142, v143
	global_store_dwordx2 v11, v[144:145], s[24:25]
	s_add_u32 s24, s24, 0x800
	s_addc_u32 s25, s25, 0
	s_waitcnt vmcnt(4)
	v_and_b32_e32 v67, 0xffff0000, v65
	v_lshlrev_b32_e32 v66, 16, v65
	v_and_b32_e32 v65, 0xffff0000, v64
	v_lshlrev_b32_e32 v64, 16, v64
	v_add_f32_e32 v140, v64, v60
	v_add_f32_e32 v141, v65, v61
	v_add_f32_e32 v142, v66, v62
	v_add_f32_e32 v143, v67, v63
	v_mul_f32_e32 v140, 0.5, v140
	v_mul_f32_e32 v141, 0.5, v141
	v_mul_f32_e32 v142, 0.5, v142
	v_mul_f32_e32 v143, 0.5, v143
	v_sub_f32_e32 v140, v140, v64
	v_sub_f32_e32 v141, v141, v65
	v_sub_f32_e32 v142, v142, v66
	v_sub_f32_e32 v143, v143, v67
	v_cvt_pk_bf16_f32 v144, v140, v141
	v_cvt_pk_bf16_f32 v145, v142, v143
	global_store_dwordx2 v11, v[144:145], s[24:25]
	s_add_u32 s24, s24, 0x800
	s_addc_u32 s25, s25, 0
	s_waitcnt vmcnt(3)
	v_and_b32_e32 v71, 0xffff0000, v69
	v_lshlrev_b32_e32 v70, 16, v69
	v_and_b32_e32 v69, 0xffff0000, v68
	v_lshlrev_b32_e32 v68, 16, v68
	v_add_f32_e32 v140, v68, v64
	v_add_f32_e32 v141, v69, v65
	v_add_f32_e32 v142, v70, v66
	v_add_f32_e32 v143, v71, v67
	v_mul_f32_e32 v140, 0.5, v140
	v_mul_f32_e32 v141, 0.5, v141
	v_mul_f32_e32 v142, 0.5, v142
	v_mul_f32_e32 v143, 0.5, v143
	v_sub_f32_e32 v140, v140, v68
	v_sub_f32_e32 v141, v141, v69
	v_sub_f32_e32 v142, v142, v70
	v_sub_f32_e32 v143, v143, v71
	v_cvt_pk_bf16_f32 v144, v140, v141
	v_cvt_pk_bf16_f32 v145, v142, v143
	global_store_dwordx2 v11, v[144:145], s[24:25]
	s_add_u32 s24, s24, 0x800
	s_addc_u32 s25, s25, 0
	s_waitcnt vmcnt(2)
	v_and_b32_e32 v75, 0xffff0000, v73
	v_lshlrev_b32_e32 v74, 16, v73
	v_and_b32_e32 v73, 0xffff0000, v72
	v_lshlrev_b32_e32 v72, 16, v72
	v_add_f32_e32 v140, v72, v68
	v_add_f32_e32 v141, v73, v69
	v_add_f32_e32 v142, v74, v70
	v_add_f32_e32 v143, v75, v71
	v_mul_f32_e32 v140, 0.5, v140
	v_mul_f32_e32 v141, 0.5, v141
	v_mul_f32_e32 v142, 0.5, v142
	v_mul_f32_e32 v143, 0.5, v143
	v_sub_f32_e32 v140, v140, v72
	v_sub_f32_e32 v141, v141, v73
	v_sub_f32_e32 v142, v142, v74
	v_sub_f32_e32 v143, v143, v75
	v_cvt_pk_bf16_f32 v144, v140, v141
	v_cvt_pk_bf16_f32 v145, v142, v143
	global_store_dwordx2 v11, v[144:145], s[24:25]
	s_add_u32 s24, s24, 0x800
	s_addc_u32 s25, s25, 0
	s_waitcnt vmcnt(1)
	v_and_b32_e32 v79, 0xffff0000, v77
	v_lshlrev_b32_e32 v78, 16, v77
	v_and_b32_e32 v77, 0xffff0000, v76
	v_lshlrev_b32_e32 v76, 16, v76
	v_add_f32_e32 v140, v76, v72
	v_add_f32_e32 v141, v77, v73
	v_add_f32_e32 v142, v78, v74
	v_add_f32_e32 v143, v79, v75
	v_mul_f32_e32 v140, 0.5, v140
	v_mul_f32_e32 v141, 0.5, v141
	v_mul_f32_e32 v142, 0.5, v142
	v_mul_f32_e32 v143, 0.5, v143
	v_sub_f32_e32 v140, v140, v76
	v_sub_f32_e32 v141, v141, v77
	v_sub_f32_e32 v142, v142, v78
	v_sub_f32_e32 v143, v143, v79
	v_cvt_pk_bf16_f32 v144, v140, v141
	v_cvt_pk_bf16_f32 v145, v142, v143
	global_store_dwordx2 v11, v[144:145], s[24:25]
	s_add_u32 s24, s24, 0x800
	s_addc_u32 s25, s25, 0
	s_waitcnt vmcnt(0)
	v_and_b32_e32 v83, 0xffff0000, v81
	v_lshlrev_b32_e32 v82, 16, v81
	v_and_b32_e32 v81, 0xffff0000, v80
	v_lshlrev_b32_e32 v80, 16, v80
	v_add_f32_e32 v140, v80, v76
	v_add_f32_e32 v141, v81, v77
	v_add_f32_e32 v142, v82, v78
	v_add_f32_e32 v143, v83, v79
	v_mul_f32_e32 v140, 0.5, v140
	v_mul_f32_e32 v141, 0.5, v141
	v_mul_f32_e32 v142, 0.5, v142
	v_mul_f32_e32 v143, 0.5, v143
	v_sub_f32_e32 v140, v140, v80
	v_sub_f32_e32 v141, v141, v81
	v_sub_f32_e32 v142, v142, v82
	v_sub_f32_e32 v143, v143, v83
	v_cvt_pk_bf16_f32 v144, v140, v141
	v_cvt_pk_bf16_f32 v145, v142, v143
	global_store_dwordx2 v11, v[144:145], s[24:25]
	s_add_u32 s24, s24, 0x800
	s_addc_u32 s25, s25, 0
	s_cmp_eq_u32 s18, 127
	s_cbranch_scc0 .Lp13f_next
	s_mul_i32 s26, s17, 61440
	s_add_u32 s26, s26, 0x431c000
	s_add_u32 s22, s12, s26
	s_addc_u32 s23, s13, 0
	global_store_dwordx4 v12, v[24:27], s[22:23]
	s_add_u32 s22, s22, 0x1000
	s_addc_u32 s23, s23, 0
	global_store_dwordx4 v12, v[28:31], s[22:23]
	s_add_u32 s22, s22, 0x1000
	s_addc_u32 s23, s23, 0
	global_store_dwordx4 v12, v[32:35], s[22:23]
	s_add_u32 s22, s22, 0x1000
	s_addc_u32 s23, s23, 0
	global_store_dwordx4 v12, v[36:39], s[22:23]
	s_add_u32 s22, s22, 0x1000
	s_addc_u32 s23, s23, 0
	global_store_dwordx4 v12, v[40:43], s[22:23]
	s_add_u32 s22, s22, 0x1000
	s_addc_u32 s23, s23, 0
	global_store_dwordx4 v12, v[44:47], s[22:23]
	s_add_u32 s22, s22, 0x1000
	s_addc_u32 s23, s23, 0
	global_store_dwordx4 v12, v[48:51], s[22:23]
	s_add_u32 s22, s22, 0x1000
	s_addc_u32 s23, s23, 0
	global_store_dwordx4 v12, v[52:55], s[22:23]
	s_add_u32 s22, s22, 0x1000
	s_addc_u32 s23, s23, 0
	global_store_dwordx4 v12, v[56:59], s[22:23]
	s_add_u32 s22, s22, 0x1000
	s_addc_u32 s23, s23, 0
	global_store_dwordx4 v12, v[60:63], s[22:23]
	s_add_u32 s22, s22, 0x1000
	s_addc_u32 s23, s23, 0
	global_store_dwordx4 v12, v[64:67], s[22:23]
	s_add_u32 s22, s22, 0x1000
	s_addc_u32 s23, s23, 0
	global_store_dwordx4 v12, v[68:71], s[22:23]
	s_add_u32 s22, s22, 0x1000
	s_addc_u32 s23, s23, 0
	global_store_dwordx4 v12, v[72:75], s[22:23]
	s_add_u32 s22, s22, 0x1000
	s_addc_u32 s23, s23, 0
	global_store_dwordx4 v12, v[76:79], s[22:23]
	s_add_u32 s22, s22, 0x1000
	s_addc_u32 s23, s23, 0
	global_store_dwordx4 v12, v[80:83], s[22:23]
	s_add_u32 s22, s22, 0x1000
	s_addc_u32 s23, s23, 0
	s_branch .Lp13f_next
.Lp13f_w1:
	s_sub_u32 s26, s20, 3
	s_lshl_b32 s27, s26, 12
	s_lshr_b32 s28, s26, 20
	s_add_u32 s22, s8, s27
	s_addc_u32 s23, s9, s28
	global_load_dwordx2 v[16:17], v11, s[22:23]
	s_add_u32 s22, s22, 0x1000
	s_addc_u32 s23, s23, 0
	global_load_dwordx2 v[20:21], v11, s[22:23]
	s_add_u32 s22, s22, 0x1000
	s_addc_u32 s23, s23, 0
	global_load_dwordx2 v[24:25], v11, s[22:23]
	s_add_u32 s22, s22, 0x1000
	s_addc_u32 s23, s23, 0
	global_load_dwordx2 v[28:29], v11, s[22:23]
	s_add_u32 s22, s22, 0x1000
	s_addc_u32 s23, s23, 0
	global_load_dwordx2 v[32:33], v11, s[22:23]
	s_add_u32 s22, s22, 0x1000
	s_addc_u32 s23, s23, 0
	global_load_dwordx2 v[36:37], v11, s[22:23]
	s_add_u32 s22, s22, 0x1000
	s_addc_u32 s23, s23, 0
	global_load_dwordx2 v[40:41], v11, s[22:23]
	s_add_u32 s22, s22, 0x1000
	s_addc_u32 s23, s23, 0
	global_load_dwordx2 v[44:45], v11, s[22:23]
	s_add_u32 s22, s22, 0x1000
	s_addc_u32 s23, s23, 0
	global_load_dwordx2 v[48:49], v11, s[22:23]
	s_add_u32 s22, s22, 0x1000
	s_addc_u32 s23, s23, 0
	global_load_dwordx2 v[52:53], v11, s[22:23]
	s_add_u32 s22, s22, 0x1000
	s_addc_u32 s23, s23, 0
	global_load_dwordx2 v[56:57], v11, s[22:23]
	s_add_u32 s22, s22, 0x1000
	s_addc_u32 s23, s23, 0
	global_load_dwordx2 v[60:61], v11, s[22:23]
	s_add_u32 s22, s22, 0x1000
	s_addc_u32 s23, s23, 0
	global_load_dwordx2 v[64:65], v11, s[22:23]
	s_add_u32 s22, s22, 0x1000
	s_addc_u32 s23, s23, 0
	global_load_dwordx2 v[68:69], v11, s[22:23]
	s_add_u32 s22, s22, 0x1000
	s_addc_u32 s23, s23, 0
	global_load_dwordx2 v[72:73], v11, s[22:23]
	s_add_u32 s22, s22, 0x1000
	s_addc_u32 s23, s23, 0
	global_load_dwordx2 v[76:77], v11, s[22:23]
	s_add_u32 s22, s22, 0x1000
	s_addc_u32 s23, s23, 0
	global_load_dwordx2 v[80:81], v11, s[22:23]
	s_add_u32 s22, s22, 0x1000
	s_addc_u32 s23, s23, 0
	global_load_dwordx2 v[84:85], v11, s[22:23]
	s_add_u32 s22, s22, 0x1000
	s_addc_u32 s23, s23, 0
	global_load_dwordx2 v[88:89], v11, s[22:23]
	s_add_u32 s22, s22, 0x1000
	s_addc_u32 s23, s23, 0
	s_waitcnt vmcnt(15)
	v_and_b32_e32 v19, 0xffff0000, v17
	v_lshlrev_b32_e32 v18, 16, v17
	v_and_b32_e32 v17, 0xffff0000, v16
	v_lshlrev_b32_e32 v16, 16, v16
	v_and_b32_e32 v23, 0xffff0000, v21
	v_lshlrev_b32_e32 v22, 16, v21
	v_and_b32_e32 v21, 0xffff0000, v20
	v_lshlrev_b32_e32 v20, 16, v20
	v_and_b32_e32 v27, 0xffff0000, v25
	v_lshlrev_b32_e32 v26, 16, v25
	v_and_b32_e32 v25, 0xffff0000, v24
	v_lshlrev_b32_e32 v24, 16, v24
	v_and_b32_e32 v31, 0xffff0000, v29
	v_lshlrev_b32_e32 v30, 16, v29
	v_and_b32_e32 v29, 0xffff0000, v28
	v_lshlrev_b32_e32 v28, 16, v28
	v_add_f32_e32 v140, v28, v24
	v_add_f32_e32 v141, v29, v25
	v_add_f32_e32 v142, v30, v26
	v_add_f32_e32 v143, v31, v27
	v_add_f32_e32 v140, v140, v20
	v_add_f32_e32 v141, v141, v21
	v_add_f32_e32 v142, v142, v22
	v_add_f32_e32 v143, v143, v23
	v_add_f32_e32 v140, v140, v16
	v_add_f32_e32 v141, v141, v17
	v_add_f32_e32 v142, v142, v18
	v_add_f32_e32 v143, v143, v19
	v_mul_f32_e32 v140, 0x3e800000, v140
	v_mul_f32_e32 v141, 0x3e800000, v141
	v_mul_f32_e32 v142, 0x3e800000, v142
	v_mul_f32_e32 v143, 0x3e800000, v143
	v_sub_f32_e32 v140, v140, v28
	v_sub_f32_e32 v141, v141, v29
	v_sub_f32_e32 v142, v142, v30
	v_sub_f32_e32 v143, v143, v31
	v_cvt_pk_bf16_f32 v144, v140, v141
	v_cvt_pk_bf16_f32 v145, v142, v143
	global_store_dwordx2 v11, v[144:145], s[24:25]
	s_add_u32 s24, s24, 0x800
	s_addc_u32 s25, s25, 0
	s_waitcnt vmcnt(14)
	v_and_b32_e32 v35, 0xffff0000, v33
	v_lshlrev_b32_e32 v34, 16, v33
	v_and_b32_e32 v33, 0xffff0000, v32
	v_lshlrev_b32_e32 v32, 16, v32
	v_add_f32_e32 v140, v32, v28
	v_add_f32_e32 v141, v33, v29
	v_add_f32_e32 v142, v34, v30
	v_add_f32_e32 v143, v35, v31
	v_add_f32_e32 v140, v140, v24
	v_add_f32_e32 v141, v141, v25
	v_add_f32_e32 v142, v142, v26
	v_add_f32_e32 v143, v143, v27
	v_add_f32_e32 v140, v140, v20
	v_add_f32_e32 v141, v141, v21
	v_add_f32_e32 v142, v142, v22
	v_add_f32_e32 v143, v143, v23
	v_mul_f32_e32 v140, 0x3e800000, v140
	v_mul_f32_e32 v141, 0x3e800000, v141
	v_mul_f32_e32 v142, 0x3e800000, v142
	v_mul_f32_e32 v143, 0x3e800000, v143
	v_sub_f32_e32 v140, v140, v32
	v_sub_f32_e32 v141, v141, v33
	v_sub_f32_e32 v142, v142, v34
	v_sub_f32_e32 v143, v143, v35
	v_cvt_pk_bf16_f32 v144, v140, v141
	v_cvt_pk_bf16_f32 v145, v142, v143
	global_store_dwordx2 v11, v[144:145], s[24:25]
	s_add_u32 s24, s24, 0x800
	s_addc_u32 s25, s25, 0
	s_waitcnt vmcnt(13)
	v_and_b32_e32 v39, 0xffff0000, v37
	v_lshlrev_b32_e32 v38, 16, v37
	v_and_b32_e32 v37, 0xffff0000, v36
	v_lshlrev_b32_e32 v36, 16, v36
	v_add_f32_e32 v140, v36, v32
	v_add_f32_e32 v141, v37, v33
	v_add_f32_e32 v142, v38, v34
	v_add_f32_e32 v143, v39, v35
	v_add_f32_e32 v140, v140, v28
	v_add_f32_e32 v141, v141, v29
	v_add_f32_e32 v142, v142, v30
	v_add_f32_e32 v143, v143, v31
	v_add_f32_e32 v140, v140, v24
	v_add_f32_e32 v141, v141, v25
	v_add_f32_e32 v142, v142, v26
	v_add_f32_e32 v143, v143, v27
	v_mul_f32_e32 v140, 0x3e800000, v140
	v_mul_f32_e32 v141, 0x3e800000, v141
	v_mul_f32_e32 v142, 0x3e800000, v142
	v_mul_f32_e32 v143, 0x3e800000, v143
	v_sub_f32_e32 v140, v140, v36
	v_sub_f32_e32 v141, v141, v37
	v_sub_f32_e32 v142, v142, v38
	v_sub_f32_e32 v143, v143, v39
	v_cvt_pk_bf16_f32 v144, v140, v141
	v_cvt_pk_bf16_f32 v145, v142, v143
	global_store_dwordx2 v11, v[144:145], s[24:25]
	s_add_u32 s24, s24, 0x800
	s_addc_u32 s25, s25, 0
	s_waitcnt vmcnt(12)
	v_and_b32_e32 v43, 0xffff0000, v41
	v_lshlrev_b32_e32 v42, 16, v41
	v_and_b32_e32 v41, 0xffff0000, v40
	v_lshlrev_b32_e32 v40, 16, v40
	v_add_f32_e32 v140, v40, v36
	v_add_f32_e32 v141, v41, v37
	v_add_f32_e32 v142, v42, v38
	v_add_f32_e32 v143, v43, v39
	v_add_f32_e32 v140, v140, v32
	v_add_f32_e32 v141, v141, v33
	v_add_f32_e32 v142, v142, v34
	v_add_f32_e32 v143, v143, v35
	v_add_f32_e32 v140, v140, v28
	v_add_f32_e32 v141, v141, v29
	v_add_f32_e32 v142, v142, v30
	v_add_f32_e32 v143, v143, v31
	v_mul_f32_e32 v140, 0x3e800000, v140
	v_mul_f32_e32 v141, 0x3e800000, v141
	v_mul_f32_e32 v142, 0x3e800000, v142
	v_mul_f32_e32 v143, 0x3e800000, v143
	v_sub_f32_e32 v140, v140, v40
	v_sub_f32_e32 v141, v141, v41
	v_sub_f32_e32 v142, v142, v42
	v_sub_f32_e32 v143, v143, v43
	v_cvt_pk_bf16_f32 v144, v140, v141
	v_cvt_pk_bf16_f32 v145, v142, v143
	global_store_dwordx2 v11, v[144:145], s[24:25]
	s_add_u32 s24, s24, 0x800
	s_addc_u32 s25, s25, 0
	s_waitcnt vmcnt(11)
	v_and_b32_e32 v47, 0xffff0000, v45
	v_lshlrev_b32_e32 v46, 16, v45
	v_and_b32_e32 v45, 0xffff0000, v44
	v_lshlrev_b32_e32 v44, 16, v44
	v_add_f32_e32 v140, v44, v40
	v_add_f32_e32 v141, v45, v41
	v_add_f32_e32 v142, v46, v42
	v_add_f32_e32 v143, v47, v43
	v_add_f32_e32 v140, v140, v36
	v_add_f32_e32 v141, v141, v37
	v_add_f32_e32 v142, v142, v38
	v_add_f32_e32 v143, v143, v39
	v_add_f32_e32 v140, v140, v32
	v_add_f32_e32 v141, v141, v33
	v_add_f32_e32 v142, v142, v34
	v_add_f32_e32 v143, v143, v35
	v_mul_f32_e32 v140, 0x3e800000, v140
	v_mul_f32_e32 v141, 0x3e800000, v141
	v_mul_f32_e32 v142, 0x3e800000, v142
	v_mul_f32_e32 v143, 0x3e800000, v143
	v_sub_f32_e32 v140, v140, v44
	v_sub_f32_e32 v141, v141, v45
	v_sub_f32_e32 v142, v142, v46
	v_sub_f32_e32 v143, v143, v47
	v_cvt_pk_bf16_f32 v144, v140, v141
	v_cvt_pk_bf16_f32 v145, v142, v143
	global_store_dwordx2 v11, v[144:145], s[24:25]
	s_add_u32 s24, s24, 0x800
	s_addc_u32 s25, s25, 0
	s_waitcnt vmcnt(10)
	v_and_b32_e32 v51, 0xffff0000, v49
	v_lshlrev_b32_e32 v50, 16, v49
	v_and_b32_e32 v49, 0xffff0000, v48
	v_lshlrev_b32_e32 v48, 16, v48
	v_add_f32_e32 v140, v48, v44
	v_add_f32_e32 v141, v49, v45
	v_add_f32_e32 v142, v50, v46
	v_add_f32_e32 v143, v51, v47
	v_add_f32_e32 v140, v140, v40
	v_add_f32_e32 v141, v141, v41
	v_add_f32_e32 v142, v142, v42
	v_add_f32_e32 v143, v143, v43
	v_add_f32_e32 v140, v140, v36
	v_add_f32_e32 v141, v141, v37
	v_add_f32_e32 v142, v142, v38
	v_add_f32_e32 v143, v143, v39
	v_mul_f32_e32 v140, 0x3e800000, v140
	v_mul_f32_e32 v141, 0x3e800000, v141
	v_mul_f32_e32 v142, 0x3e800000, v142
	v_mul_f32_e32 v143, 0x3e800000, v143
	v_sub_f32_e32 v140, v140, v48
	v_sub_f32_e32 v141, v141, v49
	v_sub_f32_e32 v142, v142, v50
	v_sub_f32_e32 v143, v143, v51
	v_cvt_pk_bf16_f32 v144, v140, v141
	v_cvt_pk_bf16_f32 v145, v142, v143
	global_store_dwordx2 v11, v[144:145], s[24:25]
	s_add_u32 s24, s24, 0x800
	s_addc_u32 s25, s25, 0
	s_waitcnt vmcnt(9)
	v_and_b32_e32 v55, 0xffff0000, v53
	v_lshlrev_b32_e32 v54, 16, v53
	v_and_b32_e32 v53, 0xffff0000, v52
	v_lshlrev_b32_e32 v52, 16, v52
	v_add_f32_e32 v140, v52, v48
	v_add_f32_e32 v141, v53, v49
	v_add_f32_e32 v142, v54, v50
	v_add_f32_e32 v143, v55, v51
	v_add_f32_e32 v140, v140, v44
	v_add_f32_e32 v141, v141, v45
	v_add_f32_e32 v142, v142, v46
	v_add_f32_e32 v143, v143, v47
	v_add_f32_e32 v140, v140, v40
	v_add_f32_e32 v141, v141, v41
	v_add_f32_e32 v142, v142, v42
	v_add_f32_e32 v143, v143, v43
	v_mul_f32_e32 v140, 0x3e800000, v140
	v_mul_f32_e32 v141, 0x3e800000, v141
	v_mul_f32_e32 v142, 0x3e800000, v142
	v_mul_f32_e32 v143, 0x3e800000, v143
	v_sub_f32_e32 v140, v140, v52
	v_sub_f32_e32 v141, v141, v53
	v_sub_f32_e32 v142, v142, v54
	v_sub_f32_e32 v143, v143, v55
	v_cvt_pk_bf16_f32 v144, v140, v141
	v_cvt_pk_bf16_f32 v145, v142, v143
	global_store_dwordx2 v11, v[144:145], s[24:25]
	s_add_u32 s24, s24, 0x800
	s_addc_u32 s25, s25, 0
	s_waitcnt vmcnt(8)
	v_and_b32_e32 v59, 0xffff0000, v57
	v_lshlrev_b32_e32 v58, 16, v57
	v_and_b32_e32 v57, 0xffff0000, v56
	v_lshlrev_b32_e32 v56, 16, v56
	v_add_f32_e32 v140, v56, v52
	v_add_f32_e32 v141, v57, v53
	v_add_f32_e32 v142, v58, v54
	v_add_f32_e32 v143, v59, v55
	v_add_f32_e32 v140, v140, v48
	v_add_f32_e32 v141, v141, v49
	v_add_f32_e32 v142, v142, v50
	v_add_f32_e32 v143, v143, v51
	v_add_f32_e32 v140, v140, v44
	v_add_f32_e32 v141, v141, v45
	v_add_f32_e32 v142, v142, v46
	v_add_f32_e32 v143, v143, v47
	v_mul_f32_e32 v140, 0x3e800000, v140
	v_mul_f32_e32 v141, 0x3e800000, v141
	v_mul_f32_e32 v142, 0x3e800000, v142
	v_mul_f32_e32 v143, 0x3e800000, v143
	v_sub_f32_e32 v140, v140, v56
	v_sub_f32_e32 v141, v141, v57
	v_sub_f32_e32 v142, v142, v58
	v_sub_f32_e32 v143, v143, v59
	v_cvt_pk_bf16_f32 v144, v140, v141
	v_cvt_pk_bf16_f32 v145, v142, v143
	global_store_dwordx2 v11, v[144:145], s[24:25]
	s_add_u32 s24, s24, 0x800
	s_addc_u32 s25, s25, 0
	s_waitcnt vmcnt(7)
	v_and_b32_e32 v63, 0xffff0000, v61
	v_lshlrev_b32_e32 v62, 16, v61
	v_and_b32_e32 v61, 0xffff0000, v60
	v_lshlrev_b32_e32 v60, 16, v60
	v_add_f32_e32 v140, v60, v56
	v_add_f32_e32 v141, v61, v57
	v_add_f32_e32 v142, v62, v58
	v_add_f32_e32 v143, v63, v59
	v_add_f32_e32 v140, v140, v52
	v_add_f32_e32 v141, v141, v53
	v_add_f32_e32 v142, v142, v54
	v_add_f32_e32 v143, v143, v55
	v_add_f32_e32 v140, v140, v48
	v_add_f32_e32 v141, v141, v49
	v_add_f32_e32 v142, v142, v50
	v_add_f32_e32 v143, v143, v51
	v_mul_f32_e32 v140, 0x3e800000, v140
	v_mul_f32_e32 v141, 0x3e800000, v141
	v_mul_f32_e32 v142, 0x3e800000, v142
	v_mul_f32_e32 v143, 0x3e800000, v143
	v_sub_f32_e32 v140, v140, v60
	v_sub_f32_e32 v141, v141, v61
	v_sub_f32_e32 v142, v142, v62
	v_sub_f32_e32 v143, v143, v63
	v_cvt_pk_bf16_f32 v144, v140, v141
	v_cvt_pk_bf16_f32 v145, v142, v143
	global_store_dwordx2 v11, v[144:145], s[24:25]
	s_add_u32 s24, s24, 0x800
	s_addc_u32 s25, s25, 0
	s_waitcnt vmcnt(6)
	v_and_b32_e32 v67, 0xffff0000, v65
	v_lshlrev_b32_e32 v66, 16, v65
	v_and_b32_e32 v65, 0xffff0000, v64
	v_lshlrev_b32_e32 v64, 16, v64
	v_add_f32_e32 v140, v64, v60
	v_add_f32_e32 v141, v65, v61
	v_add_f32_e32 v142, v66, v62
	v_add_f32_e32 v143, v67, v63
	v_add_f32_e32 v140, v140, v56
	v_add_f32_e32 v141, v141, v57
	v_add_f32_e32 v142, v142, v58
	v_add_f32_e32 v143, v143, v59
	v_add_f32_e32 v140, v140, v52
	v_add_f32_e32 v141, v141, v53
	v_add_f32_e32 v142, v142, v54
	v_add_f32_e32 v143, v143, v55
	v_mul_f32_e32 v140, 0x3e800000, v140
	v_mul_f32_e32 v141, 0x3e800000, v141
	v_mul_f32_e32 v142, 0x3e800000, v142
	v_mul_f32_e32 v143, 0x3e800000, v143
	v_sub_f32_e32 v140, v140, v64
	v_sub_f32_e32 v141, v141, v65
	v_sub_f32_e32 v142, v142, v66
	v_sub_f32_e32 v143, v143, v67
	v_cvt_pk_bf16_f32 v144, v140, v141
	v_cvt_pk_bf16_f32 v145, v142, v143
	global_store_dwordx2 v11, v[144:145], s[24:25]
	s_add_u32 s24, s24, 0x800
	s_addc_u32 s25, s25, 0
	s_waitcnt vmcnt(5)
	v_and_b32_e32 v71, 0xffff0000, v69
	v_lshlrev_b32_e32 v70, 16, v69
	v_and_b32_e32 v69, 0xffff0000, v68
	v_lshlrev_b32_e32 v68, 16, v68
	v_add_f32_e32 v140, v68, v64
	v_add_f32_e32 v141, v69, v65
	v_add_f32_e32 v142, v70, v66
	v_add_f32_e32 v143, v71, v67
	v_add_f32_e32 v140, v140, v60
	v_add_f32_e32 v141, v141, v61
	v_add_f32_e32 v142, v142, v62
	v_add_f32_e32 v143, v143, v63
	v_add_f32_e32 v140, v140, v56
	v_add_f32_e32 v141, v141, v57
	v_add_f32_e32 v142, v142, v58
	v_add_f32_e32 v143, v143, v59
	v_mul_f32_e32 v140, 0x3e800000, v140
	v_mul_f32_e32 v141, 0x3e800000, v141
	v_mul_f32_e32 v142, 0x3e800000, v142
	v_mul_f32_e32 v143, 0x3e800000, v143
	v_sub_f32_e32 v140, v140, v68
	v_sub_f32_e32 v141, v141, v69
	v_sub_f32_e32 v142, v142, v70
	v_sub_f32_e32 v143, v143, v71
	v_cvt_pk_bf16_f32 v144, v140, v141
	v_cvt_pk_bf16_f32 v145, v142, v143
	global_store_dwordx2 v11, v[144:145], s[24:25]
	s_add_u32 s24, s24, 0x800
	s_addc_u32 s25, s25, 0
	s_waitcnt vmcnt(4)
	v_and_b32_e32 v75, 0xffff0000, v73
	v_lshlrev_b32_e32 v74, 16, v73
	v_and_b32_e32 v73, 0xffff0000, v72
	v_lshlrev_b32_e32 v72, 16, v72
	v_add_f32_e32 v140, v72, v68
	v_add_f32_e32 v141, v73, v69
	v_add_f32_e32 v142, v74, v70
	v_add_f32_e32 v143, v75, v71
	v_add_f32_e32 v140, v140, v64
	v_add_f32_e32 v141, v141, v65
	v_add_f32_e32 v142, v142, v66
	v_add_f32_e32 v143, v143, v67
	v_add_f32_e32 v140, v140, v60
	v_add_f32_e32 v141, v141, v61
	v_add_f32_e32 v142, v142, v62
	v_add_f32_e32 v143, v143, v63
	v_mul_f32_e32 v140, 0x3e800000, v140
	v_mul_f32_e32 v141, 0x3e800000, v141
	v_mul_f32_e32 v142, 0x3e800000, v142
	v_mul_f32_e32 v143, 0x3e800000, v143
	v_sub_f32_e32 v140, v140, v72
	v_sub_f32_e32 v141, v141, v73
	v_sub_f32_e32 v142, v142, v74
	v_sub_f32_e32 v143, v143, v75
	v_cvt_pk_bf16_f32 v144, v140, v141
	v_cvt_pk_bf16_f32 v145, v142, v143
	global_store_dwordx2 v11, v[144:145], s[24:25]
	s_add_u32 s24, s24, 0x800
	s_addc_u32 s25, s25, 0
	s_waitcnt vmcnt(3)
	v_and_b32_e32 v79, 0xffff0000, v77
	v_lshlrev_b32_e32 v78, 16, v77
	v_and_b32_e32 v77, 0xffff0000, v76
	v_lshlrev_b32_e32 v76, 16, v76
	v_add_f32_e32 v140, v76, v72
	v_add_f32_e32 v141, v77, v73
	v_add_f32_e32 v142, v78, v74
	v_add_f32_e32 v143, v79, v75
	v_add_f32_e32 v140, v140, v68
	v_add_f32_e32 v141, v141, v69
	v_add_f32_e32 v142, v142, v70
	v_add_f32_e32 v143, v143, v71
	v_add_f32_e32 v140, v140, v64
	v_add_f32_e32 v141, v141, v65
	v_add_f32_e32 v142, v142, v66
	v_add_f32_e32 v143, v143, v67
	v_mul_f32_e32 v140, 0x3e800000, v140
	v_mul_f32_e32 v141, 0x3e800000, v141
	v_mul_f32_e32 v142, 0x3e800000, v142
	v_mul_f32_e32 v143, 0x3e800000, v143
	v_sub_f32_e32 v140, v140, v76
	v_sub_f32_e32 v141, v141, v77
	v_sub_f32_e32 v142, v142, v78
	v_sub_f32_e32 v143, v143, v79
	v_cvt_pk_bf16_f32 v144, v140, v141
	v_cvt_pk_bf16_f32 v145, v142, v143
	global_store_dwordx2 v11, v[144:145], s[24:25]
	s_add_u32 s24, s24, 0x800
	s_addc_u32 s25, s25, 0
	s_waitcnt vmcnt(2)
	v_and_b32_e32 v83, 0xffff0000, v81
	v_lshlrev_b32_e32 v82, 16, v81
	v_and_b32_e32 v81, 0xffff0000, v80
	v_lshlrev_b32_e32 v80, 16, v80
	v_add_f32_e32 v140, v80, v76
	v_add_f32_e32 v141, v81, v77
	v_add_f32_e32 v142, v82, v78
	v_add_f32_e32 v143, v83, v79
	v_add_f32_e32 v140, v140, v72
	v_add_f32_e32 v141, v141, v73
	v_add_f32_e32 v142, v142, v74
	v_add_f32_e32 v143, v143, v75
	v_add_f32_e32 v140, v140, v68
	v_add_f32_e32 v141, v141, v69
	v_add_f32_e32 v142, v142, v70
	v_add_f32_e32 v143, v143, v71
	v_mul_f32_e32 v140, 0x3e800000, v140
	v_mul_f32_e32 v141, 0x3e800000, v141
	v_mul_f32_e32 v142, 0x3e800000, v142
	v_mul_f32_e32 v143, 0x3e800000, v143
	v_sub_f32_e32 v140, v140, v80
	v_sub_f32_e32 v141, v141, v81
	v_sub_f32_e32 v142, v142, v82
	v_sub_f32_e32 v143, v143, v83
	v_cvt_pk_bf16_f32 v144, v140, v141
	v_cvt_pk_bf16_f32 v145, v142, v143
	global_store_dwordx2 v11, v[144:145], s[24:25]
	s_add_u32 s24, s24, 0x800
	s_addc_u32 s25, s25, 0
	s_waitcnt vmcnt(1)
	v_and_b32_e32 v87, 0xffff0000, v85
	v_lshlrev_b32_e32 v86, 16, v85
	v_and_b32_e32 v85, 0xffff0000, v84
	v_lshlrev_b32_e32 v84, 16, v84
	v_add_f32_e32 v140, v84, v80
	v_add_f32_e32 v141, v85, v81
	v_add_f32_e32 v142, v86, v82
	v_add_f32_e32 v143, v87, v83
	v_add_f32_e32 v140, v140, v76
	v_add_f32_e32 v141, v141, v77
	v_add_f32_e32 v142, v142, v78
	v_add_f32_e32 v143, v143, v79
	v_add_f32_e32 v140, v140, v72
	v_add_f32_e32 v141, v141, v73
	v_add_f32_e32 v142, v142, v74
	v_add_f32_e32 v143, v143, v75
	v_mul_f32_e32 v140, 0x3e800000, v140
	v_mul_f32_e32 v141, 0x3e800000, v141
	v_mul_f32_e32 v142, 0x3e800000, v142
	v_mul_f32_e32 v143, 0x3e800000, v143
	v_sub_f32_e32 v140, v140, v84
	v_sub_f32_e32 v141, v141, v85
	v_sub_f32_e32 v142, v142, v86
	v_sub_f32_e32 v143, v143, v87
	v_cvt_pk_bf16_f32 v144, v140, v141
	v_cvt_pk_bf16_f32 v145, v142, v143
	global_store_dwordx2 v11, v[144:145], s[24:25]
	s_add_u32 s24, s24, 0x800
	s_addc_u32 s25, s25, 0
	s_waitcnt vmcnt(0)
	v_and_b32_e32 v91, 0xffff0000, v89
	v_lshlrev_b32_e32 v90, 16, v89
	v_and_b32_e32 v89, 0xffff0000, v88
	v_lshlrev_b32_e32 v88, 16, v88
	v_add_f32_e32 v140, v88, v84
	v_add_f32_e32 v141, v89, v85
	v_add_f32_e32 v142, v90, v86
	v_add_f32_e32 v143, v91, v87
	v_add_f32_e32 v140, v140, v80
	v_add_f32_e32 v141, v141, v81
	v_add_f32_e32 v142, v142, v82
	v_add_f32_e32 v143, v143, v83
	v_add_f32_e32 v140, v140, v76
	v_add_f32_e32 v141, v141, v77
	v_add_f32_e32 v142, v142, v78
	v_add_f32_e32 v143, v143, v79
	v_mul_f32_e32 v140, 0x3e800000, v140
	v_mul_f32_e32 v141, 0x3e800000, v141
	v_mul_f32_e32 v142, 0x3e800000, v142
	v_mul_f32_e32 v143, 0x3e800000, v143
	v_sub_f32_e32 v140, v140, v88
	v_sub_f32_e32 v141, v141, v89
	v_sub_f32_e32 v142, v142, v90
	v_sub_f32_e32 v143, v143, v91
	v_cvt_pk_bf16_f32 v144, v140, v141
	v_cvt_pk_bf16_f32 v145, v142, v143
	global_store_dwordx2 v11, v[144:145], s[24:25]
	s_add_u32 s24, s24, 0x800
	s_addc_u32 s25, s25, 0
	s_cmp_eq_u32 s18, 127
	s_cbranch_scc0 .Lp13f_next
; DI float bflo(unsigned u) { return __uint_as_float(u << 16); }
; DI float bfhi(unsigned u) { return __uint_as_float(u & 0xffff0000u); }
; template <int WIN>
; DI void pool_elem(const Params& p, int row, int c) {
;     ...
;     if (t >= WIN - 1) {
;       cnt = (float)WIN;
;       unsigned w[WIN - 1];
; #pragma unroll
;       for (int j = 1; j < WIN; ++j) w[j - 1] = *(const unsigned*)(P2 + (size_t)(row - j) * 2048 + c);
; #pragma unroll
;       for (int j = 1; j < WIN; ++j) { s0 += bflo(w[j - 1]); s1 += bfhi(w[j - 1]); }
;     } else {
;       cnt = (float)(t + 1);
;       for (int j = 1; j <= t; ++j) {
;         unsigned w = *(const unsigned*)(P2 + (size_t)(row - j) * 2048 + c);
;         s0 += bflo(w); s1 += bfhi(w);
;       }
;     }
;     if (t >= 2033) {
;       float2 o = {u0, u1};
;       *(float2*)(p.out + O_POOLP + ((size_t)b * 15 + (t - 2033)) * 1024 + c) = o;
;     }
;   } else {
;     const int s = row - NPR;
;     cnt = (float)WIN;
;     const float* sp = p.state_pool + (size_t)s * 15 * 1024 + c;
;     float2 st[15];
; #pragma unroll
;     for (int j = 0; j < 15; ++j) st[j] = *(const float2*)(sp + (size_t)j * 1024);
; #pragma unroll
;     for (int j = 1; j < WIN; ++j) { s0 += st[15 - j].x; s1 += st[15 - j].y; }
;     float* op = p.out + O_POOLS + (size_t)s * 15 * 1024 + c;
; #pragma unroll
;     for (int j = 0; j < 14; ++j) *(float2*)(op + (size_t)j * 1024) = st[j + 1];
;     float2 o = {u0, u1};
;     *(float2*)(op + (size_t)14 * 1024) = o;
;   }
;   *(unsigned*)(p.MIX + (size_t)row * 1024 + c) = pack2(s0 / cnt - u0, s1 / cnt - u1);
	s_mul_i32 s26, s17, 61440
	s_add_u32 s26, s26, 0x431c000
	s_add_u32 s22, s12, s26
	s_addc_u32 s23, s13, 0
	global_store_dwordx4 v12, v[32:35], s[22:23]
	s_add_u32 s22, s22, 0x1000
	s_addc_u32 s23, s23, 0
	global_store_dwordx4 v12, v[36:39], s[22:23]
	s_add_u32 s22, s22, 0x1000
	s_addc_u32 s23, s23, 0
	global_store_dwordx4 v12, v[40:43], s[22:23]
	s_add_u32 s22, s22, 0x1000
	s_addc_u32 s23, s23, 0
	global_store_dwordx4 v12, v[44:47], s[22:23]
	s_add_u32 s22, s22, 0x1000
	s_addc_u32 s23, s23, 0
	global_store_dwordx4 v12, v[48:51], s[22:23]
	s_add_u32 s22, s22, 0x1000
	s_addc_u32 s23, s23, 0
	global_store_dwordx4 v12, v[52:55], s[22:23]
	s_add_u32 s22, s22, 0x1000
	s_addc_u32 s23, s23, 0
	global_store_dwordx4 v12, v[56:59], s[22:23]
	s_add_u32 s22, s22, 0x1000
	s_addc_u32 s23, s23, 0
	global_store_dwordx4 v12, v[60:63], s[22:23]
	s_add_u32 s22, s22, 0x1000
	s_addc_u32 s23, s23, 0
	global_store_dwordx4 v12, v[64:67], s[22:23]
	s_add_u32 s22, s22, 0x1000
	s_addc_u32 s23, s23, 0
	global_store_dwordx4 v12, v[68:71], s[22:23]
	s_add_u32 s22, s22, 0x1000
	s_addc_u32 s23, s23, 0
	global_store_dwordx4 v12, v[72:75], s[22:23]
	s_add_u32 s22, s22, 0x1000
	s_addc_u32 s23, s23, 0
	global_store_dwordx4 v12, v[76:79], s[22:23]
	s_add_u32 s22, s22, 0x1000
	s_addc_u32 s23, s23, 0
	global_store_dwordx4 v12, v[80:83], s[22:23]
	s_add_u32 s22, s22, 0x1000
	s_addc_u32 s23, s23, 0
	global_store_dwordx4 v12, v[84:87], s[22:23]
	s_add_u32 s22, s22, 0x1000
	s_addc_u32 s23, s23, 0
	global_store_dwordx4 v12, v[88:91], s[22:23]
	s_add_u32 s22, s22, 0x1000
	s_addc_u32 s23, s23, 0
	s_branch .Lp13f_next
.Lp13f_w2:
	s_sub_u32 s26, s20, 7
	s_lshl_b32 s27, s26, 12
	s_lshr_b32 s28, s26, 20
	s_add_u32 s22, s8, s27
	s_addc_u32 s23, s9, s28
	global_load_dwordx2 v[16:17], v11, s[22:23]
	s_add_u32 s22, s22, 0x1000
	s_addc_u32 s23, s23, 0
	global_load_dwordx2 v[20:21], v11, s[22:23]
	s_add_u32 s22, s22, 0x1000
	s_addc_u32 s23, s23, 0
	global_load_dwordx2 v[24:25], v11, s[22:23]
	s_add_u32 s22, s22, 0x1000
	s_addc_u32 s23, s23, 0
	global_load_dwordx2 v[28:29], v11, s[22:23]
	s_add_u32 s22, s22, 0x1000
	s_addc_u32 s23, s23, 0
	global_load_dwordx2 v[32:33], v11, s[22:23]
	s_add_u32 s22, s22, 0x1000
	s_addc_u32 s23, s23, 0
	global_load_dwordx2 v[36:37], v11, s[22:23]
	s_add_u32 s22, s22, 0x1000
	s_addc_u32 s23, s23, 0
	global_load_dwordx2 v[40:41], v11, s[22:23]
	s_add_u32 s22, s22, 0x1000
	s_addc_u32 s23, s23, 0
	global_load_dwordx2 v[44:45], v11, s[22:23]
	s_add_u32 s22, s22, 0x1000
	s_addc_u32 s23, s23, 0
	global_load_dwordx2 v[48:49], v11, s[22:23]
	s_add_u32 s22, s22, 0x1000
	s_addc_u32 s23, s23, 0
	global_load_dwordx2 v[52:53], v11, s[22:23]
	s_add_u32 s22, s22, 0x1000
	s_addc_u32 s23, s23, 0
	global_load_dwordx2 v[56:57], v11, s[22:23]
	s_add_u32 s22, s22, 0x1000
	s_addc_u32 s23, s23, 0
	global_load_dwordx2 v[60:61], v11, s[22:23]
	s_add_u32 s22, s22, 0x1000
	s_addc_u32 s23, s23, 0
	global_load_dwordx2 v[64:65], v11, s[22:23]
	s_add_u32 s22, s22, 0x1000
	s_addc_u32 s23, s23, 0
	global_load_dwordx2 v[68:69], v11, s[22:23]
	s_add_u32 s22, s22, 0x1000
	s_addc_u32 s23, s23, 0
	global_load_dwordx2 v[72:73], v11, s[22:23]
	s_add_u32 s22, s22, 0x1000
	s_addc_u32 s23, s23, 0
	global_load_dwordx2 v[76:77], v11, s[22:23]
	s_add_u32 s22, s22, 0x1000
	s_addc_u32 s23, s23, 0
	global_load_dwordx2 v[80:81], v11, s[22:23]
	s_add_u32 s22, s22, 0x1000
	s_addc_u32 s23, s23, 0
	global_load_dwordx2 v[84:85], v11, s[22:23]
	s_add_u32 s22, s22, 0x1000
	s_addc_u32 s23, s23, 0
	global_load_dwordx2 v[88:89], v11, s[22:23]
	s_add_u32 s22, s22, 0x1000
	s_addc_u32 s23, s23, 0
	global_load_dwordx2 v[92:93], v11, s[22:23]
	s_add_u32 s22, s22, 0x1000
	s_addc_u32 s23, s23, 0
	global_load_dwordx2 v[96:97], v11, s[22:23]
	s_add_u32 s22, s22, 0x1000
	s_addc_u32 s23, s23, 0
	global_load_dwordx2 v[100:101], v11, s[22:23]
	s_add_u32 s22, s22, 0x1000
	s_addc_u32 s23, s23, 0
	global_load_dwordx2 v[104:105], v11, s[22:23]
	s_add_u32 s22, s22, 0x1000
	s_addc_u32 s23, s23, 0
	s_waitcnt vmcnt(15)
	v_and_b32_e32 v19, 0xffff0000, v17
	v_lshlrev_b32_e32 v18, 16, v17
	v_and_b32_e32 v17, 0xffff0000, v16
	v_lshlrev_b32_e32 v16, 16, v16
	v_and_b32_e32 v23, 0xffff0000, v21
	v_lshlrev_b32_e32 v22, 16, v21
	v_and_b32_e32 v21, 0xffff0000, v20
	v_lshlrev_b32_e32 v20, 16, v20
	v_and_b32_e32 v27, 0xffff0000, v25
	v_lshlrev_b32_e32 v26, 16, v25
	v_and_b32_e32 v25, 0xffff0000, v24
	v_lshlrev_b32_e32 v24, 16, v24
	v_and_b32_e32 v31, 0xffff0000, v29
	v_lshlrev_b32_e32 v30, 16, v29
	v_and_b32_e32 v29, 0xffff0000, v28
	v_lshlrev_b32_e32 v28, 16, v28
	v_and_b32_e32 v35, 0xffff0000, v33
	v_lshlrev_b32_e32 v34, 16, v33
	v_and_b32_e32 v33, 0xffff0000, v32
	v_lshlrev_b32_e32 v32, 16, v32
	v_and_b32_e32 v39, 0xffff0000, v37
	v_lshlrev_b32_e32 v38, 16, v37
	v_and_b32_e32 v37, 0xffff0000, v36
	v_lshlrev_b32_e32 v36, 16, v36
	v_and_b32_e32 v43, 0xffff0000, v41
	v_lshlrev_b32_e32 v42, 16, v41
	v_and_b32_e32 v41, 0xffff0000, v40
	v_lshlrev_b32_e32 v40, 16, v40
	v_and_b32_e32 v47, 0xffff0000, v45
	v_lshlrev_b32_e32 v46, 16, v45
	v_and_b32_e32 v45, 0xffff0000, v44
	v_lshlrev_b32_e32 v44, 16, v44
	v_add_f32_e32 v140, v44, v40
	v_add_f32_e32 v141, v45, v41
	v_add_f32_e32 v142, v46, v42
	v_add_f32_e32 v143, v47, v43
	v_add_f32_e32 v140, v140, v36
	v_add_f32_e32 v141, v141, v37
	v_add_f32_e32 v142, v142, v38
	v_add_f32_e32 v143, v143, v39
	v_add_f32_e32 v140, v140, v32
	v_add_f32_e32 v141, v141, v33
	v_add_f32_e32 v142, v142, v34
	v_add_f32_e32 v143, v143, v35
	v_add_f32_e32 v140, v140, v28
	v_add_f32_e32 v141, v141, v29
	v_add_f32_e32 v142, v142, v30
	v_add_f32_e32 v143, v143, v31
	v_add_f32_e32 v140, v140, v24
	v_add_f32_e32 v141, v141, v25
	v_add_f32_e32 v142, v142, v26
	v_add_f32_e32 v143, v143, v27
	v_add_f32_e32 v140, v140, v20
	v_add_f32_e32 v141, v141, v21
	v_add_f32_e32 v142, v142, v22
	v_add_f32_e32 v143, v143, v23
	v_add_f32_e32 v140, v140, v16
	v_add_f32_e32 v141, v141, v17
	v_add_f32_e32 v142, v142, v18
	v_add_f32_e32 v143, v143, v19
	v_mul_f32_e32 v140, 0x3e000000, v140
	v_mul_f32_e32 v141, 0x3e000000, v141
	v_mul_f32_e32 v142, 0x3e000000, v142
	v_mul_f32_e32 v143, 0x3e000000, v143
	v_sub_f32_e32 v140, v140, v44
	v_sub_f32_e32 v141, v141, v45
	v_sub_f32_e32 v142, v142, v46
	v_sub_f32_e32 v143, v143, v47
	v_cvt_pk_bf16_f32 v144, v140, v141
	v_cvt_pk_bf16_f32 v145, v142, v143
	global_store_dwordx2 v11, v[144:145], s[24:25]
	s_add_u32 s24, s24, 0x800
	s_addc_u32 s25, s25, 0
	s_waitcnt vmcnt(14)
; DI float bflo(unsigned u) { return __uint_as_float(u << 16); }
; DI float bfhi(unsigned u) { return __uint_as_float(u & 0xffff0000u); }
; template <int WIN>
; DI void pool_elem(const Params& p, int row, int c) {
;     ...
;     if (t >= WIN - 1) {
;       cnt = (float)WIN;
;       unsigned w[WIN - 1];
; #pragma unroll
;       for (int j = 1; j < WIN; ++j) w[j - 1] = *(const unsigned*)(P2 + (size_t)(row - j) * 2048 + c);
; #pragma unroll
;       for (int j = 1; j < WIN; ++j) { s0 += bflo(w[j - 1]); s1 += bfhi(w[j - 1]); }
;     ...
;   *(unsigned*)(p.MIX + (size_t)row * 1024 + c) = pack2(s0 / cnt - u0, s1 / cnt - u1);
	v_and_b32_e32 v51, 0xffff0000, v49
	v_lshlrev_b32_e32 v50, 16, v49
	v_and_b32_e32 v49, 0xffff0000, v48
	v_lshlrev_b32_e32 v48, 16, v48
	v_add_f32_e32 v140, v48, v44
	v_add_f32_e32 v141, v49, v45
	v_add_f32_e32 v142, v50, v46
	v_add_f32_e32 v143, v51, v47
	v_add_f32_e32 v140, v140, v40
	v_add_f32_e32 v141, v141, v41
	v_add_f32_e32 v142, v142, v42
	v_add_f32_e32 v143, v143, v43
	v_add_f32_e32 v140, v140, v36
	v_add_f32_e32 v141, v141, v37
	v_add_f32_e32 v142, v142, v38
	v_add_f32_e32 v143, v143, v39
	v_add_f32_e32 v140, v140, v32
	v_add_f32_e32 v141, v141, v33
	v_add_f32_e32 v142, v142, v34
	v_add_f32_e32 v143, v143, v35
	v_add_f32_e32 v140, v140, v28
	v_add_f32_e32 v141, v141, v29
	v_add_f32_e32 v142, v142, v30
	v_add_f32_e32 v143, v143, v31
	v_add_f32_e32 v140, v140, v24
	v_add_f32_e32 v141, v141, v25
	v_add_f32_e32 v142, v142, v26
	v_add_f32_e32 v143, v143, v27
	v_add_f32_e32 v140, v140, v20
	v_add_f32_e32 v141, v141, v21
	v_add_f32_e32 v142, v142, v22
	v_add_f32_e32 v143, v143, v23
	v_mul_f32_e32 v140, 0x3e000000, v140
	v_mul_f32_e32 v141, 0x3e000000, v141
	v_mul_f32_e32 v142, 0x3e000000, v142
	v_mul_f32_e32 v143, 0x3e000000, v143
	v_sub_f32_e32 v140, v140, v48
	v_sub_f32_e32 v141, v141, v49
	v_sub_f32_e32 v142, v142, v50
	v_sub_f32_e32 v143, v143, v51
	v_cvt_pk_bf16_f32 v144, v140, v141
	v_cvt_pk_bf16_f32 v145, v142, v143
	global_store_dwordx2 v11, v[144:145], s[24:25]
	s_add_u32 s24, s24, 0x800
	s_addc_u32 s25, s25, 0
	s_waitcnt vmcnt(13)
	v_and_b32_e32 v55, 0xffff0000, v53
	v_lshlrev_b32_e32 v54, 16, v53
	v_and_b32_e32 v53, 0xffff0000, v52
	v_lshlrev_b32_e32 v52, 16, v52
	v_add_f32_e32 v140, v52, v48
	v_add_f32_e32 v141, v53, v49
	v_add_f32_e32 v142, v54, v50
	v_add_f32_e32 v143, v55, v51
	v_add_f32_e32 v140, v140, v44
	v_add_f32_e32 v141, v141, v45
	v_add_f32_e32 v142, v142, v46
	v_add_f32_e32 v143, v143, v47
	v_add_f32_e32 v140, v140, v40
	v_add_f32_e32 v141, v141, v41
	v_add_f32_e32 v142, v142, v42
	v_add_f32_e32 v143, v143, v43
	v_add_f32_e32 v140, v140, v36
	v_add_f32_e32 v141, v141, v37
	v_add_f32_e32 v142, v142, v38
	v_add_f32_e32 v143, v143, v39
	v_add_f32_e32 v140, v140, v32
	v_add_f32_e32 v141, v141, v33
	v_add_f32_e32 v142, v142, v34
	v_add_f32_e32 v143, v143, v35
	v_add_f32_e32 v140, v140, v28
	v_add_f32_e32 v141, v141, v29
	v_add_f32_e32 v142, v142, v30
	v_add_f32_e32 v143, v143, v31
	v_add_f32_e32 v140, v140, v24
	v_add_f32_e32 v141, v141, v25
	v_add_f32_e32 v142, v142, v26
	v_add_f32_e32 v143, v143, v27
	v_mul_f32_e32 v140, 0x3e000000, v140
	v_mul_f32_e32 v141, 0x3e000000, v141
	v_mul_f32_e32 v142, 0x3e000000, v142
	v_mul_f32_e32 v143, 0x3e000000, v143
	v_sub_f32_e32 v140, v140, v52
	v_sub_f32_e32 v141, v141, v53
	v_sub_f32_e32 v142, v142, v54
	v_sub_f32_e32 v143, v143, v55
	v_cvt_pk_bf16_f32 v144, v140, v141
	v_cvt_pk_bf16_f32 v145, v142, v143
	global_store_dwordx2 v11, v[144:145], s[24:25]
	s_add_u32 s24, s24, 0x800
	s_addc_u32 s25, s25, 0
	s_waitcnt vmcnt(12)
	v_and_b32_e32 v59, 0xffff0000, v57
	v_lshlrev_b32_e32 v58, 16, v57
	v_and_b32_e32 v57, 0xffff0000, v56
	v_lshlrev_b32_e32 v56, 16, v56
	v_add_f32_e32 v140, v56, v52
	v_add_f32_e32 v141, v57, v53
	v_add_f32_e32 v142, v58, v54
	v_add_f32_e32 v143, v59, v55
	v_add_f32_e32 v140, v140, v48
	v_add_f32_e32 v141, v141, v49
	v_add_f32_e32 v142, v142, v50
	v_add_f32_e32 v143, v143, v51
	v_add_f32_e32 v140, v140, v44
	v_add_f32_e32 v141, v141, v45
	v_add_f32_e32 v142, v142, v46
	v_add_f32_e32 v143, v143, v47
	v_add_f32_e32 v140, v140, v40
	v_add_f32_e32 v141, v141, v41
	v_add_f32_e32 v142, v142, v42
	v_add_f32_e32 v143, v143, v43
	v_add_f32_e32 v140, v140, v36
	v_add_f32_e32 v141, v141, v37
	v_add_f32_e32 v142, v142, v38
	v_add_f32_e32 v143, v143, v39
	v_add_f32_e32 v140, v140, v32
	v_add_f32_e32 v141, v141, v33
	v_add_f32_e32 v142, v142, v34
	v_add_f32_e32 v143, v143, v35
	v_add_f32_e32 v140, v140, v28
	v_add_f32_e32 v141, v141, v29
	v_add_f32_e32 v142, v142, v30
	v_add_f32_e32 v143, v143, v31
	v_mul_f32_e32 v140, 0x3e000000, v140
	v_mul_f32_e32 v141, 0x3e000000, v141
	v_mul_f32_e32 v142, 0x3e000000, v142
	v_mul_f32_e32 v143, 0x3e000000, v143
	v_sub_f32_e32 v140, v140, v56
	v_sub_f32_e32 v141, v141, v57
	v_sub_f32_e32 v142, v142, v58
	v_sub_f32_e32 v143, v143, v59
	v_cvt_pk_bf16_f32 v144, v140, v141
	v_cvt_pk_bf16_f32 v145, v142, v143
	global_store_dwordx2 v11, v[144:145], s[24:25]
	s_add_u32 s24, s24, 0x800
	s_addc_u32 s25, s25, 0
	s_waitcnt vmcnt(11)
	v_and_b32_e32 v63, 0xffff0000, v61
	v_lshlrev_b32_e32 v62, 16, v61
	v_and_b32_e32 v61, 0xffff0000, v60
	v_lshlrev_b32_e32 v60, 16, v60
	v_add_f32_e32 v140, v60, v56
	v_add_f32_e32 v141, v61, v57
	v_add_f32_e32 v142, v62, v58
	v_add_f32_e32 v143, v63, v59
	v_add_f32_e32 v140, v140, v52
	v_add_f32_e32 v141, v141, v53
	v_add_f32_e32 v142, v142, v54
	v_add_f32_e32 v143, v143, v55
	v_add_f32_e32 v140, v140, v48
	v_add_f32_e32 v141, v141, v49
	v_add_f32_e32 v142, v142, v50
	v_add_f32_e32 v143, v143, v51
	v_add_f32_e32 v140, v140, v44
	v_add_f32_e32 v141, v141, v45
	v_add_f32_e32 v142, v142, v46
	v_add_f32_e32 v143, v143, v47
	v_add_f32_e32 v140, v140, v40
	v_add_f32_e32 v141, v141, v41
	v_add_f32_e32 v142, v142, v42
	v_add_f32_e32 v143, v143, v43
	v_add_f32_e32 v140, v140, v36
	v_add_f32_e32 v141, v141, v37
	v_add_f32_e32 v142, v142, v38
	v_add_f32_e32 v143, v143, v39
	v_add_f32_e32 v140, v140, v32
	v_add_f32_e32 v141, v141, v33
	v_add_f32_e32 v142, v142, v34
	v_add_f32_e32 v143, v143, v35
	v_mul_f32_e32 v140, 0x3e000000, v140
	v_mul_f32_e32 v141, 0x3e000000, v141
	v_mul_f32_e32 v142, 0x3e000000, v142
	v_mul_f32_e32 v143, 0x3e000000, v143
	v_sub_f32_e32 v140, v140, v60
	v_sub_f32_e32 v141, v141, v61
	v_sub_f32_e32 v142, v142, v62
	v_sub_f32_e32 v143, v143, v63
	v_cvt_pk_bf16_f32 v144, v140, v141
	v_cvt_pk_bf16_f32 v145, v142, v143
	global_store_dwordx2 v11, v[144:145], s[24:25]
	s_add_u32 s24, s24, 0x800
	s_addc_u32 s25, s25, 0
	s_waitcnt vmcnt(10)
; DI float bflo(unsigned u) { return __uint_as_float(u << 16); }
; DI float bfhi(unsigned u) { return __uint_as_float(u & 0xffff0000u); }
; template <int WIN>
; DI void pool_elem(const Params& p, int row, int c) {
;     ...
;     if (t >= WIN - 1) {
;       cnt = (float)WIN;
;       unsigned w[WIN - 1];
; #pragma unroll
;       for (int j = 1; j < WIN; ++j) w[j - 1] = *(const unsigned*)(P2 + (size_t)(row - j) * 2048 + c);
; #pragma unroll
;       for (int j = 1; j < WIN; ++j) { s0 += bflo(w[j - 1]); s1 += bfhi(w[j - 1]); }
;     ...
;   *(unsigned*)(p.MIX + (size_t)row * 1024 + c) = pack2(s0 / cnt - u0, s1 / cnt - u1);
	v_and_b32_e32 v67, 0xffff0000, v65
	v_lshlrev_b32_e32 v66, 16, v65
	v_and_b32_e32 v65, 0xffff0000, v64
	v_lshlrev_b32_e32 v64, 16, v64
	v_add_f32_e32 v140, v64, v60
	v_add_f32_e32 v141, v65, v61
	v_add_f32_e32 v142, v66, v62
	v_add_f32_e32 v143, v67, v63
	v_add_f32_e32 v140, v140, v56
	v_add_f32_e32 v141, v141, v57
	v_add_f32_e32 v142, v142, v58
	v_add_f32_e32 v143, v143, v59
	v_add_f32_e32 v140, v140, v52
	v_add_f32_e32 v141, v141, v53
	v_add_f32_e32 v142, v142, v54
	v_add_f32_e32 v143, v143, v55
	v_add_f32_e32 v140, v140, v48
	v_add_f32_e32 v141, v141, v49
	v_add_f32_e32 v142, v142, v50
	v_add_f32_e32 v143, v143, v51
	v_add_f32_e32 v140, v140, v44
	v_add_f32_e32 v141, v141, v45
	v_add_f32_e32 v142, v142, v46
	v_add_f32_e32 v143, v143, v47
	v_add_f32_e32 v140, v140, v40
	v_add_f32_e32 v141, v141, v41
	v_add_f32_e32 v142, v142, v42
	v_add_f32_e32 v143, v143, v43
	v_add_f32_e32 v140, v140, v36
	v_add_f32_e32 v141, v141, v37
	v_add_f32_e32 v142, v142, v38
	v_add_f32_e32 v143, v143, v39
	v_mul_f32_e32 v140, 0x3e000000, v140
	v_mul_f32_e32 v141, 0x3e000000, v141
	v_mul_f32_e32 v142, 0x3e000000, v142
	v_mul_f32_e32 v143, 0x3e000000, v143
	v_sub_f32_e32 v140, v140, v64
	v_sub_f32_e32 v141, v141, v65
	v_sub_f32_e32 v142, v142, v66
	v_sub_f32_e32 v143, v143, v67
	v_cvt_pk_bf16_f32 v144, v140, v141
	v_cvt_pk_bf16_f32 v145, v142, v143
	global_store_dwordx2 v11, v[144:145], s[24:25]
	s_add_u32 s24, s24, 0x800
	s_addc_u32 s25, s25, 0
	s_waitcnt vmcnt(9)
	v_and_b32_e32 v71, 0xffff0000, v69
	v_lshlrev_b32_e32 v70, 16, v69
	v_and_b32_e32 v69, 0xffff0000, v68
	v_lshlrev_b32_e32 v68, 16, v68
	v_add_f32_e32 v140, v68, v64
	v_add_f32_e32 v141, v69, v65
	v_add_f32_e32 v142, v70, v66
	v_add_f32_e32 v143, v71, v67
	v_add_f32_e32 v140, v140, v60
	v_add_f32_e32 v141, v141, v61
	v_add_f32_e32 v142, v142, v62
	v_add_f32_e32 v143, v143, v63
	v_add_f32_e32 v140, v140, v56
	v_add_f32_e32 v141, v141, v57
	v_add_f32_e32 v142, v142, v58
	v_add_f32_e32 v143, v143, v59
	v_add_f32_e32 v140, v140, v52
	v_add_f32_e32 v141, v141, v53
	v_add_f32_e32 v142, v142, v54
	v_add_f32_e32 v143, v143, v55
	v_add_f32_e32 v140, v140, v48
	v_add_f32_e32 v141, v141, v49
	v_add_f32_e32 v142, v142, v50
	v_add_f32_e32 v143, v143, v51
	v_add_f32_e32 v140, v140, v44
	v_add_f32_e32 v141, v141, v45
	v_add_f32_e32 v142, v142, v46
	v_add_f32_e32 v143, v143, v47
	v_add_f32_e32 v140, v140, v40
	v_add_f32_e32 v141, v141, v41
	v_add_f32_e32 v142, v142, v42
	v_add_f32_e32 v143, v143, v43
	v_mul_f32_e32 v140, 0x3e000000, v140
	v_mul_f32_e32 v141, 0x3e000000, v141
	v_mul_f32_e32 v142, 0x3e000000, v142
	v_mul_f32_e32 v143, 0x3e000000, v143
	v_sub_f32_e32 v140, v140, v68
	v_sub_f32_e32 v141, v141, v69
	v_sub_f32_e32 v142, v142, v70
	v_sub_f32_e32 v143, v143, v71
	v_cvt_pk_bf16_f32 v144, v140, v141
	v_cvt_pk_bf16_f32 v145, v142, v143
	global_store_dwordx2 v11, v[144:145], s[24:25]
	s_add_u32 s24, s24, 0x800
	s_addc_u32 s25, s25, 0
	s_waitcnt vmcnt(8)
	v_and_b32_e32 v75, 0xffff0000, v73
	v_lshlrev_b32_e32 v74, 16, v73
	v_and_b32_e32 v73, 0xffff0000, v72
	v_lshlrev_b32_e32 v72, 16, v72
	v_add_f32_e32 v140, v72, v68
	v_add_f32_e32 v141, v73, v69
	v_add_f32_e32 v142, v74, v70
	v_add_f32_e32 v143, v75, v71
	v_add_f32_e32 v140, v140, v64
	v_add_f32_e32 v141, v141, v65
	v_add_f32_e32 v142, v142, v66
	v_add_f32_e32 v143, v143, v67
	v_add_f32_e32 v140, v140, v60
	v_add_f32_e32 v141, v141, v61
	v_add_f32_e32 v142, v142, v62
	v_add_f32_e32 v143, v143, v63
	v_add_f32_e32 v140, v140, v56
	v_add_f32_e32 v141, v141, v57
	v_add_f32_e32 v142, v142, v58
	v_add_f32_e32 v143, v143, v59
	v_add_f32_e32 v140, v140, v52
	v_add_f32_e32 v141, v141, v53
	v_add_f32_e32 v142, v142, v54
	v_add_f32_e32 v143, v143, v55
	v_add_f32_e32 v140, v140, v48
	v_add_f32_e32 v141, v141, v49
	v_add_f32_e32 v142, v142, v50
	v_add_f32_e32 v143, v143, v51
	v_add_f32_e32 v140, v140, v44
	v_add_f32_e32 v141, v141, v45
	v_add_f32_e32 v142, v142, v46
	v_add_f32_e32 v143, v143, v47
	v_mul_f32_e32 v140, 0x3e000000, v140
	v_mul_f32_e32 v141, 0x3e000000, v141
	v_mul_f32_e32 v142, 0x3e000000, v142
	v_mul_f32_e32 v143, 0x3e000000, v143
	v_sub_f32_e32 v140, v140, v72
	v_sub_f32_e32 v141, v141, v73
	v_sub_f32_e32 v142, v142, v74
	v_sub_f32_e32 v143, v143, v75
	v_cvt_pk_bf16_f32 v144, v140, v141
	v_cvt_pk_bf16_f32 v145, v142, v143
	global_store_dwordx2 v11, v[144:145], s[24:25]
	s_add_u32 s24, s24, 0x800
	s_addc_u32 s25, s25, 0
	s_waitcnt vmcnt(7)
	v_and_b32_e32 v79, 0xffff0000, v77
	v_lshlrev_b32_e32 v78, 16, v77
	v_and_b32_e32 v77, 0xffff0000, v76
	v_lshlrev_b32_e32 v76, 16, v76
	v_add_f32_e32 v140, v76, v72
	v_add_f32_e32 v141, v77, v73
	v_add_f32_e32 v142, v78, v74
	v_add_f32_e32 v143, v79, v75
	v_add_f32_e32 v140, v140, v68
	v_add_f32_e32 v141, v141, v69
	v_add_f32_e32 v142, v142, v70
	v_add_f32_e32 v143, v143, v71
	v_add_f32_e32 v140, v140, v64
	v_add_f32_e32 v141, v141, v65
	v_add_f32_e32 v142, v142, v66
	v_add_f32_e32 v143, v143, v67
	v_add_f32_e32 v140, v140, v60
	v_add_f32_e32 v141, v141, v61
	v_add_f32_e32 v142, v142, v62
	v_add_f32_e32 v143, v143, v63
	v_add_f32_e32 v140, v140, v56
	v_add_f32_e32 v141, v141, v57
	v_add_f32_e32 v142, v142, v58
	v_add_f32_e32 v143, v143, v59
	v_add_f32_e32 v140, v140, v52
	v_add_f32_e32 v141, v141, v53
	v_add_f32_e32 v142, v142, v54
	v_add_f32_e32 v143, v143, v55
	v_add_f32_e32 v140, v140, v48
	v_add_f32_e32 v141, v141, v49
	v_add_f32_e32 v142, v142, v50
	v_add_f32_e32 v143, v143, v51
	v_mul_f32_e32 v140, 0x3e000000, v140
	v_mul_f32_e32 v141, 0x3e000000, v141
	v_mul_f32_e32 v142, 0x3e000000, v142
	v_mul_f32_e32 v143, 0x3e000000, v143
	v_sub_f32_e32 v140, v140, v76
	v_sub_f32_e32 v141, v141, v77
	v_sub_f32_e32 v142, v142, v78
	v_sub_f32_e32 v143, v143, v79
	v_cvt_pk_bf16_f32 v144, v140, v141
	v_cvt_pk_bf16_f32 v145, v142, v143
	global_store_dwordx2 v11, v[144:145], s[24:25]
	s_add_u32 s24, s24, 0x800
	s_addc_u32 s25, s25, 0
	s_waitcnt vmcnt(6)
; DI float bflo(unsigned u) { return __uint_as_float(u << 16); }
; DI float bfhi(unsigned u) { return __uint_as_float(u & 0xffff0000u); }
; template <int WIN>
; DI void pool_elem(const Params& p, int row, int c) {
;     ...
;     if (t >= WIN - 1) {
;       cnt = (float)WIN;
;       unsigned w[WIN - 1];
; #pragma unroll
;       for (int j = 1; j < WIN; ++j) w[j - 1] = *(const unsigned*)(P2 + (size_t)(row - j) * 2048 + c);
; #pragma unroll
;       for (int j = 1; j < WIN; ++j) { s0 += bflo(w[j - 1]); s1 += bfhi(w[j - 1]); }
;     ...
;   *(unsigned*)(p.MIX + (size_t)row * 1024 + c) = pack2(s0 / cnt - u0, s1 / cnt - u1);
	v_and_b32_e32 v83, 0xffff0000, v81
	v_lshlrev_b32_e32 v82, 16, v81
	v_and_b32_e32 v81, 0xffff0000, v80
	v_lshlrev_b32_e32 v80, 16, v80
	v_add_f32_e32 v140, v80, v76
	v_add_f32_e32 v141, v81, v77
	v_add_f32_e32 v142, v82, v78
	v_add_f32_e32 v143, v83, v79
	v_add_f32_e32 v140, v140, v72
	v_add_f32_e32 v141, v141, v73
	v_add_f32_e32 v142, v142, v74
	v_add_f32_e32 v143, v143, v75
	v_add_f32_e32 v140, v140, v68
	v_add_f32_e32 v141, v141, v69
	v_add_f32_e32 v142, v142, v70
	v_add_f32_e32 v143, v143, v71
	v_add_f32_e32 v140, v140, v64
	v_add_f32_e32 v141, v141, v65
	v_add_f32_e32 v142, v142, v66
	v_add_f32_e32 v143, v143, v67
	v_add_f32_e32 v140, v140, v60
	v_add_f32_e32 v141, v141, v61
	v_add_f32_e32 v142, v142, v62
	v_add_f32_e32 v143, v143, v63
	v_add_f32_e32 v140, v140, v56
	v_add_f32_e32 v141, v141, v57
	v_add_f32_e32 v142, v142, v58
	v_add_f32_e32 v143, v143, v59
	v_add_f32_e32 v140, v140, v52
	v_add_f32_e32 v141, v141, v53
	v_add_f32_e32 v142, v142, v54
	v_add_f32_e32 v143, v143, v55
	v_mul_f32_e32 v140, 0x3e000000, v140
	v_mul_f32_e32 v141, 0x3e000000, v141
	v_mul_f32_e32 v142, 0x3e000000, v142
	v_mul_f32_e32 v143, 0x3e000000, v143
	v_sub_f32_e32 v140, v140, v80
	v_sub_f32_e32 v141, v141, v81
	v_sub_f32_e32 v142, v142, v82
	v_sub_f32_e32 v143, v143, v83
	v_cvt_pk_bf16_f32 v144, v140, v141
	v_cvt_pk_bf16_f32 v145, v142, v143
	global_store_dwordx2 v11, v[144:145], s[24:25]
	s_add_u32 s24, s24, 0x800
	s_addc_u32 s25, s25, 0
	s_waitcnt vmcnt(5)
	v_and_b32_e32 v87, 0xffff0000, v85
	v_lshlrev_b32_e32 v86, 16, v85
	v_and_b32_e32 v85, 0xffff0000, v84
	v_lshlrev_b32_e32 v84, 16, v84
	v_add_f32_e32 v140, v84, v80
	v_add_f32_e32 v141, v85, v81
	v_add_f32_e32 v142, v86, v82
	v_add_f32_e32 v143, v87, v83
	v_add_f32_e32 v140, v140, v76
	v_add_f32_e32 v141, v141, v77
	v_add_f32_e32 v142, v142, v78
	v_add_f32_e32 v143, v143, v79
	v_add_f32_e32 v140, v140, v72
	v_add_f32_e32 v141, v141, v73
	v_add_f32_e32 v142, v142, v74
	v_add_f32_e32 v143, v143, v75
	v_add_f32_e32 v140, v140, v68
	v_add_f32_e32 v141, v141, v69
	v_add_f32_e32 v142, v142, v70
	v_add_f32_e32 v143, v143, v71
	v_add_f32_e32 v140, v140, v64
	v_add_f32_e32 v141, v141, v65
	v_add_f32_e32 v142, v142, v66
	v_add_f32_e32 v143, v143, v67
	v_add_f32_e32 v140, v140, v60
	v_add_f32_e32 v141, v141, v61
	v_add_f32_e32 v142, v142, v62
	v_add_f32_e32 v143, v143, v63
	v_add_f32_e32 v140, v140, v56
	v_add_f32_e32 v141, v141, v57
	v_add_f32_e32 v142, v142, v58
	v_add_f32_e32 v143, v143, v59
	v_mul_f32_e32 v140, 0x3e000000, v140
	v_mul_f32_e32 v141, 0x3e000000, v141
	v_mul_f32_e32 v142, 0x3e000000, v142
	v_mul_f32_e32 v143, 0x3e000000, v143
	v_sub_f32_e32 v140, v140, v84
	v_sub_f32_e32 v141, v141, v85
	v_sub_f32_e32 v142, v142, v86
	v_sub_f32_e32 v143, v143, v87
	v_cvt_pk_bf16_f32 v144, v140, v141
	v_cvt_pk_bf16_f32 v145, v142, v143
	global_store_dwordx2 v11, v[144:145], s[24:25]
	s_add_u32 s24, s24, 0x800
	s_addc_u32 s25, s25, 0
	s_waitcnt vmcnt(4)
	v_and_b32_e32 v91, 0xffff0000, v89
	v_lshlrev_b32_e32 v90, 16, v89
	v_and_b32_e32 v89, 0xffff0000, v88
	v_lshlrev_b32_e32 v88, 16, v88
	v_add_f32_e32 v140, v88, v84
	v_add_f32_e32 v141, v89, v85
	v_add_f32_e32 v142, v90, v86
	v_add_f32_e32 v143, v91, v87
	v_add_f32_e32 v140, v140, v80
	v_add_f32_e32 v141, v141, v81
	v_add_f32_e32 v142, v142, v82
	v_add_f32_e32 v143, v143, v83
	v_add_f32_e32 v140, v140, v76
	v_add_f32_e32 v141, v141, v77
	v_add_f32_e32 v142, v142, v78
	v_add_f32_e32 v143, v143, v79
	v_add_f32_e32 v140, v140, v72
	v_add_f32_e32 v141, v141, v73
	v_add_f32_e32 v142, v142, v74
	v_add_f32_e32 v143, v143, v75
	v_add_f32_e32 v140, v140, v68
	v_add_f32_e32 v141, v141, v69
	v_add_f32_e32 v142, v142, v70
	v_add_f32_e32 v143, v143, v71
	v_add_f32_e32 v140, v140, v64
	v_add_f32_e32 v141, v141, v65
	v_add_f32_e32 v142, v142, v66
	v_add_f32_e32 v143, v143, v67
	v_add_f32_e32 v140, v140, v60
	v_add_f32_e32 v141, v141, v61
	v_add_f32_e32 v142, v142, v62
	v_add_f32_e32 v143, v143, v63
	v_mul_f32_e32 v140, 0x3e000000, v140
	v_mul_f32_e32 v141, 0x3e000000, v141
	v_mul_f32_e32 v142, 0x3e000000, v142
	v_mul_f32_e32 v143, 0x3e000000, v143
	v_sub_f32_e32 v140, v140, v88
	v_sub_f32_e32 v141, v141, v89
	v_sub_f32_e32 v142, v142, v90
	v_sub_f32_e32 v143, v143, v91
	v_cvt_pk_bf16_f32 v144, v140, v141
	v_cvt_pk_bf16_f32 v145, v142, v143
	global_store_dwordx2 v11, v[144:145], s[24:25]
	s_add_u32 s24, s24, 0x800
	s_addc_u32 s25, s25, 0
	s_waitcnt vmcnt(3)
	v_and_b32_e32 v95, 0xffff0000, v93
	v_lshlrev_b32_e32 v94, 16, v93
	v_and_b32_e32 v93, 0xffff0000, v92
	v_lshlrev_b32_e32 v92, 16, v92
	v_add_f32_e32 v140, v92, v88
	v_add_f32_e32 v141, v93, v89
	v_add_f32_e32 v142, v94, v90
	v_add_f32_e32 v143, v95, v91
	v_add_f32_e32 v140, v140, v84
	v_add_f32_e32 v141, v141, v85
	v_add_f32_e32 v142, v142, v86
	v_add_f32_e32 v143, v143, v87
	v_add_f32_e32 v140, v140, v80
	v_add_f32_e32 v141, v141, v81
	v_add_f32_e32 v142, v142, v82
	v_add_f32_e32 v143, v143, v83
	v_add_f32_e32 v140, v140, v76
	v_add_f32_e32 v141, v141, v77
	v_add_f32_e32 v142, v142, v78
	v_add_f32_e32 v143, v143, v79
	v_add_f32_e32 v140, v140, v72
	v_add_f32_e32 v141, v141, v73
	v_add_f32_e32 v142, v142, v74
	v_add_f32_e32 v143, v143, v75
	v_add_f32_e32 v140, v140, v68
	v_add_f32_e32 v141, v141, v69
	v_add_f32_e32 v142, v142, v70
	v_add_f32_e32 v143, v143, v71
	v_add_f32_e32 v140, v140, v64
	v_add_f32_e32 v141, v141, v65
	v_add_f32_e32 v142, v142, v66
	v_add_f32_e32 v143, v143, v67
	v_mul_f32_e32 v140, 0x3e000000, v140
	v_mul_f32_e32 v141, 0x3e000000, v141
	v_mul_f32_e32 v142, 0x3e000000, v142
	v_mul_f32_e32 v143, 0x3e000000, v143
	v_sub_f32_e32 v140, v140, v92
	v_sub_f32_e32 v141, v141, v93
	v_sub_f32_e32 v142, v142, v94
	v_sub_f32_e32 v143, v143, v95
	v_cvt_pk_bf16_f32 v144, v140, v141
	v_cvt_pk_bf16_f32 v145, v142, v143
	global_store_dwordx2 v11, v[144:145], s[24:25]
	s_add_u32 s24, s24, 0x800
	s_addc_u32 s25, s25, 0
	s_waitcnt vmcnt(2)
; DI float bflo(unsigned u) { return __uint_as_float(u << 16); }
; DI float bfhi(unsigned u) { return __uint_as_float(u & 0xffff0000u); }
; template <int WIN>
; DI void pool_elem(const Params& p, int row, int c) {
;     ...
;     if (t >= WIN - 1) {
;       cnt = (float)WIN;
;       unsigned w[WIN - 1];
; #pragma unroll
;       for (int j = 1; j < WIN; ++j) w[j - 1] = *(const unsigned*)(P2 + (size_t)(row - j) * 2048 + c);
; #pragma unroll
;       for (int j = 1; j < WIN; ++j) { s0 += bflo(w[j - 1]); s1 += bfhi(w[j - 1]); }
;     } else {
;       cnt = (float)(t + 1);
;       for (int j = 1; j <= t; ++j) {
;         unsigned w = *(const unsigned*)(P2 + (size_t)(row - j) * 2048 + c);
;         s0 += bflo(w); s1 += bfhi(w);
;       }
;     }
;     if (t >= 2033) {
;       float2 o = {u0, u1};
;       *(float2*)(p.out + O_POOLP + ((size_t)b * 15 + (t - 2033)) * 1024 + c) = o;
;     }
;   } else {
;     const int s = row - NPR;
;     cnt = (float)WIN;
;     const float* sp = p.state_pool + (size_t)s * 15 * 1024 + c;
;     float2 st[15];
; #pragma unroll
;     for (int j = 0; j < 15; ++j) st[j] = *(const float2*)(sp + (size_t)j * 1024);
; #pragma unroll
;     for (int j = 1; j < WIN; ++j) { s0 += st[15 - j].x; s1 += st[15 - j].y; }
;     float* op = p.out + O_POOLS + (size_t)s * 15 * 1024 + c;
; #pragma unroll
;     for (int j = 0; j < 14; ++j) *(float2*)(op + (size_t)j * 1024) = st[j + 1];
;     float2 o = {u0, u1};
;     *(float2*)(op + (size_t)14 * 1024) = o;
;   }
;   *(unsigned*)(p.MIX + (size_t)row * 1024 + c) = pack2(s0 / cnt - u0, s1 / cnt - u1);
	v_and_b32_e32 v99, 0xffff0000, v97
	v_lshlrev_b32_e32 v98, 16, v97
	v_and_b32_e32 v97, 0xffff0000, v96
	v_lshlrev_b32_e32 v96, 16, v96
	v_add_f32_e32 v140, v96, v92
	v_add_f32_e32 v141, v97, v93
	v_add_f32_e32 v142, v98, v94
	v_add_f32_e32 v143, v99, v95
	v_add_f32_e32 v140, v140, v88
	v_add_f32_e32 v141, v141, v89
	v_add_f32_e32 v142, v142, v90
	v_add_f32_e32 v143, v143, v91
	v_add_f32_e32 v140, v140, v84
	v_add_f32_e32 v141, v141, v85
	v_add_f32_e32 v142, v142, v86
	v_add_f32_e32 v143, v143, v87
	v_add_f32_e32 v140, v140, v80
	v_add_f32_e32 v141, v141, v81
	v_add_f32_e32 v142, v142, v82
	v_add_f32_e32 v143, v143, v83
	v_add_f32_e32 v140, v140, v76
	v_add_f32_e32 v141, v141, v77
	v_add_f32_e32 v142, v142, v78
	v_add_f32_e32 v143, v143, v79
	v_add_f32_e32 v140, v140, v72
	v_add_f32_e32 v141, v141, v73
	v_add_f32_e32 v142, v142, v74
	v_add_f32_e32 v143, v143, v75
	v_add_f32_e32 v140, v140, v68
	v_add_f32_e32 v141, v141, v69
	v_add_f32_e32 v142, v142, v70
	v_add_f32_e32 v143, v143, v71
	v_mul_f32_e32 v140, 0x3e000000, v140
	v_mul_f32_e32 v141, 0x3e000000, v141
	v_mul_f32_e32 v142, 0x3e000000, v142
	v_mul_f32_e32 v143, 0x3e000000, v143
	v_sub_f32_e32 v140, v140, v96
	v_sub_f32_e32 v141, v141, v97
	v_sub_f32_e32 v142, v142, v98
	v_sub_f32_e32 v143, v143, v99
	v_cvt_pk_bf16_f32 v144, v140, v141
	v_cvt_pk_bf16_f32 v145, v142, v143
	global_store_dwordx2 v11, v[144:145], s[24:25]
	s_add_u32 s24, s24, 0x800
	s_addc_u32 s25, s25, 0
	s_waitcnt vmcnt(1)
	v_and_b32_e32 v103, 0xffff0000, v101
	v_lshlrev_b32_e32 v102, 16, v101
	v_and_b32_e32 v101, 0xffff0000, v100
	v_lshlrev_b32_e32 v100, 16, v100
	v_add_f32_e32 v140, v100, v96
	v_add_f32_e32 v141, v101, v97
	v_add_f32_e32 v142, v102, v98
	v_add_f32_e32 v143, v103, v99
	v_add_f32_e32 v140, v140, v92
	v_add_f32_e32 v141, v141, v93
	v_add_f32_e32 v142, v142, v94
	v_add_f32_e32 v143, v143, v95
	v_add_f32_e32 v140, v140, v88
	v_add_f32_e32 v141, v141, v89
	v_add_f32_e32 v142, v142, v90
	v_add_f32_e32 v143, v143, v91
	v_add_f32_e32 v140, v140, v84
	v_add_f32_e32 v141, v141, v85
	v_add_f32_e32 v142, v142, v86
	v_add_f32_e32 v143, v143, v87
	v_add_f32_e32 v140, v140, v80
	v_add_f32_e32 v141, v141, v81
	v_add_f32_e32 v142, v142, v82
	v_add_f32_e32 v143, v143, v83
	v_add_f32_e32 v140, v140, v76
	v_add_f32_e32 v141, v141, v77
	v_add_f32_e32 v142, v142, v78
	v_add_f32_e32 v143, v143, v79
	v_add_f32_e32 v140, v140, v72
	v_add_f32_e32 v141, v141, v73
	v_add_f32_e32 v142, v142, v74
	v_add_f32_e32 v143, v143, v75
	v_mul_f32_e32 v140, 0x3e000000, v140
	v_mul_f32_e32 v141, 0x3e000000, v141
	v_mul_f32_e32 v142, 0x3e000000, v142
	v_mul_f32_e32 v143, 0x3e000000, v143
	v_sub_f32_e32 v140, v140, v100
	v_sub_f32_e32 v141, v141, v101
	v_sub_f32_e32 v142, v142, v102
	v_sub_f32_e32 v143, v143, v103
	v_cvt_pk_bf16_f32 v144, v140, v141
	v_cvt_pk_bf16_f32 v145, v142, v143
	global_store_dwordx2 v11, v[144:145], s[24:25]
	s_add_u32 s24, s24, 0x800
	s_addc_u32 s25, s25, 0
	s_waitcnt vmcnt(0)
	v_and_b32_e32 v107, 0xffff0000, v105
	v_lshlrev_b32_e32 v106, 16, v105
	v_and_b32_e32 v105, 0xffff0000, v104
	v_lshlrev_b32_e32 v104, 16, v104
	v_add_f32_e32 v140, v104, v100
	v_add_f32_e32 v141, v105, v101
	v_add_f32_e32 v142, v106, v102
	v_add_f32_e32 v143, v107, v103
	v_add_f32_e32 v140, v140, v96
	v_add_f32_e32 v141, v141, v97
	v_add_f32_e32 v142, v142, v98
	v_add_f32_e32 v143, v143, v99
	v_add_f32_e32 v140, v140, v92
	v_add_f32_e32 v141, v141, v93
	v_add_f32_e32 v142, v142, v94
	v_add_f32_e32 v143, v143, v95
	v_add_f32_e32 v140, v140, v88
	v_add_f32_e32 v141, v141, v89
	v_add_f32_e32 v142, v142, v90
	v_add_f32_e32 v143, v143, v91
	v_add_f32_e32 v140, v140, v84
	v_add_f32_e32 v141, v141, v85
	v_add_f32_e32 v142, v142, v86
	v_add_f32_e32 v143, v143, v87
	v_add_f32_e32 v140, v140, v80
	v_add_f32_e32 v141, v141, v81
	v_add_f32_e32 v142, v142, v82
	v_add_f32_e32 v143, v143, v83
	v_add_f32_e32 v140, v140, v76
	v_add_f32_e32 v141, v141, v77
	v_add_f32_e32 v142, v142, v78
	v_add_f32_e32 v143, v143, v79
	v_mul_f32_e32 v140, 0x3e000000, v140
	v_mul_f32_e32 v141, 0x3e000000, v141
	v_mul_f32_e32 v142, 0x3e000000, v142
	v_mul_f32_e32 v143, 0x3e000000, v143
	v_sub_f32_e32 v140, v140, v104
	v_sub_f32_e32 v141, v141, v105
	v_sub_f32_e32 v142, v142, v106
	v_sub_f32_e32 v143, v143, v107
	v_cvt_pk_bf16_f32 v144, v140, v141
	v_cvt_pk_bf16_f32 v145, v142, v143
	global_store_dwordx2 v11, v[144:145], s[24:25]
	s_add_u32 s24, s24, 0x800
	s_addc_u32 s25, s25, 0
	s_cmp_eq_u32 s18, 127
	s_cbranch_scc0 .Lp13f_next
	s_mul_i32 s26, s17, 61440
	s_add_u32 s26, s26, 0x431c000
	s_add_u32 s22, s12, s26
	s_addc_u32 s23, s13, 0
	global_store_dwordx4 v12, v[48:51], s[22:23]
	s_add_u32 s22, s22, 0x1000
	s_addc_u32 s23, s23, 0
	global_store_dwordx4 v12, v[52:55], s[22:23]
	s_add_u32 s22, s22, 0x1000
	s_addc_u32 s23, s23, 0
	global_store_dwordx4 v12, v[56:59], s[22:23]
	s_add_u32 s22, s22, 0x1000
	s_addc_u32 s23, s23, 0
	global_store_dwordx4 v12, v[60:63], s[22:23]
	s_add_u32 s22, s22, 0x1000
	s_addc_u32 s23, s23, 0
	global_store_dwordx4 v12, v[64:67], s[22:23]
	s_add_u32 s22, s22, 0x1000
	s_addc_u32 s23, s23, 0
	global_store_dwordx4 v12, v[68:71], s[22:23]
	s_add_u32 s22, s22, 0x1000
	s_addc_u32 s23, s23, 0
	global_store_dwordx4 v12, v[72:75], s[22:23]
	s_add_u32 s22, s22, 0x1000
	s_addc_u32 s23, s23, 0
	global_store_dwordx4 v12, v[76:79], s[22:23]
	s_add_u32 s22, s22, 0x1000
	s_addc_u32 s23, s23, 0
	global_store_dwordx4 v12, v[80:83], s[22:23]
	s_add_u32 s22, s22, 0x1000
	s_addc_u32 s23, s23, 0
	global_store_dwordx4 v12, v[84:87], s[22:23]
	s_add_u32 s22, s22, 0x1000
	s_addc_u32 s23, s23, 0
	global_store_dwordx4 v12, v[88:91], s[22:23]
	s_add_u32 s22, s22, 0x1000
	s_addc_u32 s23, s23, 0
	global_store_dwordx4 v12, v[92:95], s[22:23]
	s_add_u32 s22, s22, 0x1000
	s_addc_u32 s23, s23, 0
	global_store_dwordx4 v12, v[96:99], s[22:23]
	s_add_u32 s22, s22, 0x1000
	s_addc_u32 s23, s23, 0
	global_store_dwordx4 v12, v[100:103], s[22:23]
	s_add_u32 s22, s22, 0x1000
	s_addc_u32 s23, s23, 0
	global_store_dwordx4 v12, v[104:107], s[22:23]
	s_add_u32 s22, s22, 0x1000
	s_addc_u32 s23, s23, 0
	s_branch .Lp13f_next
; DI float bflo(unsigned u) { return __uint_as_float(u << 16); }
; DI float bfhi(unsigned u) { return __uint_as_float(u & 0xffff0000u); }
; template <int WIN>
; DI void pool_elem(const Params& p, int row, int c) {
;     ...
;     if (t >= WIN - 1) {
;       cnt = (float)WIN;
;       unsigned w[WIN - 1];
; #pragma unroll
;       for (int j = 1; j < WIN; ++j) w[j - 1] = *(const unsigned*)(P2 + (size_t)(row - j) * 2048 + c);
; #pragma unroll
;       for (int j = 1; j < WIN; ++j) { s0 += bflo(w[j - 1]); s1 += bfhi(w[j - 1]); }
.Lp13f_w3:
	s_sub_u32 s26, s20, 15
	s_lshl_b32 s27, s26, 12
	s_lshr_b32 s28, s26, 20
	s_add_u32 s22, s8, s27
	s_addc_u32 s23, s9, s28
	global_load_dwordx2 v[16:17], v11, s[22:23]
	s_add_u32 s22, s22, 0x1000
	s_addc_u32 s23, s23, 0
	global_load_dwordx2 v[20:21], v11, s[22:23]
	s_add_u32 s22, s22, 0x1000
	s_addc_u32 s23, s23, 0
	global_load_dwordx2 v[24:25], v11, s[22:23]
	s_add_u32 s22, s22, 0x1000
	s_addc_u32 s23, s23, 0
	global_load_dwordx2 v[28:29], v11, s[22:23]
	s_add_u32 s22, s22, 0x1000
	s_addc_u32 s23, s23, 0
	global_load_dwordx2 v[32:33], v11, s[22:23]
	s_add_u32 s22, s22, 0x1000
	s_addc_u32 s23, s23, 0
	global_load_dwordx2 v[36:37], v11, s[22:23]
	s_add_u32 s22, s22, 0x1000
	s_addc_u32 s23, s23, 0
	global_load_dwordx2 v[40:41], v11, s[22:23]
	s_add_u32 s22, s22, 0x1000
	s_addc_u32 s23, s23, 0
	global_load_dwordx2 v[44:45], v11, s[22:23]
	s_add_u32 s22, s22, 0x1000
	s_addc_u32 s23, s23, 0
	global_load_dwordx2 v[48:49], v11, s[22:23]
	s_add_u32 s22, s22, 0x1000
	s_addc_u32 s23, s23, 0
	global_load_dwordx2 v[52:53], v11, s[22:23]
	s_add_u32 s22, s22, 0x1000
	s_addc_u32 s23, s23, 0
	global_load_dwordx2 v[56:57], v11, s[22:23]
	s_add_u32 s22, s22, 0x1000
	s_addc_u32 s23, s23, 0
	global_load_dwordx2 v[60:61], v11, s[22:23]
	s_add_u32 s22, s22, 0x1000
	s_addc_u32 s23, s23, 0
	global_load_dwordx2 v[64:65], v11, s[22:23]
	s_add_u32 s22, s22, 0x1000
	s_addc_u32 s23, s23, 0
	global_load_dwordx2 v[68:69], v11, s[22:23]
	s_add_u32 s22, s22, 0x1000
	s_addc_u32 s23, s23, 0
	global_load_dwordx2 v[72:73], v11, s[22:23]
	s_add_u32 s22, s22, 0x1000
	s_addc_u32 s23, s23, 0
	global_load_dwordx2 v[76:77], v11, s[22:23]
	s_add_u32 s22, s22, 0x1000
	s_addc_u32 s23, s23, 0
	global_load_dwordx2 v[80:81], v11, s[22:23]
	s_add_u32 s22, s22, 0x1000
	s_addc_u32 s23, s23, 0
	global_load_dwordx2 v[84:85], v11, s[22:23]
	s_add_u32 s22, s22, 0x1000
	s_addc_u32 s23, s23, 0
	global_load_dwordx2 v[88:89], v11, s[22:23]
	s_add_u32 s22, s22, 0x1000
	s_addc_u32 s23, s23, 0
	global_load_dwordx2 v[92:93], v11, s[22:23]
	s_add_u32 s22, s22, 0x1000
	s_addc_u32 s23, s23, 0
	global_load_dwordx2 v[96:97], v11, s[22:23]
	s_add_u32 s22, s22, 0x1000
	s_addc_u32 s23, s23, 0
	global_load_dwordx2 v[100:101], v11, s[22:23]
	s_add_u32 s22, s22, 0x1000
	s_addc_u32 s23, s23, 0
	global_load_dwordx2 v[104:105], v11, s[22:23]
	s_add_u32 s22, s22, 0x1000
	s_addc_u32 s23, s23, 0
	global_load_dwordx2 v[108:109], v11, s[22:23]
	s_add_u32 s22, s22, 0x1000
	s_addc_u32 s23, s23, 0
	global_load_dwordx2 v[112:113], v11, s[22:23]
	s_add_u32 s22, s22, 0x1000
	s_addc_u32 s23, s23, 0
	global_load_dwordx2 v[116:117], v11, s[22:23]
	s_add_u32 s22, s22, 0x1000
	s_addc_u32 s23, s23, 0
	global_load_dwordx2 v[120:121], v11, s[22:23]
	s_add_u32 s22, s22, 0x1000
	s_addc_u32 s23, s23, 0
	global_load_dwordx2 v[124:125], v11, s[22:23]
	s_add_u32 s22, s22, 0x1000
	s_addc_u32 s23, s23, 0
	global_load_dwordx2 v[128:129], v11, s[22:23]
	s_add_u32 s22, s22, 0x1000
	s_addc_u32 s23, s23, 0
	global_load_dwordx2 v[132:133], v11, s[22:23]
	s_add_u32 s22, s22, 0x1000
	s_addc_u32 s23, s23, 0
	global_load_dwordx2 v[136:137], v11, s[22:23]
	s_add_u32 s22, s22, 0x1000
	s_addc_u32 s23, s23, 0
	s_waitcnt vmcnt(15)
	v_and_b32_e32 v19, 0xffff0000, v17
	v_lshlrev_b32_e32 v18, 16, v17
	v_and_b32_e32 v17, 0xffff0000, v16
	v_lshlrev_b32_e32 v16, 16, v16
	v_and_b32_e32 v23, 0xffff0000, v21
	v_lshlrev_b32_e32 v22, 16, v21
	v_and_b32_e32 v21, 0xffff0000, v20
	v_lshlrev_b32_e32 v20, 16, v20
	v_and_b32_e32 v27, 0xffff0000, v25
	v_lshlrev_b32_e32 v26, 16, v25
	v_and_b32_e32 v25, 0xffff0000, v24
	v_lshlrev_b32_e32 v24, 16, v24
	v_and_b32_e32 v31, 0xffff0000, v29
	v_lshlrev_b32_e32 v30, 16, v29
	v_and_b32_e32 v29, 0xffff0000, v28
	v_lshlrev_b32_e32 v28, 16, v28
	v_and_b32_e32 v35, 0xffff0000, v33
	v_lshlrev_b32_e32 v34, 16, v33
	v_and_b32_e32 v33, 0xffff0000, v32
	v_lshlrev_b32_e32 v32, 16, v32
	v_and_b32_e32 v39, 0xffff0000, v37
	v_lshlrev_b32_e32 v38, 16, v37
	v_and_b32_e32 v37, 0xffff0000, v36
	v_lshlrev_b32_e32 v36, 16, v36
	v_and_b32_e32 v43, 0xffff0000, v41
	v_lshlrev_b32_e32 v42, 16, v41
	v_and_b32_e32 v41, 0xffff0000, v40
	v_lshlrev_b32_e32 v40, 16, v40
	v_and_b32_e32 v47, 0xffff0000, v45
	v_lshlrev_b32_e32 v46, 16, v45
	v_and_b32_e32 v45, 0xffff0000, v44
	v_lshlrev_b32_e32 v44, 16, v44
	v_and_b32_e32 v51, 0xffff0000, v49
	v_lshlrev_b32_e32 v50, 16, v49
	v_and_b32_e32 v49, 0xffff0000, v48
	v_lshlrev_b32_e32 v48, 16, v48
	v_and_b32_e32 v55, 0xffff0000, v53
	v_lshlrev_b32_e32 v54, 16, v53
	v_and_b32_e32 v53, 0xffff0000, v52
	v_lshlrev_b32_e32 v52, 16, v52
	v_and_b32_e32 v59, 0xffff0000, v57
	v_lshlrev_b32_e32 v58, 16, v57
	v_and_b32_e32 v57, 0xffff0000, v56
	v_lshlrev_b32_e32 v56, 16, v56
	v_and_b32_e32 v63, 0xffff0000, v61
	v_lshlrev_b32_e32 v62, 16, v61
	v_and_b32_e32 v61, 0xffff0000, v60
	v_lshlrev_b32_e32 v60, 16, v60
	v_and_b32_e32 v67, 0xffff0000, v65
	v_lshlrev_b32_e32 v66, 16, v65
	v_and_b32_e32 v65, 0xffff0000, v64
	v_lshlrev_b32_e32 v64, 16, v64
	v_and_b32_e32 v71, 0xffff0000, v69
	v_lshlrev_b32_e32 v70, 16, v69
	v_and_b32_e32 v69, 0xffff0000, v68
	v_lshlrev_b32_e32 v68, 16, v68
	v_and_b32_e32 v75, 0xffff0000, v73
	v_lshlrev_b32_e32 v74, 16, v73
	v_and_b32_e32 v73, 0xffff0000, v72
	v_lshlrev_b32_e32 v72, 16, v72
	v_and_b32_e32 v79, 0xffff0000, v77
	v_lshlrev_b32_e32 v78, 16, v77
	v_and_b32_e32 v77, 0xffff0000, v76
	v_lshlrev_b32_e32 v76, 16, v76
	v_add_f32_e32 v140, v76, v72
	v_add_f32_e32 v141, v77, v73
	v_add_f32_e32 v142, v78, v74
	v_add_f32_e32 v143, v79, v75
	v_add_f32_e32 v140, v140, v68
	v_add_f32_e32 v141, v141, v69
	v_add_f32_e32 v142, v142, v70
	v_add_f32_e32 v143, v143, v71
	v_add_f32_e32 v140, v140, v64
; DI float bflo(unsigned u) { return __uint_as_float(u << 16); }
; DI float bfhi(unsigned u) { return __uint_as_float(u & 0xffff0000u); }
; template <int WIN>
; DI void pool_elem(const Params& p, int row, int c) {
;     ...
;     if (t >= WIN - 1) {
;       cnt = (float)WIN;
;       unsigned w[WIN - 1];
; #pragma unroll
;       for (int j = 1; j < WIN; ++j) w[j - 1] = *(const unsigned*)(P2 + (size_t)(row - j) * 2048 + c);
; #pragma unroll
;       for (int j = 1; j < WIN; ++j) { s0 += bflo(w[j - 1]); s1 += bfhi(w[j - 1]); }
;     ...
;   *(unsigned*)(p.MIX + (size_t)row * 1024 + c) = pack2(s0 / cnt - u0, s1 / cnt - u1);
	v_add_f32_e32 v141, v141, v65
	v_add_f32_e32 v142, v142, v66
	v_add_f32_e32 v143, v143, v67
	v_add_f32_e32 v140, v140, v60
	v_add_f32_e32 v141, v141, v61
	v_add_f32_e32 v142, v142, v62
	v_add_f32_e32 v143, v143, v63
	v_add_f32_e32 v140, v140, v56
	v_add_f32_e32 v141, v141, v57
	v_add_f32_e32 v142, v142, v58
	v_add_f32_e32 v143, v143, v59
	v_add_f32_e32 v140, v140, v52
	v_add_f32_e32 v141, v141, v53
	v_add_f32_e32 v142, v142, v54
	v_add_f32_e32 v143, v143, v55
	v_add_f32_e32 v140, v140, v48
	v_add_f32_e32 v141, v141, v49
	v_add_f32_e32 v142, v142, v50
	v_add_f32_e32 v143, v143, v51
	v_add_f32_e32 v140, v140, v44
	v_add_f32_e32 v141, v141, v45
	v_add_f32_e32 v142, v142, v46
	v_add_f32_e32 v143, v143, v47
	v_add_f32_e32 v140, v140, v40
	v_add_f32_e32 v141, v141, v41
	v_add_f32_e32 v142, v142, v42
	v_add_f32_e32 v143, v143, v43
	v_add_f32_e32 v140, v140, v36
	v_add_f32_e32 v141, v141, v37
	v_add_f32_e32 v142, v142, v38
	v_add_f32_e32 v143, v143, v39
	v_add_f32_e32 v140, v140, v32
	v_add_f32_e32 v141, v141, v33
	v_add_f32_e32 v142, v142, v34
	v_add_f32_e32 v143, v143, v35
	v_add_f32_e32 v140, v140, v28
	v_add_f32_e32 v141, v141, v29
	v_add_f32_e32 v142, v142, v30
	v_add_f32_e32 v143, v143, v31
	v_add_f32_e32 v140, v140, v24
	v_add_f32_e32 v141, v141, v25
	v_add_f32_e32 v142, v142, v26
	v_add_f32_e32 v143, v143, v27
	v_add_f32_e32 v140, v140, v20
	v_add_f32_e32 v141, v141, v21
	v_add_f32_e32 v142, v142, v22
	v_add_f32_e32 v143, v143, v23
	v_add_f32_e32 v140, v140, v16
	v_add_f32_e32 v141, v141, v17
	v_add_f32_e32 v142, v142, v18
	v_add_f32_e32 v143, v143, v19
	v_mul_f32_e32 v140, 0x3d800000, v140
	v_mul_f32_e32 v141, 0x3d800000, v141
	v_mul_f32_e32 v142, 0x3d800000, v142
	v_mul_f32_e32 v143, 0x3d800000, v143
	v_sub_f32_e32 v140, v140, v76
	v_sub_f32_e32 v141, v141, v77
	v_sub_f32_e32 v142, v142, v78
	v_sub_f32_e32 v143, v143, v79
	v_cvt_pk_bf16_f32 v144, v140, v141
	v_cvt_pk_bf16_f32 v145, v142, v143
	global_store_dwordx2 v11, v[144:145], s[24:25]
	s_add_u32 s24, s24, 0x800
	s_addc_u32 s25, s25, 0
	s_waitcnt vmcnt(14)
	v_and_b32_e32 v83, 0xffff0000, v81
	v_lshlrev_b32_e32 v82, 16, v81
	v_and_b32_e32 v81, 0xffff0000, v80
	v_lshlrev_b32_e32 v80, 16, v80
	v_add_f32_e32 v140, v80, v76
	v_add_f32_e32 v141, v81, v77
	v_add_f32_e32 v142, v82, v78
	v_add_f32_e32 v143, v83, v79
	v_add_f32_e32 v140, v140, v72
	v_add_f32_e32 v141, v141, v73
	v_add_f32_e32 v142, v142, v74
	v_add_f32_e32 v143, v143, v75
	v_add_f32_e32 v140, v140, v68
	v_add_f32_e32 v141, v141, v69
	v_add_f32_e32 v142, v142, v70
	v_add_f32_e32 v143, v143, v71
	v_add_f32_e32 v140, v140, v64
	v_add_f32_e32 v141, v141, v65
	v_add_f32_e32 v142, v142, v66
	v_add_f32_e32 v143, v143, v67
	v_add_f32_e32 v140, v140, v60
	v_add_f32_e32 v141, v141, v61
	v_add_f32_e32 v142, v142, v62
	v_add_f32_e32 v143, v143, v63
	v_add_f32_e32 v140, v140, v56
	v_add_f32_e32 v141, v141, v57
	v_add_f32_e32 v142, v142, v58
	v_add_f32_e32 v143, v143, v59
	v_add_f32_e32 v140, v140, v52
	v_add_f32_e32 v141, v141, v53
	v_add_f32_e32 v142, v142, v54
	v_add_f32_e32 v143, v143, v55
	v_add_f32_e32 v140, v140, v48
	v_add_f32_e32 v141, v141, v49
	v_add_f32_e32 v142, v142, v50
	v_add_f32_e32 v143, v143, v51
	v_add_f32_e32 v140, v140, v44
	v_add_f32_e32 v141, v141, v45
	v_add_f32_e32 v142, v142, v46
	v_add_f32_e32 v143, v143, v47
	v_add_f32_e32 v140, v140, v40
	v_add_f32_e32 v141, v141, v41
	v_add_f32_e32 v142, v142, v42
	v_add_f32_e32 v143, v143, v43
	v_add_f32_e32 v140, v140, v36
	v_add_f32_e32 v141, v141, v37
	v_add_f32_e32 v142, v142, v38
	v_add_f32_e32 v143, v143, v39
	v_add_f32_e32 v140, v140, v32
	v_add_f32_e32 v141, v141, v33
	v_add_f32_e32 v142, v142, v34
	v_add_f32_e32 v143, v143, v35
	v_add_f32_e32 v140, v140, v28
	v_add_f32_e32 v141, v141, v29
	v_add_f32_e32 v142, v142, v30
	v_add_f32_e32 v143, v143, v31
	v_add_f32_e32 v140, v140, v24
	v_add_f32_e32 v141, v141, v25
	v_add_f32_e32 v142, v142, v26
	v_add_f32_e32 v143, v143, v27
	v_add_f32_e32 v140, v140, v20
	v_add_f32_e32 v141, v141, v21
	v_add_f32_e32 v142, v142, v22
	v_add_f32_e32 v143, v143, v23
	v_mul_f32_e32 v140, 0x3d800000, v140
	v_mul_f32_e32 v141, 0x3d800000, v141
	v_mul_f32_e32 v142, 0x3d800000, v142
	v_mul_f32_e32 v143, 0x3d800000, v143
	v_sub_f32_e32 v140, v140, v80
	v_sub_f32_e32 v141, v141, v81
	v_sub_f32_e32 v142, v142, v82
	v_sub_f32_e32 v143, v143, v83
	v_cvt_pk_bf16_f32 v144, v140, v141
	v_cvt_pk_bf16_f32 v145, v142, v143
	global_store_dwordx2 v11, v[144:145], s[24:25]
	s_add_u32 s24, s24, 0x800
	s_addc_u32 s25, s25, 0
	s_waitcnt vmcnt(13)
; DI float bflo(unsigned u) { return __uint_as_float(u << 16); }
; DI float bfhi(unsigned u) { return __uint_as_float(u & 0xffff0000u); }
; template <int WIN>
; DI void pool_elem(const Params& p, int row, int c) {
;     ...
;     if (t >= WIN - 1) {
;       cnt = (float)WIN;
;       unsigned w[WIN - 1];
; #pragma unroll
;       for (int j = 1; j < WIN; ++j) w[j - 1] = *(const unsigned*)(P2 + (size_t)(row - j) * 2048 + c);
; #pragma unroll
;       for (int j = 1; j < WIN; ++j) { s0 += bflo(w[j - 1]); s1 += bfhi(w[j - 1]); }
;     ...
;   *(unsigned*)(p.MIX + (size_t)row * 1024 + c) = pack2(s0 / cnt - u0, s1 / cnt - u1);
	v_and_b32_e32 v87, 0xffff0000, v85
	v_lshlrev_b32_e32 v86, 16, v85
	v_and_b32_e32 v85, 0xffff0000, v84
	v_lshlrev_b32_e32 v84, 16, v84
	v_add_f32_e32 v140, v84, v80
	v_add_f32_e32 v141, v85, v81
	v_add_f32_e32 v142, v86, v82
	v_add_f32_e32 v143, v87, v83
	v_add_f32_e32 v140, v140, v76
	v_add_f32_e32 v141, v141, v77
	v_add_f32_e32 v142, v142, v78
	v_add_f32_e32 v143, v143, v79
	v_add_f32_e32 v140, v140, v72
	v_add_f32_e32 v141, v141, v73
	v_add_f32_e32 v142, v142, v74
	v_add_f32_e32 v143, v143, v75
	v_add_f32_e32 v140, v140, v68
	v_add_f32_e32 v141, v141, v69
	v_add_f32_e32 v142, v142, v70
	v_add_f32_e32 v143, v143, v71
	v_add_f32_e32 v140, v140, v64
	v_add_f32_e32 v141, v141, v65
	v_add_f32_e32 v142, v142, v66
	v_add_f32_e32 v143, v143, v67
	v_add_f32_e32 v140, v140, v60
	v_add_f32_e32 v141, v141, v61
	v_add_f32_e32 v142, v142, v62
	v_add_f32_e32 v143, v143, v63
	v_add_f32_e32 v140, v140, v56
	v_add_f32_e32 v141, v141, v57
	v_add_f32_e32 v142, v142, v58
	v_add_f32_e32 v143, v143, v59
	v_add_f32_e32 v140, v140, v52
	v_add_f32_e32 v141, v141, v53
	v_add_f32_e32 v142, v142, v54
	v_add_f32_e32 v143, v143, v55
	v_add_f32_e32 v140, v140, v48
	v_add_f32_e32 v141, v141, v49
	v_add_f32_e32 v142, v142, v50
	v_add_f32_e32 v143, v143, v51
	v_add_f32_e32 v140, v140, v44
	v_add_f32_e32 v141, v141, v45
	v_add_f32_e32 v142, v142, v46
	v_add_f32_e32 v143, v143, v47
	v_add_f32_e32 v140, v140, v40
	v_add_f32_e32 v141, v141, v41
	v_add_f32_e32 v142, v142, v42
	v_add_f32_e32 v143, v143, v43
	v_add_f32_e32 v140, v140, v36
	v_add_f32_e32 v141, v141, v37
	v_add_f32_e32 v142, v142, v38
	v_add_f32_e32 v143, v143, v39
	v_add_f32_e32 v140, v140, v32
	v_add_f32_e32 v141, v141, v33
	v_add_f32_e32 v142, v142, v34
	v_add_f32_e32 v143, v143, v35
	v_add_f32_e32 v140, v140, v28
	v_add_f32_e32 v141, v141, v29
	v_add_f32_e32 v142, v142, v30
	v_add_f32_e32 v143, v143, v31
	v_add_f32_e32 v140, v140, v24
	v_add_f32_e32 v141, v141, v25
	v_add_f32_e32 v142, v142, v26
	v_add_f32_e32 v143, v143, v27
	v_mul_f32_e32 v140, 0x3d800000, v140
	v_mul_f32_e32 v141, 0x3d800000, v141
	v_mul_f32_e32 v142, 0x3d800000, v142
	v_mul_f32_e32 v143, 0x3d800000, v143
	v_sub_f32_e32 v140, v140, v84
	v_sub_f32_e32 v141, v141, v85
	v_sub_f32_e32 v142, v142, v86
	v_sub_f32_e32 v143, v143, v87
	v_cvt_pk_bf16_f32 v144, v140, v141
	v_cvt_pk_bf16_f32 v145, v142, v143
	global_store_dwordx2 v11, v[144:145], s[24:25]
	s_add_u32 s24, s24, 0x800
	s_addc_u32 s25, s25, 0
	s_waitcnt vmcnt(12)
	v_and_b32_e32 v91, 0xffff0000, v89
	v_lshlrev_b32_e32 v90, 16, v89
	v_and_b32_e32 v89, 0xffff0000, v88
	v_lshlrev_b32_e32 v88, 16, v88
	v_add_f32_e32 v140, v88, v84
	v_add_f32_e32 v141, v89, v85
	v_add_f32_e32 v142, v90, v86
	v_add_f32_e32 v143, v91, v87
	v_add_f32_e32 v140, v140, v80
	v_add_f32_e32 v141, v141, v81
	v_add_f32_e32 v142, v142, v82
	v_add_f32_e32 v143, v143, v83
	v_add_f32_e32 v140, v140, v76
	v_add_f32_e32 v141, v141, v77
	v_add_f32_e32 v142, v142, v78
	v_add_f32_e32 v143, v143, v79
	v_add_f32_e32 v140, v140, v72
	v_add_f32_e32 v141, v141, v73
	v_add_f32_e32 v142, v142, v74
	v_add_f32_e32 v143, v143, v75
	v_add_f32_e32 v140, v140, v68
	v_add_f32_e32 v141, v141, v69
	v_add_f32_e32 v142, v142, v70
	v_add_f32_e32 v143, v143, v71
	v_add_f32_e32 v140, v140, v64
	v_add_f32_e32 v141, v141, v65
	v_add_f32_e32 v142, v142, v66
	v_add_f32_e32 v143, v143, v67
	v_add_f32_e32 v140, v140, v60
	v_add_f32_e32 v141, v141, v61
	v_add_f32_e32 v142, v142, v62
	v_add_f32_e32 v143, v143, v63
	v_add_f32_e32 v140, v140, v56
	v_add_f32_e32 v141, v141, v57
	v_add_f32_e32 v142, v142, v58
	v_add_f32_e32 v143, v143, v59
	v_add_f32_e32 v140, v140, v52
	v_add_f32_e32 v141, v141, v53
	v_add_f32_e32 v142, v142, v54
	v_add_f32_e32 v143, v143, v55
	v_add_f32_e32 v140, v140, v48
	v_add_f32_e32 v141, v141, v49
	v_add_f32_e32 v142, v142, v50
	v_add_f32_e32 v143, v143, v51
	v_add_f32_e32 v140, v140, v44
	v_add_f32_e32 v141, v141, v45
	v_add_f32_e32 v142, v142, v46
	v_add_f32_e32 v143, v143, v47
	v_add_f32_e32 v140, v140, v40
	v_add_f32_e32 v141, v141, v41
	v_add_f32_e32 v142, v142, v42
	v_add_f32_e32 v143, v143, v43
	v_add_f32_e32 v140, v140, v36
	v_add_f32_e32 v141, v141, v37
	v_add_f32_e32 v142, v142, v38
	v_add_f32_e32 v143, v143, v39
	v_add_f32_e32 v140, v140, v32
	v_add_f32_e32 v141, v141, v33
	v_add_f32_e32 v142, v142, v34
	v_add_f32_e32 v143, v143, v35
	v_add_f32_e32 v140, v140, v28
	v_add_f32_e32 v141, v141, v29
	v_add_f32_e32 v142, v142, v30
	v_add_f32_e32 v143, v143, v31
	v_mul_f32_e32 v140, 0x3d800000, v140
	v_mul_f32_e32 v141, 0x3d800000, v141
	v_mul_f32_e32 v142, 0x3d800000, v142
	v_mul_f32_e32 v143, 0x3d800000, v143
	v_sub_f32_e32 v140, v140, v88
	v_sub_f32_e32 v141, v141, v89
	v_sub_f32_e32 v142, v142, v90
	v_sub_f32_e32 v143, v143, v91
	v_cvt_pk_bf16_f32 v144, v140, v141
	v_cvt_pk_bf16_f32 v145, v142, v143
	global_store_dwordx2 v11, v[144:145], s[24:25]
	s_add_u32 s24, s24, 0x800
	s_addc_u32 s25, s25, 0
	s_waitcnt vmcnt(11)
; DI float bflo(unsigned u) { return __uint_as_float(u << 16); }
; DI float bfhi(unsigned u) { return __uint_as_float(u & 0xffff0000u); }
; template <int WIN>
; DI void pool_elem(const Params& p, int row, int c) {
;     ...
;     if (t >= WIN - 1) {
;       cnt = (float)WIN;
;       unsigned w[WIN - 1];
; #pragma unroll
;       for (int j = 1; j < WIN; ++j) w[j - 1] = *(const unsigned*)(P2 + (size_t)(row - j) * 2048 + c);
; #pragma unroll
;       for (int j = 1; j < WIN; ++j) { s0 += bflo(w[j - 1]); s1 += bfhi(w[j - 1]); }
;     ...
;   *(unsigned*)(p.MIX + (size_t)row * 1024 + c) = pack2(s0 / cnt - u0, s1 / cnt - u1);
	v_and_b32_e32 v95, 0xffff0000, v93
	v_lshlrev_b32_e32 v94, 16, v93
	v_and_b32_e32 v93, 0xffff0000, v92
	v_lshlrev_b32_e32 v92, 16, v92
	v_add_f32_e32 v140, v92, v88
	v_add_f32_e32 v141, v93, v89
	v_add_f32_e32 v142, v94, v90
	v_add_f32_e32 v143, v95, v91
	v_add_f32_e32 v140, v140, v84
	v_add_f32_e32 v141, v141, v85
	v_add_f32_e32 v142, v142, v86
	v_add_f32_e32 v143, v143, v87
	v_add_f32_e32 v140, v140, v80
	v_add_f32_e32 v141, v141, v81
	v_add_f32_e32 v142, v142, v82
	v_add_f32_e32 v143, v143, v83
	v_add_f32_e32 v140, v140, v76
	v_add_f32_e32 v141, v141, v77
	v_add_f32_e32 v142, v142, v78
	v_add_f32_e32 v143, v143, v79
	v_add_f32_e32 v140, v140, v72
	v_add_f32_e32 v141, v141, v73
	v_add_f32_e32 v142, v142, v74
	v_add_f32_e32 v143, v143, v75
	v_add_f32_e32 v140, v140, v68
	v_add_f32_e32 v141, v141, v69
	v_add_f32_e32 v142, v142, v70
	v_add_f32_e32 v143, v143, v71
	v_add_f32_e32 v140, v140, v64
	v_add_f32_e32 v141, v141, v65
	v_add_f32_e32 v142, v142, v66
	v_add_f32_e32 v143, v143, v67
	v_add_f32_e32 v140, v140, v60
	v_add_f32_e32 v141, v141, v61
	v_add_f32_e32 v142, v142, v62
	v_add_f32_e32 v143, v143, v63
	v_add_f32_e32 v140, v140, v56
	v_add_f32_e32 v141, v141, v57
	v_add_f32_e32 v142, v142, v58
	v_add_f32_e32 v143, v143, v59
	v_add_f32_e32 v140, v140, v52
	v_add_f32_e32 v141, v141, v53
	v_add_f32_e32 v142, v142, v54
	v_add_f32_e32 v143, v143, v55
	v_add_f32_e32 v140, v140, v48
	v_add_f32_e32 v141, v141, v49
	v_add_f32_e32 v142, v142, v50
	v_add_f32_e32 v143, v143, v51
	v_add_f32_e32 v140, v140, v44
	v_add_f32_e32 v141, v141, v45
	v_add_f32_e32 v142, v142, v46
	v_add_f32_e32 v143, v143, v47
	v_add_f32_e32 v140, v140, v40
	v_add_f32_e32 v141, v141, v41
	v_add_f32_e32 v142, v142, v42
	v_add_f32_e32 v143, v143, v43
	v_add_f32_e32 v140, v140, v36
	v_add_f32_e32 v141, v141, v37
	v_add_f32_e32 v142, v142, v38
	v_add_f32_e32 v143, v143, v39
	v_add_f32_e32 v140, v140, v32
	v_add_f32_e32 v141, v141, v33
	v_add_f32_e32 v142, v142, v34
	v_add_f32_e32 v143, v143, v35
	v_mul_f32_e32 v140, 0x3d800000, v140
	v_mul_f32_e32 v141, 0x3d800000, v141
	v_mul_f32_e32 v142, 0x3d800000, v142
	v_mul_f32_e32 v143, 0x3d800000, v143
	v_sub_f32_e32 v140, v140, v92
	v_sub_f32_e32 v141, v141, v93
	v_sub_f32_e32 v142, v142, v94
	v_sub_f32_e32 v143, v143, v95
	v_cvt_pk_bf16_f32 v144, v140, v141
	v_cvt_pk_bf16_f32 v145, v142, v143
	global_store_dwordx2 v11, v[144:145], s[24:25]
	s_add_u32 s24, s24, 0x800
	s_addc_u32 s25, s25, 0
	s_waitcnt vmcnt(10)
	v_and_b32_e32 v99, 0xffff0000, v97
	v_lshlrev_b32_e32 v98, 16, v97
	v_and_b32_e32 v97, 0xffff0000, v96
	v_lshlrev_b32_e32 v96, 16, v96
	v_add_f32_e32 v140, v96, v92
	v_add_f32_e32 v141, v97, v93
	v_add_f32_e32 v142, v98, v94
	v_add_f32_e32 v143, v99, v95
	v_add_f32_e32 v140, v140, v88
	v_add_f32_e32 v141, v141, v89
	v_add_f32_e32 v142, v142, v90
	v_add_f32_e32 v143, v143, v91
	v_add_f32_e32 v140, v140, v84
	v_add_f32_e32 v141, v141, v85
	v_add_f32_e32 v142, v142, v86
	v_add_f32_e32 v143, v143, v87
	v_add_f32_e32 v140, v140, v80
	v_add_f32_e32 v141, v141, v81
	v_add_f32_e32 v142, v142, v82
	v_add_f32_e32 v143, v143, v83
	v_add_f32_e32 v140, v140, v76
	v_add_f32_e32 v141, v141, v77
	v_add_f32_e32 v142, v142, v78
	v_add_f32_e32 v143, v143, v79
	v_add_f32_e32 v140, v140, v72
	v_add_f32_e32 v141, v141, v73
	v_add_f32_e32 v142, v142, v74
	v_add_f32_e32 v143, v143, v75
	v_add_f32_e32 v140, v140, v68
	v_add_f32_e32 v141, v141, v69
	v_add_f32_e32 v142, v142, v70
	v_add_f32_e32 v143, v143, v71
	v_add_f32_e32 v140, v140, v64
	v_add_f32_e32 v141, v141, v65
	v_add_f32_e32 v142, v142, v66
	v_add_f32_e32 v143, v143, v67
	v_add_f32_e32 v140, v140, v60
	v_add_f32_e32 v141, v141, v61
	v_add_f32_e32 v142, v142, v62
	v_add_f32_e32 v143, v143, v63
	v_add_f32_e32 v140, v140, v56
	v_add_f32_e32 v141, v141, v57
	v_add_f32_e32 v142, v142, v58
	v_add_f32_e32 v143, v143, v59
	v_add_f32_e32 v140, v140, v52
	v_add_f32_e32 v141, v141, v53
	v_add_f32_e32 v142, v142, v54
	v_add_f32_e32 v143, v143, v55
	v_add_f32_e32 v140, v140, v48
	v_add_f32_e32 v141, v141, v49
	v_add_f32_e32 v142, v142, v50
	v_add_f32_e32 v143, v143, v51
	v_add_f32_e32 v140, v140, v44
	v_add_f32_e32 v141, v141, v45
	v_add_f32_e32 v142, v142, v46
	v_add_f32_e32 v143, v143, v47
	v_add_f32_e32 v140, v140, v40
	v_add_f32_e32 v141, v141, v41
	v_add_f32_e32 v142, v142, v42
	v_add_f32_e32 v143, v143, v43
	v_add_f32_e32 v140, v140, v36
	v_add_f32_e32 v141, v141, v37
	v_add_f32_e32 v142, v142, v38
	v_add_f32_e32 v143, v143, v39
	v_mul_f32_e32 v140, 0x3d800000, v140
	v_mul_f32_e32 v141, 0x3d800000, v141
	v_mul_f32_e32 v142, 0x3d800000, v142
	v_mul_f32_e32 v143, 0x3d800000, v143
	v_sub_f32_e32 v140, v140, v96
	v_sub_f32_e32 v141, v141, v97
	v_sub_f32_e32 v142, v142, v98
	v_sub_f32_e32 v143, v143, v99
	v_cvt_pk_bf16_f32 v144, v140, v141
	v_cvt_pk_bf16_f32 v145, v142, v143
	global_store_dwordx2 v11, v[144:145], s[24:25]
	s_add_u32 s24, s24, 0x800
	s_addc_u32 s25, s25, 0
	s_waitcnt vmcnt(9)
; DI float bflo(unsigned u) { return __uint_as_float(u << 16); }
; DI float bfhi(unsigned u) { return __uint_as_float(u & 0xffff0000u); }
; template <int WIN>
; DI void pool_elem(const Params& p, int row, int c) {
;     ...
;     if (t >= WIN - 1) {
;       cnt = (float)WIN;
;       unsigned w[WIN - 1];
; #pragma unroll
;       for (int j = 1; j < WIN; ++j) w[j - 1] = *(const unsigned*)(P2 + (size_t)(row - j) * 2048 + c);
; #pragma unroll
;       for (int j = 1; j < WIN; ++j) { s0 += bflo(w[j - 1]); s1 += bfhi(w[j - 1]); }
;     ...
;   *(unsigned*)(p.MIX + (size_t)row * 1024 + c) = pack2(s0 / cnt - u0, s1 / cnt - u1);
	v_and_b32_e32 v103, 0xffff0000, v101
	v_lshlrev_b32_e32 v102, 16, v101
	v_and_b32_e32 v101, 0xffff0000, v100
	v_lshlrev_b32_e32 v100, 16, v100
	v_add_f32_e32 v140, v100, v96
	v_add_f32_e32 v141, v101, v97
	v_add_f32_e32 v142, v102, v98
	v_add_f32_e32 v143, v103, v99
	v_add_f32_e32 v140, v140, v92
	v_add_f32_e32 v141, v141, v93
	v_add_f32_e32 v142, v142, v94
	v_add_f32_e32 v143, v143, v95
	v_add_f32_e32 v140, v140, v88
	v_add_f32_e32 v141, v141, v89
	v_add_f32_e32 v142, v142, v90
	v_add_f32_e32 v143, v143, v91
	v_add_f32_e32 v140, v140, v84
	v_add_f32_e32 v141, v141, v85
	v_add_f32_e32 v142, v142, v86
	v_add_f32_e32 v143, v143, v87
	v_add_f32_e32 v140, v140, v80
	v_add_f32_e32 v141, v141, v81
	v_add_f32_e32 v142, v142, v82
	v_add_f32_e32 v143, v143, v83
	v_add_f32_e32 v140, v140, v76
	v_add_f32_e32 v141, v141, v77
	v_add_f32_e32 v142, v142, v78
	v_add_f32_e32 v143, v143, v79
	v_add_f32_e32 v140, v140, v72
	v_add_f32_e32 v141, v141, v73
	v_add_f32_e32 v142, v142, v74
	v_add_f32_e32 v143, v143, v75
	v_add_f32_e32 v140, v140, v68
	v_add_f32_e32 v141, v141, v69
	v_add_f32_e32 v142, v142, v70
	v_add_f32_e32 v143, v143, v71
	v_add_f32_e32 v140, v140, v64
	v_add_f32_e32 v141, v141, v65
	v_add_f32_e32 v142, v142, v66
	v_add_f32_e32 v143, v143, v67
	v_add_f32_e32 v140, v140, v60
	v_add_f32_e32 v141, v141, v61
	v_add_f32_e32 v142, v142, v62
	v_add_f32_e32 v143, v143, v63
	v_add_f32_e32 v140, v140, v56
	v_add_f32_e32 v141, v141, v57
	v_add_f32_e32 v142, v142, v58
	v_add_f32_e32 v143, v143, v59
	v_add_f32_e32 v140, v140, v52
	v_add_f32_e32 v141, v141, v53
	v_add_f32_e32 v142, v142, v54
	v_add_f32_e32 v143, v143, v55
	v_add_f32_e32 v140, v140, v48
	v_add_f32_e32 v141, v141, v49
	v_add_f32_e32 v142, v142, v50
	v_add_f32_e32 v143, v143, v51
	v_add_f32_e32 v140, v140, v44
	v_add_f32_e32 v141, v141, v45
	v_add_f32_e32 v142, v142, v46
	v_add_f32_e32 v143, v143, v47
	v_add_f32_e32 v140, v140, v40
	v_add_f32_e32 v141, v141, v41
	v_add_f32_e32 v142, v142, v42
	v_add_f32_e32 v143, v143, v43
	v_mul_f32_e32 v140, 0x3d800000, v140
	v_mul_f32_e32 v141, 0x3d800000, v141
	v_mul_f32_e32 v142, 0x3d800000, v142
	v_mul_f32_e32 v143, 0x3d800000, v143
	v_sub_f32_e32 v140, v140, v100
	v_sub_f32_e32 v141, v141, v101
	v_sub_f32_e32 v142, v142, v102
	v_sub_f32_e32 v143, v143, v103
	v_cvt_pk_bf16_f32 v144, v140, v141
	v_cvt_pk_bf16_f32 v145, v142, v143
	global_store_dwordx2 v11, v[144:145], s[24:25]
	s_add_u32 s24, s24, 0x800
	s_addc_u32 s25, s25, 0
	s_waitcnt vmcnt(8)
	v_and_b32_e32 v107, 0xffff0000, v105
	v_lshlrev_b32_e32 v106, 16, v105
	v_and_b32_e32 v105, 0xffff0000, v104
	v_lshlrev_b32_e32 v104, 16, v104
	v_add_f32_e32 v140, v104, v100
	v_add_f32_e32 v141, v105, v101
	v_add_f32_e32 v142, v106, v102
	v_add_f32_e32 v143, v107, v103
	v_add_f32_e32 v140, v140, v96
	v_add_f32_e32 v141, v141, v97
	v_add_f32_e32 v142, v142, v98
	v_add_f32_e32 v143, v143, v99
	v_add_f32_e32 v140, v140, v92
	v_add_f32_e32 v141, v141, v93
	v_add_f32_e32 v142, v142, v94
	v_add_f32_e32 v143, v143, v95
	v_add_f32_e32 v140, v140, v88
	v_add_f32_e32 v141, v141, v89
	v_add_f32_e32 v142, v142, v90
	v_add_f32_e32 v143, v143, v91
	v_add_f32_e32 v140, v140, v84
	v_add_f32_e32 v141, v141, v85
	v_add_f32_e32 v142, v142, v86
	v_add_f32_e32 v143, v143, v87
	v_add_f32_e32 v140, v140, v80
	v_add_f32_e32 v141, v141, v81
	v_add_f32_e32 v142, v142, v82
	v_add_f32_e32 v143, v143, v83
	v_add_f32_e32 v140, v140, v76
	v_add_f32_e32 v141, v141, v77
	v_add_f32_e32 v142, v142, v78
	v_add_f32_e32 v143, v143, v79
	v_add_f32_e32 v140, v140, v72
	v_add_f32_e32 v141, v141, v73
	v_add_f32_e32 v142, v142, v74
	v_add_f32_e32 v143, v143, v75
	v_add_f32_e32 v140, v140, v68
	v_add_f32_e32 v141, v141, v69
	v_add_f32_e32 v142, v142, v70
	v_add_f32_e32 v143, v143, v71
	v_add_f32_e32 v140, v140, v64
	v_add_f32_e32 v141, v141, v65
	v_add_f32_e32 v142, v142, v66
	v_add_f32_e32 v143, v143, v67
	v_add_f32_e32 v140, v140, v60
	v_add_f32_e32 v141, v141, v61
	v_add_f32_e32 v142, v142, v62
	v_add_f32_e32 v143, v143, v63
	v_add_f32_e32 v140, v140, v56
	v_add_f32_e32 v141, v141, v57
	v_add_f32_e32 v142, v142, v58
	v_add_f32_e32 v143, v143, v59
	v_add_f32_e32 v140, v140, v52
	v_add_f32_e32 v141, v141, v53
	v_add_f32_e32 v142, v142, v54
	v_add_f32_e32 v143, v143, v55
	v_add_f32_e32 v140, v140, v48
	v_add_f32_e32 v141, v141, v49
	v_add_f32_e32 v142, v142, v50
	v_add_f32_e32 v143, v143, v51
	v_add_f32_e32 v140, v140, v44
	v_add_f32_e32 v141, v141, v45
	v_add_f32_e32 v142, v142, v46
	v_add_f32_e32 v143, v143, v47
	v_mul_f32_e32 v140, 0x3d800000, v140
	v_mul_f32_e32 v141, 0x3d800000, v141
	v_mul_f32_e32 v142, 0x3d800000, v142
	v_mul_f32_e32 v143, 0x3d800000, v143
	v_sub_f32_e32 v140, v140, v104
	v_sub_f32_e32 v141, v141, v105
	v_sub_f32_e32 v142, v142, v106
	v_sub_f32_e32 v143, v143, v107
	v_cvt_pk_bf16_f32 v144, v140, v141
	v_cvt_pk_bf16_f32 v145, v142, v143
	global_store_dwordx2 v11, v[144:145], s[24:25]
	s_add_u32 s24, s24, 0x800
	s_addc_u32 s25, s25, 0
	s_waitcnt vmcnt(7)
; DI float bflo(unsigned u) { return __uint_as_float(u << 16); }
; DI float bfhi(unsigned u) { return __uint_as_float(u & 0xffff0000u); }
; template <int WIN>
; DI void pool_elem(const Params& p, int row, int c) {
;     ...
;     if (t >= WIN - 1) {
;       cnt = (float)WIN;
;       unsigned w[WIN - 1];
; #pragma unroll
;       for (int j = 1; j < WIN; ++j) w[j - 1] = *(const unsigned*)(P2 + (size_t)(row - j) * 2048 + c);
; #pragma unroll
;       for (int j = 1; j < WIN; ++j) { s0 += bflo(w[j - 1]); s1 += bfhi(w[j - 1]); }
;     ...
;   *(unsigned*)(p.MIX + (size_t)row * 1024 + c) = pack2(s0 / cnt - u0, s1 / cnt - u1);
	v_and_b32_e32 v111, 0xffff0000, v109
	v_lshlrev_b32_e32 v110, 16, v109
	v_and_b32_e32 v109, 0xffff0000, v108
	v_lshlrev_b32_e32 v108, 16, v108
	v_add_f32_e32 v140, v108, v104
	v_add_f32_e32 v141, v109, v105
	v_add_f32_e32 v142, v110, v106
	v_add_f32_e32 v143, v111, v107
	v_add_f32_e32 v140, v140, v100
	v_add_f32_e32 v141, v141, v101
	v_add_f32_e32 v142, v142, v102
	v_add_f32_e32 v143, v143, v103
	v_add_f32_e32 v140, v140, v96
	v_add_f32_e32 v141, v141, v97
	v_add_f32_e32 v142, v142, v98
	v_add_f32_e32 v143, v143, v99
	v_add_f32_e32 v140, v140, v92
	v_add_f32_e32 v141, v141, v93
	v_add_f32_e32 v142, v142, v94
	v_add_f32_e32 v143, v143, v95
	v_add_f32_e32 v140, v140, v88
	v_add_f32_e32 v141, v141, v89
	v_add_f32_e32 v142, v142, v90
	v_add_f32_e32 v143, v143, v91
	v_add_f32_e32 v140, v140, v84
	v_add_f32_e32 v141, v141, v85
	v_add_f32_e32 v142, v142, v86
	v_add_f32_e32 v143, v143, v87
	v_add_f32_e32 v140, v140, v80
	v_add_f32_e32 v141, v141, v81
	v_add_f32_e32 v142, v142, v82
	v_add_f32_e32 v143, v143, v83
	v_add_f32_e32 v140, v140, v76
	v_add_f32_e32 v141, v141, v77
	v_add_f32_e32 v142, v142, v78
	v_add_f32_e32 v143, v143, v79
	v_add_f32_e32 v140, v140, v72
	v_add_f32_e32 v141, v141, v73
	v_add_f32_e32 v142, v142, v74
	v_add_f32_e32 v143, v143, v75
	v_add_f32_e32 v140, v140, v68
	v_add_f32_e32 v141, v141, v69
	v_add_f32_e32 v142, v142, v70
	v_add_f32_e32 v143, v143, v71
	v_add_f32_e32 v140, v140, v64
	v_add_f32_e32 v141, v141, v65
	v_add_f32_e32 v142, v142, v66
	v_add_f32_e32 v143, v143, v67
	v_add_f32_e32 v140, v140, v60
	v_add_f32_e32 v141, v141, v61
	v_add_f32_e32 v142, v142, v62
	v_add_f32_e32 v143, v143, v63
	v_add_f32_e32 v140, v140, v56
	v_add_f32_e32 v141, v141, v57
	v_add_f32_e32 v142, v142, v58
	v_add_f32_e32 v143, v143, v59
	v_add_f32_e32 v140, v140, v52
	v_add_f32_e32 v141, v141, v53
	v_add_f32_e32 v142, v142, v54
	v_add_f32_e32 v143, v143, v55
	v_add_f32_e32 v140, v140, v48
	v_add_f32_e32 v141, v141, v49
	v_add_f32_e32 v142, v142, v50
	v_add_f32_e32 v143, v143, v51
	v_mul_f32_e32 v140, 0x3d800000, v140
	v_mul_f32_e32 v141, 0x3d800000, v141
	v_mul_f32_e32 v142, 0x3d800000, v142
	v_mul_f32_e32 v143, 0x3d800000, v143
	v_sub_f32_e32 v140, v140, v108
	v_sub_f32_e32 v141, v141, v109
	v_sub_f32_e32 v142, v142, v110
	v_sub_f32_e32 v143, v143, v111
	v_cvt_pk_bf16_f32 v144, v140, v141
	v_cvt_pk_bf16_f32 v145, v142, v143
	global_store_dwordx2 v11, v[144:145], s[24:25]
	s_add_u32 s24, s24, 0x800
	s_addc_u32 s25, s25, 0
	s_waitcnt vmcnt(6)
	v_and_b32_e32 v115, 0xffff0000, v113
	v_lshlrev_b32_e32 v114, 16, v113
	v_and_b32_e32 v113, 0xffff0000, v112
	v_lshlrev_b32_e32 v112, 16, v112
	v_add_f32_e32 v140, v112, v108
	v_add_f32_e32 v141, v113, v109
	v_add_f32_e32 v142, v114, v110
	v_add_f32_e32 v143, v115, v111
	v_add_f32_e32 v140, v140, v104
	v_add_f32_e32 v141, v141, v105
	v_add_f32_e32 v142, v142, v106
	v_add_f32_e32 v143, v143, v107
	v_add_f32_e32 v140, v140, v100
	v_add_f32_e32 v141, v141, v101
	v_add_f32_e32 v142, v142, v102
	v_add_f32_e32 v143, v143, v103
	v_add_f32_e32 v140, v140, v96
	v_add_f32_e32 v141, v141, v97
	v_add_f32_e32 v142, v142, v98
	v_add_f32_e32 v143, v143, v99
	v_add_f32_e32 v140, v140, v92
	v_add_f32_e32 v141, v141, v93
	v_add_f32_e32 v142, v142, v94
	v_add_f32_e32 v143, v143, v95
	v_add_f32_e32 v140, v140, v88
	v_add_f32_e32 v141, v141, v89
	v_add_f32_e32 v142, v142, v90
	v_add_f32_e32 v143, v143, v91
	v_add_f32_e32 v140, v140, v84
	v_add_f32_e32 v141, v141, v85
	v_add_f32_e32 v142, v142, v86
	v_add_f32_e32 v143, v143, v87
	v_add_f32_e32 v140, v140, v80
	v_add_f32_e32 v141, v141, v81
	v_add_f32_e32 v142, v142, v82
	v_add_f32_e32 v143, v143, v83
	v_add_f32_e32 v140, v140, v76
	v_add_f32_e32 v141, v141, v77
	v_add_f32_e32 v142, v142, v78
	v_add_f32_e32 v143, v143, v79
	v_add_f32_e32 v140, v140, v72
	v_add_f32_e32 v141, v141, v73
	v_add_f32_e32 v142, v142, v74
	v_add_f32_e32 v143, v143, v75
	v_add_f32_e32 v140, v140, v68
	v_add_f32_e32 v141, v141, v69
	v_add_f32_e32 v142, v142, v70
	v_add_f32_e32 v143, v143, v71
	v_add_f32_e32 v140, v140, v64
	v_add_f32_e32 v141, v141, v65
	v_add_f32_e32 v142, v142, v66
	v_add_f32_e32 v143, v143, v67
	v_add_f32_e32 v140, v140, v60
	v_add_f32_e32 v141, v141, v61
	v_add_f32_e32 v142, v142, v62
	v_add_f32_e32 v143, v143, v63
	v_add_f32_e32 v140, v140, v56
	v_add_f32_e32 v141, v141, v57
	v_add_f32_e32 v142, v142, v58
	v_add_f32_e32 v143, v143, v59
	v_add_f32_e32 v140, v140, v52
	v_add_f32_e32 v141, v141, v53
	v_add_f32_e32 v142, v142, v54
	v_add_f32_e32 v143, v143, v55
	v_mul_f32_e32 v140, 0x3d800000, v140
	v_mul_f32_e32 v141, 0x3d800000, v141
	v_mul_f32_e32 v142, 0x3d800000, v142
	v_mul_f32_e32 v143, 0x3d800000, v143
	v_sub_f32_e32 v140, v140, v112
	v_sub_f32_e32 v141, v141, v113
	v_sub_f32_e32 v142, v142, v114
	v_sub_f32_e32 v143, v143, v115
	v_cvt_pk_bf16_f32 v144, v140, v141
	v_cvt_pk_bf16_f32 v145, v142, v143
	global_store_dwordx2 v11, v[144:145], s[24:25]
	s_add_u32 s24, s24, 0x800
	s_addc_u32 s25, s25, 0
	s_waitcnt vmcnt(5)
; DI float bflo(unsigned u) { return __uint_as_float(u << 16); }
; DI float bfhi(unsigned u) { return __uint_as_float(u & 0xffff0000u); }
; template <int WIN>
; DI void pool_elem(const Params& p, int row, int c) {
;     ...
;     if (t >= WIN - 1) {
;       cnt = (float)WIN;
;       unsigned w[WIN - 1];
; #pragma unroll
;       for (int j = 1; j < WIN; ++j) w[j - 1] = *(const unsigned*)(P2 + (size_t)(row - j) * 2048 + c);
; #pragma unroll
;       for (int j = 1; j < WIN; ++j) { s0 += bflo(w[j - 1]); s1 += bfhi(w[j - 1]); }
;     ...
;   *(unsigned*)(p.MIX + (size_t)row * 1024 + c) = pack2(s0 / cnt - u0, s1 / cnt - u1);
	v_and_b32_e32 v119, 0xffff0000, v117
	v_lshlrev_b32_e32 v118, 16, v117
	v_and_b32_e32 v117, 0xffff0000, v116
	v_lshlrev_b32_e32 v116, 16, v116
	v_add_f32_e32 v140, v116, v112
	v_add_f32_e32 v141, v117, v113
	v_add_f32_e32 v142, v118, v114
	v_add_f32_e32 v143, v119, v115
	v_add_f32_e32 v140, v140, v108
	v_add_f32_e32 v141, v141, v109
	v_add_f32_e32 v142, v142, v110
	v_add_f32_e32 v143, v143, v111
	v_add_f32_e32 v140, v140, v104
	v_add_f32_e32 v141, v141, v105
	v_add_f32_e32 v142, v142, v106
	v_add_f32_e32 v143, v143, v107
	v_add_f32_e32 v140, v140, v100
	v_add_f32_e32 v141, v141, v101
	v_add_f32_e32 v142, v142, v102
	v_add_f32_e32 v143, v143, v103
	v_add_f32_e32 v140, v140, v96
	v_add_f32_e32 v141, v141, v97
	v_add_f32_e32 v142, v142, v98
	v_add_f32_e32 v143, v143, v99
	v_add_f32_e32 v140, v140, v92
	v_add_f32_e32 v141, v141, v93
	v_add_f32_e32 v142, v142, v94
	v_add_f32_e32 v143, v143, v95
	v_add_f32_e32 v140, v140, v88
	v_add_f32_e32 v141, v141, v89
	v_add_f32_e32 v142, v142, v90
	v_add_f32_e32 v143, v143, v91
	v_add_f32_e32 v140, v140, v84
	v_add_f32_e32 v141, v141, v85
	v_add_f32_e32 v142, v142, v86
	v_add_f32_e32 v143, v143, v87
	v_add_f32_e32 v140, v140, v80
	v_add_f32_e32 v141, v141, v81
	v_add_f32_e32 v142, v142, v82
	v_add_f32_e32 v143, v143, v83
	v_add_f32_e32 v140, v140, v76
	v_add_f32_e32 v141, v141, v77
	v_add_f32_e32 v142, v142, v78
	v_add_f32_e32 v143, v143, v79
	v_add_f32_e32 v140, v140, v72
	v_add_f32_e32 v141, v141, v73
	v_add_f32_e32 v142, v142, v74
	v_add_f32_e32 v143, v143, v75
	v_add_f32_e32 v140, v140, v68
	v_add_f32_e32 v141, v141, v69
	v_add_f32_e32 v142, v142, v70
	v_add_f32_e32 v143, v143, v71
	v_add_f32_e32 v140, v140, v64
	v_add_f32_e32 v141, v141, v65
	v_add_f32_e32 v142, v142, v66
	v_add_f32_e32 v143, v143, v67
	v_add_f32_e32 v140, v140, v60
	v_add_f32_e32 v141, v141, v61
	v_add_f32_e32 v142, v142, v62
	v_add_f32_e32 v143, v143, v63
	v_add_f32_e32 v140, v140, v56
	v_add_f32_e32 v141, v141, v57
	v_add_f32_e32 v142, v142, v58
	v_add_f32_e32 v143, v143, v59
	v_mul_f32_e32 v140, 0x3d800000, v140
	v_mul_f32_e32 v141, 0x3d800000, v141
	v_mul_f32_e32 v142, 0x3d800000, v142
	v_mul_f32_e32 v143, 0x3d800000, v143
	v_sub_f32_e32 v140, v140, v116
	v_sub_f32_e32 v141, v141, v117
	v_sub_f32_e32 v142, v142, v118
	v_sub_f32_e32 v143, v143, v119
	v_cvt_pk_bf16_f32 v144, v140, v141
	v_cvt_pk_bf16_f32 v145, v142, v143
	global_store_dwordx2 v11, v[144:145], s[24:25]
	s_add_u32 s24, s24, 0x800
	s_addc_u32 s25, s25, 0
	s_waitcnt vmcnt(4)
	v_and_b32_e32 v123, 0xffff0000, v121
	v_lshlrev_b32_e32 v122, 16, v121
	v_and_b32_e32 v121, 0xffff0000, v120
	v_lshlrev_b32_e32 v120, 16, v120
	v_add_f32_e32 v140, v120, v116
	v_add_f32_e32 v141, v121, v117
	v_add_f32_e32 v142, v122, v118
	v_add_f32_e32 v143, v123, v119
	v_add_f32_e32 v140, v140, v112
	v_add_f32_e32 v141, v141, v113
	v_add_f32_e32 v142, v142, v114
	v_add_f32_e32 v143, v143, v115
	v_add_f32_e32 v140, v140, v108
	v_add_f32_e32 v141, v141, v109
	v_add_f32_e32 v142, v142, v110
	v_add_f32_e32 v143, v143, v111
	v_add_f32_e32 v140, v140, v104
	v_add_f32_e32 v141, v141, v105
	v_add_f32_e32 v142, v142, v106
	v_add_f32_e32 v143, v143, v107
	v_add_f32_e32 v140, v140, v100
	v_add_f32_e32 v141, v141, v101
	v_add_f32_e32 v142, v142, v102
	v_add_f32_e32 v143, v143, v103
	v_add_f32_e32 v140, v140, v96
	v_add_f32_e32 v141, v141, v97
	v_add_f32_e32 v142, v142, v98
	v_add_f32_e32 v143, v143, v99
	v_add_f32_e32 v140, v140, v92
	v_add_f32_e32 v141, v141, v93
	v_add_f32_e32 v142, v142, v94
	v_add_f32_e32 v143, v143, v95
	v_add_f32_e32 v140, v140, v88
	v_add_f32_e32 v141, v141, v89
	v_add_f32_e32 v142, v142, v90
	v_add_f32_e32 v143, v143, v91
	v_add_f32_e32 v140, v140, v84
	v_add_f32_e32 v141, v141, v85
	v_add_f32_e32 v142, v142, v86
	v_add_f32_e32 v143, v143, v87
	v_add_f32_e32 v140, v140, v80
	v_add_f32_e32 v141, v141, v81
	v_add_f32_e32 v142, v142, v82
	v_add_f32_e32 v143, v143, v83
	v_add_f32_e32 v140, v140, v76
	v_add_f32_e32 v141, v141, v77
	v_add_f32_e32 v142, v142, v78
	v_add_f32_e32 v143, v143, v79
	v_add_f32_e32 v140, v140, v72
	v_add_f32_e32 v141, v141, v73
	v_add_f32_e32 v142, v142, v74
	v_add_f32_e32 v143, v143, v75
	v_add_f32_e32 v140, v140, v68
	v_add_f32_e32 v141, v141, v69
	v_add_f32_e32 v142, v142, v70
	v_add_f32_e32 v143, v143, v71
	v_add_f32_e32 v140, v140, v64
	v_add_f32_e32 v141, v141, v65
	v_add_f32_e32 v142, v142, v66
	v_add_f32_e32 v143, v143, v67
	v_add_f32_e32 v140, v140, v60
	v_add_f32_e32 v141, v141, v61
	v_add_f32_e32 v142, v142, v62
	v_add_f32_e32 v143, v143, v63
	v_mul_f32_e32 v140, 0x3d800000, v140
	v_mul_f32_e32 v141, 0x3d800000, v141
	v_mul_f32_e32 v142, 0x3d800000, v142
	v_mul_f32_e32 v143, 0x3d800000, v143
	v_sub_f32_e32 v140, v140, v120
	v_sub_f32_e32 v141, v141, v121
	v_sub_f32_e32 v142, v142, v122
	v_sub_f32_e32 v143, v143, v123
	v_cvt_pk_bf16_f32 v144, v140, v141
	v_cvt_pk_bf16_f32 v145, v142, v143
	global_store_dwordx2 v11, v[144:145], s[24:25]
	s_add_u32 s24, s24, 0x800
	s_addc_u32 s25, s25, 0
	s_waitcnt vmcnt(3)
; DI float bflo(unsigned u) { return __uint_as_float(u << 16); }
; DI float bfhi(unsigned u) { return __uint_as_float(u & 0xffff0000u); }
; template <int WIN>
; DI void pool_elem(const Params& p, int row, int c) {
;     ...
;     if (t >= WIN - 1) {
;       cnt = (float)WIN;
;       unsigned w[WIN - 1];
; #pragma unroll
;       for (int j = 1; j < WIN; ++j) w[j - 1] = *(const unsigned*)(P2 + (size_t)(row - j) * 2048 + c);
; #pragma unroll
;       for (int j = 1; j < WIN; ++j) { s0 += bflo(w[j - 1]); s1 += bfhi(w[j - 1]); }
;     ...
;   *(unsigned*)(p.MIX + (size_t)row * 1024 + c) = pack2(s0 / cnt - u0, s1 / cnt - u1);
	v_and_b32_e32 v127, 0xffff0000, v125
	v_lshlrev_b32_e32 v126, 16, v125
	v_and_b32_e32 v125, 0xffff0000, v124
	v_lshlrev_b32_e32 v124, 16, v124
	v_add_f32_e32 v140, v124, v120
	v_add_f32_e32 v141, v125, v121
	v_add_f32_e32 v142, v126, v122
	v_add_f32_e32 v143, v127, v123
	v_add_f32_e32 v140, v140, v116
	v_add_f32_e32 v141, v141, v117
	v_add_f32_e32 v142, v142, v118
	v_add_f32_e32 v143, v143, v119
	v_add_f32_e32 v140, v140, v112
	v_add_f32_e32 v141, v141, v113
	v_add_f32_e32 v142, v142, v114
	v_add_f32_e32 v143, v143, v115
	v_add_f32_e32 v140, v140, v108
	v_add_f32_e32 v141, v141, v109
	v_add_f32_e32 v142, v142, v110
	v_add_f32_e32 v143, v143, v111
	v_add_f32_e32 v140, v140, v104
	v_add_f32_e32 v141, v141, v105
	v_add_f32_e32 v142, v142, v106
	v_add_f32_e32 v143, v143, v107
	v_add_f32_e32 v140, v140, v100
	v_add_f32_e32 v141, v141, v101
	v_add_f32_e32 v142, v142, v102
	v_add_f32_e32 v143, v143, v103
	v_add_f32_e32 v140, v140, v96
	v_add_f32_e32 v141, v141, v97
	v_add_f32_e32 v142, v142, v98
	v_add_f32_e32 v143, v143, v99
	v_add_f32_e32 v140, v140, v92
	v_add_f32_e32 v141, v141, v93
	v_add_f32_e32 v142, v142, v94
	v_add_f32_e32 v143, v143, v95
	v_add_f32_e32 v140, v140, v88
	v_add_f32_e32 v141, v141, v89
	v_add_f32_e32 v142, v142, v90
	v_add_f32_e32 v143, v143, v91
	v_add_f32_e32 v140, v140, v84
	v_add_f32_e32 v141, v141, v85
	v_add_f32_e32 v142, v142, v86
	v_add_f32_e32 v143, v143, v87
	v_add_f32_e32 v140, v140, v80
	v_add_f32_e32 v141, v141, v81
	v_add_f32_e32 v142, v142, v82
	v_add_f32_e32 v143, v143, v83
	v_add_f32_e32 v140, v140, v76
	v_add_f32_e32 v141, v141, v77
	v_add_f32_e32 v142, v142, v78
	v_add_f32_e32 v143, v143, v79
	v_add_f32_e32 v140, v140, v72
	v_add_f32_e32 v141, v141, v73
	v_add_f32_e32 v142, v142, v74
	v_add_f32_e32 v143, v143, v75
	v_add_f32_e32 v140, v140, v68
	v_add_f32_e32 v141, v141, v69
	v_add_f32_e32 v142, v142, v70
	v_add_f32_e32 v143, v143, v71
	v_add_f32_e32 v140, v140, v64
	v_add_f32_e32 v141, v141, v65
	v_add_f32_e32 v142, v142, v66
	v_add_f32_e32 v143, v143, v67
	v_mul_f32_e32 v140, 0x3d800000, v140
	v_mul_f32_e32 v141, 0x3d800000, v141
	v_mul_f32_e32 v142, 0x3d800000, v142
	v_mul_f32_e32 v143, 0x3d800000, v143
	v_sub_f32_e32 v140, v140, v124
	v_sub_f32_e32 v141, v141, v125
	v_sub_f32_e32 v142, v142, v126
	v_sub_f32_e32 v143, v143, v127
	v_cvt_pk_bf16_f32 v144, v140, v141
	v_cvt_pk_bf16_f32 v145, v142, v143
	global_store_dwordx2 v11, v[144:145], s[24:25]
	s_add_u32 s24, s24, 0x800
	s_addc_u32 s25, s25, 0
	s_waitcnt vmcnt(2)
	v_and_b32_e32 v131, 0xffff0000, v129
	v_lshlrev_b32_e32 v130, 16, v129
	v_and_b32_e32 v129, 0xffff0000, v128
	v_lshlrev_b32_e32 v128, 16, v128
	v_add_f32_e32 v140, v128, v124
	v_add_f32_e32 v141, v129, v125
	v_add_f32_e32 v142, v130, v126
	v_add_f32_e32 v143, v131, v127
	v_add_f32_e32 v140, v140, v120
	v_add_f32_e32 v141, v141, v121
	v_add_f32_e32 v142, v142, v122
	v_add_f32_e32 v143, v143, v123
	v_add_f32_e32 v140, v140, v116
	v_add_f32_e32 v141, v141, v117
	v_add_f32_e32 v142, v142, v118
	v_add_f32_e32 v143, v143, v119
	v_add_f32_e32 v140, v140, v112
	v_add_f32_e32 v141, v141, v113
	v_add_f32_e32 v142, v142, v114
	v_add_f32_e32 v143, v143, v115
	v_add_f32_e32 v140, v140, v108
	v_add_f32_e32 v141, v141, v109
	v_add_f32_e32 v142, v142, v110
	v_add_f32_e32 v143, v143, v111
	v_add_f32_e32 v140, v140, v104
	v_add_f32_e32 v141, v141, v105
	v_add_f32_e32 v142, v142, v106
	v_add_f32_e32 v143, v143, v107
	v_add_f32_e32 v140, v140, v100
	v_add_f32_e32 v141, v141, v101
	v_add_f32_e32 v142, v142, v102
	v_add_f32_e32 v143, v143, v103
	v_add_f32_e32 v140, v140, v96
	v_add_f32_e32 v141, v141, v97
	v_add_f32_e32 v142, v142, v98
	v_add_f32_e32 v143, v143, v99
	v_add_f32_e32 v140, v140, v92
	v_add_f32_e32 v141, v141, v93
	v_add_f32_e32 v142, v142, v94
	v_add_f32_e32 v143, v143, v95
	v_add_f32_e32 v140, v140, v88
	v_add_f32_e32 v141, v141, v89
	v_add_f32_e32 v142, v142, v90
	v_add_f32_e32 v143, v143, v91
	v_add_f32_e32 v140, v140, v84
	v_add_f32_e32 v141, v141, v85
	v_add_f32_e32 v142, v142, v86
	v_add_f32_e32 v143, v143, v87
	v_add_f32_e32 v140, v140, v80
	v_add_f32_e32 v141, v141, v81
	v_add_f32_e32 v142, v142, v82
	v_add_f32_e32 v143, v143, v83
	v_add_f32_e32 v140, v140, v76
	v_add_f32_e32 v141, v141, v77
	v_add_f32_e32 v142, v142, v78
	v_add_f32_e32 v143, v143, v79
	v_add_f32_e32 v140, v140, v72
	v_add_f32_e32 v141, v141, v73
	v_add_f32_e32 v142, v142, v74
	v_add_f32_e32 v143, v143, v75
	v_add_f32_e32 v140, v140, v68
	v_add_f32_e32 v141, v141, v69
	v_add_f32_e32 v142, v142, v70
	v_add_f32_e32 v143, v143, v71
	v_mul_f32_e32 v140, 0x3d800000, v140
	v_mul_f32_e32 v141, 0x3d800000, v141
	v_mul_f32_e32 v142, 0x3d800000, v142
	v_mul_f32_e32 v143, 0x3d800000, v143
	v_sub_f32_e32 v140, v140, v128
	v_sub_f32_e32 v141, v141, v129
	v_sub_f32_e32 v142, v142, v130
	v_sub_f32_e32 v143, v143, v131
	v_cvt_pk_bf16_f32 v144, v140, v141
	v_cvt_pk_bf16_f32 v145, v142, v143
	global_store_dwordx2 v11, v[144:145], s[24:25]
	s_add_u32 s24, s24, 0x800
	s_addc_u32 s25, s25, 0
	s_waitcnt vmcnt(1)
; DI float bflo(unsigned u) { return __uint_as_float(u << 16); }
; DI float bfhi(unsigned u) { return __uint_as_float(u & 0xffff0000u); }
; template <int WIN>
; DI void pool_elem(const Params& p, int row, int c) {
;     ...
;     if (t >= WIN - 1) {
;       cnt = (float)WIN;
;       unsigned w[WIN - 1];
; #pragma unroll
;       for (int j = 1; j < WIN; ++j) w[j - 1] = *(const unsigned*)(P2 + (size_t)(row - j) * 2048 + c);
; #pragma unroll
;       for (int j = 1; j < WIN; ++j) { s0 += bflo(w[j - 1]); s1 += bfhi(w[j - 1]); }
;     } else {
;       cnt = (float)(t + 1);
;       for (int j = 1; j <= t; ++j) {
;         unsigned w = *(const unsigned*)(P2 + (size_t)(row - j) * 2048 + c);
;         s0 += bflo(w); s1 += bfhi(w);
;       }
;     }
;     if (t >= 2033) {
;       float2 o = {u0, u1};
;       *(float2*)(p.out + O_POOLP + ((size_t)b * 15 + (t - 2033)) * 1024 + c) = o;
;     }
;   } else {
;     const int s = row - NPR;
;     cnt = (float)WIN;
;     const float* sp = p.state_pool + (size_t)s * 15 * 1024 + c;
;     float2 st[15];
; #pragma unroll
;     for (int j = 0; j < 15; ++j) st[j] = *(const float2*)(sp + (size_t)j * 1024);
; #pragma unroll
;     for (int j = 1; j < WIN; ++j) { s0 += st[15 - j].x; s1 += st[15 - j].y; }
;     float* op = p.out + O_POOLS + (size_t)s * 15 * 1024 + c;
; #pragma unroll
;     for (int j = 0; j < 14; ++j) *(float2*)(op + (size_t)j * 1024) = st[j + 1];
;     float2 o = {u0, u1};
;     *(float2*)(op + (size_t)14 * 1024) = o;
;   }
;   *(unsigned*)(p.MIX + (size_t)row * 1024 + c) = pack2(s0 / cnt - u0, s1 / cnt - u1);
	v_and_b32_e32 v135, 0xffff0000, v133
	v_lshlrev_b32_e32 v134, 16, v133
	v_and_b32_e32 v133, 0xffff0000, v132
	v_lshlrev_b32_e32 v132, 16, v132
	v_add_f32_e32 v140, v132, v128
	v_add_f32_e32 v141, v133, v129
	v_add_f32_e32 v142, v134, v130
	v_add_f32_e32 v143, v135, v131
	v_add_f32_e32 v140, v140, v124
	v_add_f32_e32 v141, v141, v125
	v_add_f32_e32 v142, v142, v126
	v_add_f32_e32 v143, v143, v127
	v_add_f32_e32 v140, v140, v120
	v_add_f32_e32 v141, v141, v121
	v_add_f32_e32 v142, v142, v122
	v_add_f32_e32 v143, v143, v123
	v_add_f32_e32 v140, v140, v116
	v_add_f32_e32 v141, v141, v117
	v_add_f32_e32 v142, v142, v118
	v_add_f32_e32 v143, v143, v119
	v_add_f32_e32 v140, v140, v112
	v_add_f32_e32 v141, v141, v113
	v_add_f32_e32 v142, v142, v114
	v_add_f32_e32 v143, v143, v115
	v_add_f32_e32 v140, v140, v108
	v_add_f32_e32 v141, v141, v109
	v_add_f32_e32 v142, v142, v110
	v_add_f32_e32 v143, v143, v111
	v_add_f32_e32 v140, v140, v104
	v_add_f32_e32 v141, v141, v105
	v_add_f32_e32 v142, v142, v106
	v_add_f32_e32 v143, v143, v107
	v_add_f32_e32 v140, v140, v100
	v_add_f32_e32 v141, v141, v101
	v_add_f32_e32 v142, v142, v102
	v_add_f32_e32 v143, v143, v103
	v_add_f32_e32 v140, v140, v96
	v_add_f32_e32 v141, v141, v97
	v_add_f32_e32 v142, v142, v98
	v_add_f32_e32 v143, v143, v99
	v_add_f32_e32 v140, v140, v92
	v_add_f32_e32 v141, v141, v93
	v_add_f32_e32 v142, v142, v94
	v_add_f32_e32 v143, v143, v95
	v_add_f32_e32 v140, v140, v88
	v_add_f32_e32 v141, v141, v89
	v_add_f32_e32 v142, v142, v90
	v_add_f32_e32 v143, v143, v91
	v_add_f32_e32 v140, v140, v84
	v_add_f32_e32 v141, v141, v85
	v_add_f32_e32 v142, v142, v86
	v_add_f32_e32 v143, v143, v87
	v_add_f32_e32 v140, v140, v80
	v_add_f32_e32 v141, v141, v81
	v_add_f32_e32 v142, v142, v82
	v_add_f32_e32 v143, v143, v83
	v_add_f32_e32 v140, v140, v76
	v_add_f32_e32 v141, v141, v77
	v_add_f32_e32 v142, v142, v78
	v_add_f32_e32 v143, v143, v79
	v_add_f32_e32 v140, v140, v72
	v_add_f32_e32 v141, v141, v73
	v_add_f32_e32 v142, v142, v74
	v_add_f32_e32 v143, v143, v75
	v_mul_f32_e32 v140, 0x3d800000, v140
	v_mul_f32_e32 v141, 0x3d800000, v141
	v_mul_f32_e32 v142, 0x3d800000, v142
	v_mul_f32_e32 v143, 0x3d800000, v143
	v_sub_f32_e32 v140, v140, v132
	v_sub_f32_e32 v141, v141, v133
	v_sub_f32_e32 v142, v142, v134
	v_sub_f32_e32 v143, v143, v135
	v_cvt_pk_bf16_f32 v144, v140, v141
	v_cvt_pk_bf16_f32 v145, v142, v143
	global_store_dwordx2 v11, v[144:145], s[24:25]
	s_add_u32 s24, s24, 0x800
	s_addc_u32 s25, s25, 0
	s_waitcnt vmcnt(0)
	v_and_b32_e32 v139, 0xffff0000, v137
	v_lshlrev_b32_e32 v138, 16, v137
	v_and_b32_e32 v137, 0xffff0000, v136
	v_lshlrev_b32_e32 v136, 16, v136
	v_add_f32_e32 v140, v136, v132
	v_add_f32_e32 v141, v137, v133
	v_add_f32_e32 v142, v138, v134
	v_add_f32_e32 v143, v139, v135
	v_add_f32_e32 v140, v140, v128
	v_add_f32_e32 v141, v141, v129
	v_add_f32_e32 v142, v142, v130
	v_add_f32_e32 v143, v143, v131
	v_add_f32_e32 v140, v140, v124
	v_add_f32_e32 v141, v141, v125
	v_add_f32_e32 v142, v142, v126
	v_add_f32_e32 v143, v143, v127
	v_add_f32_e32 v140, v140, v120
	v_add_f32_e32 v141, v141, v121
	v_add_f32_e32 v142, v142, v122
	v_add_f32_e32 v143, v143, v123
	v_add_f32_e32 v140, v140, v116
	v_add_f32_e32 v141, v141, v117
	v_add_f32_e32 v142, v142, v118
	v_add_f32_e32 v143, v143, v119
	v_add_f32_e32 v140, v140, v112
	v_add_f32_e32 v141, v141, v113
	v_add_f32_e32 v142, v142, v114
	v_add_f32_e32 v143, v143, v115
	v_add_f32_e32 v140, v140, v108
	v_add_f32_e32 v141, v141, v109
	v_add_f32_e32 v142, v142, v110
	v_add_f32_e32 v143, v143, v111
	v_add_f32_e32 v140, v140, v104
	v_add_f32_e32 v141, v141, v105
	v_add_f32_e32 v142, v142, v106
	v_add_f32_e32 v143, v143, v107
	v_add_f32_e32 v140, v140, v100
	v_add_f32_e32 v141, v141, v101
	v_add_f32_e32 v142, v142, v102
	v_add_f32_e32 v143, v143, v103
	v_add_f32_e32 v140, v140, v96
	v_add_f32_e32 v141, v141, v97
	v_add_f32_e32 v142, v142, v98
	v_add_f32_e32 v143, v143, v99
	v_add_f32_e32 v140, v140, v92
	v_add_f32_e32 v141, v141, v93
	v_add_f32_e32 v142, v142, v94
	v_add_f32_e32 v143, v143, v95
	v_add_f32_e32 v140, v140, v88
	v_add_f32_e32 v141, v141, v89
	v_add_f32_e32 v142, v142, v90
	v_add_f32_e32 v143, v143, v91
	v_add_f32_e32 v140, v140, v84
	v_add_f32_e32 v141, v141, v85
	v_add_f32_e32 v142, v142, v86
	v_add_f32_e32 v143, v143, v87
	v_add_f32_e32 v140, v140, v80
	v_add_f32_e32 v141, v141, v81
	v_add_f32_e32 v142, v142, v82
	v_add_f32_e32 v143, v143, v83
	v_add_f32_e32 v140, v140, v76
	v_add_f32_e32 v141, v141, v77
	v_add_f32_e32 v142, v142, v78
	v_add_f32_e32 v143, v143, v79
	v_mul_f32_e32 v140, 0x3d800000, v140
	v_mul_f32_e32 v141, 0x3d800000, v141
	v_mul_f32_e32 v142, 0x3d800000, v142
	v_mul_f32_e32 v143, 0x3d800000, v143
	v_sub_f32_e32 v140, v140, v136
	v_sub_f32_e32 v141, v141, v137
	v_sub_f32_e32 v142, v142, v138
	v_sub_f32_e32 v143, v143, v139
	v_cvt_pk_bf16_f32 v144, v140, v141
	v_cvt_pk_bf16_f32 v145, v142, v143
	global_store_dwordx2 v11, v[144:145], s[24:25]
	s_add_u32 s24, s24, 0x800
	s_addc_u32 s25, s25, 0
	s_cmp_eq_u32 s18, 127
	s_cbranch_scc0 .Lp13f_next
	s_mul_i32 s26, s17, 61440
	s_add_u32 s26, s26, 0x431c000
	s_add_u32 s22, s12, s26
	s_addc_u32 s23, s13, 0
	global_store_dwordx4 v12, v[80:83], s[22:23]
	s_add_u32 s22, s22, 0x1000
	s_addc_u32 s23, s23, 0
	global_store_dwordx4 v12, v[84:87], s[22:23]
	s_add_u32 s22, s22, 0x1000
	s_addc_u32 s23, s23, 0
	global_store_dwordx4 v12, v[88:91], s[22:23]
	s_add_u32 s22, s22, 0x1000
	s_addc_u32 s23, s23, 0
	global_store_dwordx4 v12, v[92:95], s[22:23]
	s_add_u32 s22, s22, 0x1000
	s_addc_u32 s23, s23, 0
	global_store_dwordx4 v12, v[96:99], s[22:23]
	s_add_u32 s22, s22, 0x1000
	s_addc_u32 s23, s23, 0
	global_store_dwordx4 v12, v[100:103], s[22:23]
	s_add_u32 s22, s22, 0x1000
	s_addc_u32 s23, s23, 0
	global_store_dwordx4 v12, v[104:107], s[22:23]
	s_add_u32 s22, s22, 0x1000
	s_addc_u32 s23, s23, 0
	global_store_dwordx4 v12, v[108:111], s[22:23]
	s_add_u32 s22, s22, 0x1000
	s_addc_u32 s23, s23, 0
	global_store_dwordx4 v12, v[112:115], s[22:23]
	s_add_u32 s22, s22, 0x1000
	s_addc_u32 s23, s23, 0
	global_store_dwordx4 v12, v[116:119], s[22:23]
	s_add_u32 s22, s22, 0x1000
	s_addc_u32 s23, s23, 0
	global_store_dwordx4 v12, v[120:123], s[22:23]
	s_add_u32 s22, s22, 0x1000
	s_addc_u32 s23, s23, 0
	global_store_dwordx4 v12, v[124:127], s[22:23]
	s_add_u32 s22, s22, 0x1000
	s_addc_u32 s23, s23, 0
	global_store_dwordx4 v12, v[128:131], s[22:23]
	s_add_u32 s22, s22, 0x1000
	s_addc_u32 s23, s23, 0
	global_store_dwordx4 v12, v[132:135], s[22:23]
	s_add_u32 s22, s22, 0x1000
	s_addc_u32 s23, s23, 0
	global_store_dwordx4 v12, v[136:139], s[22:23]
	s_add_u32 s22, s22, 0x1000
	s_addc_u32 s23, s23, 0
	s_branch .Lp13f_next
; DI float bflo(unsigned u) { return __uint_as_float(u << 16); }
; DI float bfhi(unsigned u) { return __uint_as_float(u & 0xffff0000u); }
; template <int WIN>
; DI void pool_elem(const Params& p, int row, int c) {
;     ...
;     } else {
;       cnt = (float)(t + 1);
;       for (int j = 1; j <= t; ++j) {
;         unsigned w = *(const unsigned*)(P2 + (size_t)(row - j) * 2048 + c);
;         s0 += bflo(w); s1 += bfhi(w);
;       }
;     }
;     ...
;   *(unsigned*)(p.MIX + (size_t)row * 1024 + c) = pack2(s0 / cnt - u0, s1 / cnt - u1);
.Lp13f_f0:
	s_sub_u32 s26, s20, 0
	s_lshl_b32 s27, s26, 12
	s_lshr_b32 s28, s26, 20
	s_add_u32 s22, s8, s27
	s_addc_u32 s23, s9, s28
	global_load_dwordx2 v[16:17], v11, s[22:23]
	s_add_u32 s22, s22, 0x1000
	s_addc_u32 s23, s23, 0
	global_load_dwordx2 v[20:21], v11, s[22:23]
	s_add_u32 s22, s22, 0x1000
	s_addc_u32 s23, s23, 0
	global_load_dwordx2 v[24:25], v11, s[22:23]
	s_add_u32 s22, s22, 0x1000
	s_addc_u32 s23, s23, 0
	global_load_dwordx2 v[28:29], v11, s[22:23]
	s_add_u32 s22, s22, 0x1000
	s_addc_u32 s23, s23, 0
	global_load_dwordx2 v[32:33], v11, s[22:23]
	s_add_u32 s22, s22, 0x1000
	s_addc_u32 s23, s23, 0
	global_load_dwordx2 v[36:37], v11, s[22:23]
	s_add_u32 s22, s22, 0x1000
	s_addc_u32 s23, s23, 0
	global_load_dwordx2 v[40:41], v11, s[22:23]
	s_add_u32 s22, s22, 0x1000
	s_addc_u32 s23, s23, 0
	global_load_dwordx2 v[44:45], v11, s[22:23]
	s_add_u32 s22, s22, 0x1000
	s_addc_u32 s23, s23, 0
	global_load_dwordx2 v[48:49], v11, s[22:23]
	s_add_u32 s22, s22, 0x1000
	s_addc_u32 s23, s23, 0
	global_load_dwordx2 v[52:53], v11, s[22:23]
	s_add_u32 s22, s22, 0x1000
	s_addc_u32 s23, s23, 0
	global_load_dwordx2 v[56:57], v11, s[22:23]
	s_add_u32 s22, s22, 0x1000
	s_addc_u32 s23, s23, 0
	global_load_dwordx2 v[60:61], v11, s[22:23]
	s_add_u32 s22, s22, 0x1000
	s_addc_u32 s23, s23, 0
	global_load_dwordx2 v[64:65], v11, s[22:23]
	s_add_u32 s22, s22, 0x1000
	s_addc_u32 s23, s23, 0
	global_load_dwordx2 v[68:69], v11, s[22:23]
	s_add_u32 s22, s22, 0x1000
	s_addc_u32 s23, s23, 0
	global_load_dwordx2 v[72:73], v11, s[22:23]
	s_add_u32 s22, s22, 0x1000
	s_addc_u32 s23, s23, 0
	global_load_dwordx2 v[76:77], v11, s[22:23]
	s_add_u32 s22, s22, 0x1000
	s_addc_u32 s23, s23, 0
	s_waitcnt vmcnt(15)
	v_and_b32_e32 v19, 0xffff0000, v17
	v_lshlrev_b32_e32 v18, 16, v17
	v_and_b32_e32 v17, 0xffff0000, v16
	v_lshlrev_b32_e32 v16, 16, v16
	v_mov_b32_e32 v140, v16
	v_mov_b32_e32 v141, v17
	v_mov_b32_e32 v142, v18
	v_mov_b32_e32 v143, v19
	v_mul_f32_e32 v140, 1.0, v140
	v_mul_f32_e32 v141, 1.0, v141
	v_mul_f32_e32 v142, 1.0, v142
	v_mul_f32_e32 v143, 1.0, v143
	v_sub_f32_e32 v140, v140, v16
	v_sub_f32_e32 v141, v141, v17
	v_sub_f32_e32 v142, v142, v18
	v_sub_f32_e32 v143, v143, v19
	v_cvt_pk_bf16_f32 v144, v140, v141
	v_cvt_pk_bf16_f32 v145, v142, v143
	global_store_dwordx2 v11, v[144:145], s[24:25]
	s_add_u32 s24, s24, 0x800
	s_addc_u32 s25, s25, 0
	s_waitcnt vmcnt(14)
	v_and_b32_e32 v23, 0xffff0000, v21
	v_lshlrev_b32_e32 v22, 16, v21
	v_and_b32_e32 v21, 0xffff0000, v20
	v_lshlrev_b32_e32 v20, 16, v20
	v_add_f32_e32 v140, v20, v16
	v_add_f32_e32 v141, v21, v17
	v_add_f32_e32 v142, v22, v18
	v_add_f32_e32 v143, v23, v19
	v_mul_f32_e32 v140, 0.5, v140
	v_mul_f32_e32 v141, 0.5, v141
	v_mul_f32_e32 v142, 0.5, v142
	v_mul_f32_e32 v143, 0.5, v143
	v_sub_f32_e32 v140, v140, v20
	v_sub_f32_e32 v141, v141, v21
	v_sub_f32_e32 v142, v142, v22
	v_sub_f32_e32 v143, v143, v23
	v_cvt_pk_bf16_f32 v144, v140, v141
	v_cvt_pk_bf16_f32 v145, v142, v143
	global_store_dwordx2 v11, v[144:145], s[24:25]
	s_add_u32 s24, s24, 0x800
	s_addc_u32 s25, s25, 0
	s_waitcnt vmcnt(13)
	v_and_b32_e32 v27, 0xffff0000, v25
	v_lshlrev_b32_e32 v26, 16, v25
	v_and_b32_e32 v25, 0xffff0000, v24
	v_lshlrev_b32_e32 v24, 16, v24
	v_add_f32_e32 v140, v24, v20
	v_add_f32_e32 v141, v25, v21
	v_add_f32_e32 v142, v26, v22
	v_add_f32_e32 v143, v27, v23
	v_mul_f32_e32 v140, 0.5, v140
	v_mul_f32_e32 v141, 0.5, v141
	v_mul_f32_e32 v142, 0.5, v142
	v_mul_f32_e32 v143, 0.5, v143
	v_sub_f32_e32 v140, v140, v24
	v_sub_f32_e32 v141, v141, v25
	v_sub_f32_e32 v142, v142, v26
	v_sub_f32_e32 v143, v143, v27
	v_cvt_pk_bf16_f32 v144, v140, v141
	v_cvt_pk_bf16_f32 v145, v142, v143
	global_store_dwordx2 v11, v[144:145], s[24:25]
	s_add_u32 s24, s24, 0x800
	s_addc_u32 s25, s25, 0
	s_waitcnt vmcnt(12)
	v_and_b32_e32 v31, 0xffff0000, v29
	v_lshlrev_b32_e32 v30, 16, v29
	v_and_b32_e32 v29, 0xffff0000, v28
	v_lshlrev_b32_e32 v28, 16, v28
	v_add_f32_e32 v140, v28, v24
	v_add_f32_e32 v141, v29, v25
	v_add_f32_e32 v142, v30, v26
	v_add_f32_e32 v143, v31, v27
	v_mul_f32_e32 v140, 0.5, v140
	v_mul_f32_e32 v141, 0.5, v141
	v_mul_f32_e32 v142, 0.5, v142
	v_mul_f32_e32 v143, 0.5, v143
	v_sub_f32_e32 v140, v140, v28
	v_sub_f32_e32 v141, v141, v29
	v_sub_f32_e32 v142, v142, v30
	v_sub_f32_e32 v143, v143, v31
	v_cvt_pk_bf16_f32 v144, v140, v141
	v_cvt_pk_bf16_f32 v145, v142, v143
	global_store_dwordx2 v11, v[144:145], s[24:25]
	s_add_u32 s24, s24, 0x800
	s_addc_u32 s25, s25, 0
	s_waitcnt vmcnt(11)
	v_and_b32_e32 v35, 0xffff0000, v33
	v_lshlrev_b32_e32 v34, 16, v33
	v_and_b32_e32 v33, 0xffff0000, v32
	v_lshlrev_b32_e32 v32, 16, v32
	v_add_f32_e32 v140, v32, v28
	v_add_f32_e32 v141, v33, v29
	v_add_f32_e32 v142, v34, v30
	v_add_f32_e32 v143, v35, v31
	v_mul_f32_e32 v140, 0.5, v140
	v_mul_f32_e32 v141, 0.5, v141
	v_mul_f32_e32 v142, 0.5, v142
	v_mul_f32_e32 v143, 0.5, v143
	v_sub_f32_e32 v140, v140, v32
	v_sub_f32_e32 v141, v141, v33
	v_sub_f32_e32 v142, v142, v34
	v_sub_f32_e32 v143, v143, v35
	v_cvt_pk_bf16_f32 v144, v140, v141
	v_cvt_pk_bf16_f32 v145, v142, v143
	global_store_dwordx2 v11, v[144:145], s[24:25]
	s_add_u32 s24, s24, 0x800
	s_addc_u32 s25, s25, 0
	s_waitcnt vmcnt(10)
	v_and_b32_e32 v39, 0xffff0000, v37
	v_lshlrev_b32_e32 v38, 16, v37
	v_and_b32_e32 v37, 0xffff0000, v36
	v_lshlrev_b32_e32 v36, 16, v36
	v_add_f32_e32 v140, v36, v32
	v_add_f32_e32 v141, v37, v33
	v_add_f32_e32 v142, v38, v34
	v_add_f32_e32 v143, v39, v35
	v_mul_f32_e32 v140, 0.5, v140
	v_mul_f32_e32 v141, 0.5, v141
	v_mul_f32_e32 v142, 0.5, v142
	v_mul_f32_e32 v143, 0.5, v143
	v_sub_f32_e32 v140, v140, v36
	v_sub_f32_e32 v141, v141, v37
	v_sub_f32_e32 v142, v142, v38
	v_sub_f32_e32 v143, v143, v39
	v_cvt_pk_bf16_f32 v144, v140, v141
	v_cvt_pk_bf16_f32 v145, v142, v143
	global_store_dwordx2 v11, v[144:145], s[24:25]
	s_add_u32 s24, s24, 0x800
	s_addc_u32 s25, s25, 0
	s_waitcnt vmcnt(9)
; DI float bflo(unsigned u) { return __uint_as_float(u << 16); }
; DI float bfhi(unsigned u) { return __uint_as_float(u & 0xffff0000u); }
; template <int WIN>
; DI void pool_elem(const Params& p, int row, int c) {
;     ...
;     } else {
;       cnt = (float)(t + 1);
;       for (int j = 1; j <= t; ++j) {
;         unsigned w = *(const unsigned*)(P2 + (size_t)(row - j) * 2048 + c);
;         s0 += bflo(w); s1 += bfhi(w);
;       }
;     }
;     ...
;   *(unsigned*)(p.MIX + (size_t)row * 1024 + c) = pack2(s0 / cnt - u0, s1 / cnt - u1);
	v_and_b32_e32 v43, 0xffff0000, v41
	v_lshlrev_b32_e32 v42, 16, v41
	v_and_b32_e32 v41, 0xffff0000, v40
	v_lshlrev_b32_e32 v40, 16, v40
	v_add_f32_e32 v140, v40, v36
	v_add_f32_e32 v141, v41, v37
	v_add_f32_e32 v142, v42, v38
	v_add_f32_e32 v143, v43, v39
	v_mul_f32_e32 v140, 0.5, v140
	v_mul_f32_e32 v141, 0.5, v141
	v_mul_f32_e32 v142, 0.5, v142
	v_mul_f32_e32 v143, 0.5, v143
	v_sub_f32_e32 v140, v140, v40
	v_sub_f32_e32 v141, v141, v41
	v_sub_f32_e32 v142, v142, v42
	v_sub_f32_e32 v143, v143, v43
	v_cvt_pk_bf16_f32 v144, v140, v141
	v_cvt_pk_bf16_f32 v145, v142, v143
	global_store_dwordx2 v11, v[144:145], s[24:25]
	s_add_u32 s24, s24, 0x800
	s_addc_u32 s25, s25, 0
	s_waitcnt vmcnt(8)
	v_and_b32_e32 v47, 0xffff0000, v45
	v_lshlrev_b32_e32 v46, 16, v45
	v_and_b32_e32 v45, 0xffff0000, v44
	v_lshlrev_b32_e32 v44, 16, v44
	v_add_f32_e32 v140, v44, v40
	v_add_f32_e32 v141, v45, v41
	v_add_f32_e32 v142, v46, v42
	v_add_f32_e32 v143, v47, v43
	v_mul_f32_e32 v140, 0.5, v140
	v_mul_f32_e32 v141, 0.5, v141
	v_mul_f32_e32 v142, 0.5, v142
	v_mul_f32_e32 v143, 0.5, v143
	v_sub_f32_e32 v140, v140, v44
	v_sub_f32_e32 v141, v141, v45
	v_sub_f32_e32 v142, v142, v46
	v_sub_f32_e32 v143, v143, v47
	v_cvt_pk_bf16_f32 v144, v140, v141
	v_cvt_pk_bf16_f32 v145, v142, v143
	global_store_dwordx2 v11, v[144:145], s[24:25]
	s_add_u32 s24, s24, 0x800
	s_addc_u32 s25, s25, 0
	s_waitcnt vmcnt(7)
	v_and_b32_e32 v51, 0xffff0000, v49
	v_lshlrev_b32_e32 v50, 16, v49
	v_and_b32_e32 v49, 0xffff0000, v48
	v_lshlrev_b32_e32 v48, 16, v48
	v_add_f32_e32 v140, v48, v44
	v_add_f32_e32 v141, v49, v45
	v_add_f32_e32 v142, v50, v46
	v_add_f32_e32 v143, v51, v47
	v_mul_f32_e32 v140, 0.5, v140
	v_mul_f32_e32 v141, 0.5, v141
	v_mul_f32_e32 v142, 0.5, v142
	v_mul_f32_e32 v143, 0.5, v143
	v_sub_f32_e32 v140, v140, v48
	v_sub_f32_e32 v141, v141, v49
	v_sub_f32_e32 v142, v142, v50
	v_sub_f32_e32 v143, v143, v51
	v_cvt_pk_bf16_f32 v144, v140, v141
	v_cvt_pk_bf16_f32 v145, v142, v143
	global_store_dwordx2 v11, v[144:145], s[24:25]
	s_add_u32 s24, s24, 0x800
	s_addc_u32 s25, s25, 0
	s_waitcnt vmcnt(6)
	v_and_b32_e32 v55, 0xffff0000, v53
	v_lshlrev_b32_e32 v54, 16, v53
	v_and_b32_e32 v53, 0xffff0000, v52
	v_lshlrev_b32_e32 v52, 16, v52
	v_add_f32_e32 v140, v52, v48
	v_add_f32_e32 v141, v53, v49
	v_add_f32_e32 v142, v54, v50
	v_add_f32_e32 v143, v55, v51
	v_mul_f32_e32 v140, 0.5, v140
	v_mul_f32_e32 v141, 0.5, v141
	v_mul_f32_e32 v142, 0.5, v142
	v_mul_f32_e32 v143, 0.5, v143
	v_sub_f32_e32 v140, v140, v52
	v_sub_f32_e32 v141, v141, v53
	v_sub_f32_e32 v142, v142, v54
	v_sub_f32_e32 v143, v143, v55
	v_cvt_pk_bf16_f32 v144, v140, v141
	v_cvt_pk_bf16_f32 v145, v142, v143
	global_store_dwordx2 v11, v[144:145], s[24:25]
	s_add_u32 s24, s24, 0x800
	s_addc_u32 s25, s25, 0
	s_waitcnt vmcnt(5)
	v_and_b32_e32 v59, 0xffff0000, v57
	v_lshlrev_b32_e32 v58, 16, v57
	v_and_b32_e32 v57, 0xffff0000, v56
	v_lshlrev_b32_e32 v56, 16, v56
	v_add_f32_e32 v140, v56, v52
	v_add_f32_e32 v141, v57, v53
	v_add_f32_e32 v142, v58, v54
	v_add_f32_e32 v143, v59, v55
	v_mul_f32_e32 v140, 0.5, v140
	v_mul_f32_e32 v141, 0.5, v141
	v_mul_f32_e32 v142, 0.5, v142
	v_mul_f32_e32 v143, 0.5, v143
	v_sub_f32_e32 v140, v140, v56
	v_sub_f32_e32 v141, v141, v57
	v_sub_f32_e32 v142, v142, v58
	v_sub_f32_e32 v143, v143, v59
	v_cvt_pk_bf16_f32 v144, v140, v141
	v_cvt_pk_bf16_f32 v145, v142, v143
	global_store_dwordx2 v11, v[144:145], s[24:25]
	s_add_u32 s24, s24, 0x800
	s_addc_u32 s25, s25, 0
	s_waitcnt vmcnt(4)
	v_and_b32_e32 v63, 0xffff0000, v61
	v_lshlrev_b32_e32 v62, 16, v61
	v_and_b32_e32 v61, 0xffff0000, v60
	v_lshlrev_b32_e32 v60, 16, v60
	v_add_f32_e32 v140, v60, v56
	v_add_f32_e32 v141, v61, v57
	v_add_f32_e32 v142, v62, v58
	v_add_f32_e32 v143, v63, v59
	v_mul_f32_e32 v140, 0.5, v140
	v_mul_f32_e32 v141, 0.5, v141
	v_mul_f32_e32 v142, 0.5, v142
	v_mul_f32_e32 v143, 0.5, v143
	v_sub_f32_e32 v140, v140, v60
	v_sub_f32_e32 v141, v141, v61
	v_sub_f32_e32 v142, v142, v62
	v_sub_f32_e32 v143, v143, v63
	v_cvt_pk_bf16_f32 v144, v140, v141
	v_cvt_pk_bf16_f32 v145, v142, v143
	global_store_dwordx2 v11, v[144:145], s[24:25]
	s_add_u32 s24, s24, 0x800
	s_addc_u32 s25, s25, 0
	s_waitcnt vmcnt(3)
	v_and_b32_e32 v67, 0xffff0000, v65
	v_lshlrev_b32_e32 v66, 16, v65
	v_and_b32_e32 v65, 0xffff0000, v64
	v_lshlrev_b32_e32 v64, 16, v64
	v_add_f32_e32 v140, v64, v60
	v_add_f32_e32 v141, v65, v61
	v_add_f32_e32 v142, v66, v62
	v_add_f32_e32 v143, v67, v63
	v_mul_f32_e32 v140, 0.5, v140
	v_mul_f32_e32 v141, 0.5, v141
	v_mul_f32_e32 v142, 0.5, v142
	v_mul_f32_e32 v143, 0.5, v143
	v_sub_f32_e32 v140, v140, v64
	v_sub_f32_e32 v141, v141, v65
	v_sub_f32_e32 v142, v142, v66
	v_sub_f32_e32 v143, v143, v67
	v_cvt_pk_bf16_f32 v144, v140, v141
	v_cvt_pk_bf16_f32 v145, v142, v143
	global_store_dwordx2 v11, v[144:145], s[24:25]
	s_add_u32 s24, s24, 0x800
	s_addc_u32 s25, s25, 0
	s_waitcnt vmcnt(2)
	v_and_b32_e32 v71, 0xffff0000, v69
	v_lshlrev_b32_e32 v70, 16, v69
	v_and_b32_e32 v69, 0xffff0000, v68
	v_lshlrev_b32_e32 v68, 16, v68
	v_add_f32_e32 v140, v68, v64
	v_add_f32_e32 v141, v69, v65
	v_add_f32_e32 v142, v70, v66
	v_add_f32_e32 v143, v71, v67
	v_mul_f32_e32 v140, 0.5, v140
	v_mul_f32_e32 v141, 0.5, v141
	v_mul_f32_e32 v142, 0.5, v142
	v_mul_f32_e32 v143, 0.5, v143
	v_sub_f32_e32 v140, v140, v68
	v_sub_f32_e32 v141, v141, v69
	v_sub_f32_e32 v142, v142, v70
	v_sub_f32_e32 v143, v143, v71
	v_cvt_pk_bf16_f32 v144, v140, v141
	v_cvt_pk_bf16_f32 v145, v142, v143
	global_store_dwordx2 v11, v[144:145], s[24:25]
	s_add_u32 s24, s24, 0x800
	s_addc_u32 s25, s25, 0
	s_waitcnt vmcnt(1)
	v_and_b32_e32 v75, 0xffff0000, v73
	v_lshlrev_b32_e32 v74, 16, v73
	v_and_b32_e32 v73, 0xffff0000, v72
	v_lshlrev_b32_e32 v72, 16, v72
	v_add_f32_e32 v140, v72, v68
	v_add_f32_e32 v141, v73, v69
	v_add_f32_e32 v142, v74, v70
	v_add_f32_e32 v143, v75, v71
	v_mul_f32_e32 v140, 0.5, v140
	v_mul_f32_e32 v141, 0.5, v141
	v_mul_f32_e32 v142, 0.5, v142
	v_mul_f32_e32 v143, 0.5, v143
	v_sub_f32_e32 v140, v140, v72
	v_sub_f32_e32 v141, v141, v73
	v_sub_f32_e32 v142, v142, v74
	v_sub_f32_e32 v143, v143, v75
	v_cvt_pk_bf16_f32 v144, v140, v141
	v_cvt_pk_bf16_f32 v145, v142, v143
	global_store_dwordx2 v11, v[144:145], s[24:25]
	s_add_u32 s24, s24, 0x800
	s_addc_u32 s25, s25, 0
	s_waitcnt vmcnt(0)
	v_and_b32_e32 v79, 0xffff0000, v77
	v_lshlrev_b32_e32 v78, 16, v77
	v_and_b32_e32 v77, 0xffff0000, v76
	v_lshlrev_b32_e32 v76, 16, v76
	v_add_f32_e32 v140, v76, v72
	v_add_f32_e32 v141, v77, v73
	v_add_f32_e32 v142, v78, v74
	v_add_f32_e32 v143, v79, v75
	v_mul_f32_e32 v140, 0.5, v140
	v_mul_f32_e32 v141, 0.5, v141
	v_mul_f32_e32 v142, 0.5, v142
	v_mul_f32_e32 v143, 0.5, v143
	v_sub_f32_e32 v140, v140, v76
	v_sub_f32_e32 v141, v141, v77
	v_sub_f32_e32 v142, v142, v78
	v_sub_f32_e32 v143, v143, v79
	v_cvt_pk_bf16_f32 v144, v140, v141
	v_cvt_pk_bf16_f32 v145, v142, v143
	global_store_dwordx2 v11, v[144:145], s[24:25]
	s_add_u32 s24, s24, 0x800
	s_addc_u32 s25, s25, 0
	s_branch .Lp13f_next
; DI float bflo(unsigned u) { return __uint_as_float(u << 16); }
; DI float bfhi(unsigned u) { return __uint_as_float(u & 0xffff0000u); }
; template <int WIN>
; DI void pool_elem(const Params& p, int row, int c) {
;     ...
;     } else {
;       cnt = (float)(t + 1);
;       for (int j = 1; j <= t; ++j) {
;         unsigned w = *(const unsigned*)(P2 + (size_t)(row - j) * 2048 + c);
;         s0 += bflo(w); s1 += bfhi(w);
;       }
;     }
;     ...
;   *(unsigned*)(p.MIX + (size_t)row * 1024 + c) = pack2(s0 / cnt - u0, s1 / cnt - u1);
.Lp13f_f1:
	s_sub_u32 s26, s20, 0
	s_lshl_b32 s27, s26, 12
	s_lshr_b32 s28, s26, 20
	s_add_u32 s22, s8, s27
	s_addc_u32 s23, s9, s28
	global_load_dwordx2 v[16:17], v11, s[22:23]
	s_add_u32 s22, s22, 0x1000
	s_addc_u32 s23, s23, 0
	global_load_dwordx2 v[20:21], v11, s[22:23]
	s_add_u32 s22, s22, 0x1000
	s_addc_u32 s23, s23, 0
	global_load_dwordx2 v[24:25], v11, s[22:23]
	s_add_u32 s22, s22, 0x1000
	s_addc_u32 s23, s23, 0
	global_load_dwordx2 v[28:29], v11, s[22:23]
	s_add_u32 s22, s22, 0x1000
	s_addc_u32 s23, s23, 0
	global_load_dwordx2 v[32:33], v11, s[22:23]
	s_add_u32 s22, s22, 0x1000
	s_addc_u32 s23, s23, 0
	global_load_dwordx2 v[36:37], v11, s[22:23]
	s_add_u32 s22, s22, 0x1000
	s_addc_u32 s23, s23, 0
	global_load_dwordx2 v[40:41], v11, s[22:23]
	s_add_u32 s22, s22, 0x1000
	s_addc_u32 s23, s23, 0
	global_load_dwordx2 v[44:45], v11, s[22:23]
	s_add_u32 s22, s22, 0x1000
	s_addc_u32 s23, s23, 0
	global_load_dwordx2 v[48:49], v11, s[22:23]
	s_add_u32 s22, s22, 0x1000
	s_addc_u32 s23, s23, 0
	global_load_dwordx2 v[52:53], v11, s[22:23]
	s_add_u32 s22, s22, 0x1000
	s_addc_u32 s23, s23, 0
	global_load_dwordx2 v[56:57], v11, s[22:23]
	s_add_u32 s22, s22, 0x1000
	s_addc_u32 s23, s23, 0
	global_load_dwordx2 v[60:61], v11, s[22:23]
	s_add_u32 s22, s22, 0x1000
	s_addc_u32 s23, s23, 0
	global_load_dwordx2 v[64:65], v11, s[22:23]
	s_add_u32 s22, s22, 0x1000
	s_addc_u32 s23, s23, 0
	global_load_dwordx2 v[68:69], v11, s[22:23]
	s_add_u32 s22, s22, 0x1000
	s_addc_u32 s23, s23, 0
	global_load_dwordx2 v[72:73], v11, s[22:23]
	s_add_u32 s22, s22, 0x1000
	s_addc_u32 s23, s23, 0
	global_load_dwordx2 v[76:77], v11, s[22:23]
	s_add_u32 s22, s22, 0x1000
	s_addc_u32 s23, s23, 0
	s_waitcnt vmcnt(15)
	v_and_b32_e32 v19, 0xffff0000, v17
	v_lshlrev_b32_e32 v18, 16, v17
	v_and_b32_e32 v17, 0xffff0000, v16
	v_lshlrev_b32_e32 v16, 16, v16
	v_mov_b32_e32 v140, v16
	v_mov_b32_e32 v141, v17
	v_mov_b32_e32 v142, v18
	v_mov_b32_e32 v143, v19
	v_mul_f32_e32 v140, 1.0, v140
	v_mul_f32_e32 v141, 1.0, v141
	v_mul_f32_e32 v142, 1.0, v142
	v_mul_f32_e32 v143, 1.0, v143
	v_sub_f32_e32 v140, v140, v16
	v_sub_f32_e32 v141, v141, v17
	v_sub_f32_e32 v142, v142, v18
	v_sub_f32_e32 v143, v143, v19
	v_cvt_pk_bf16_f32 v144, v140, v141
	v_cvt_pk_bf16_f32 v145, v142, v143
	global_store_dwordx2 v11, v[144:145], s[24:25]
	s_add_u32 s24, s24, 0x800
	s_addc_u32 s25, s25, 0
	s_waitcnt vmcnt(14)
	v_and_b32_e32 v23, 0xffff0000, v21
	v_lshlrev_b32_e32 v22, 16, v21
	v_and_b32_e32 v21, 0xffff0000, v20
	v_lshlrev_b32_e32 v20, 16, v20
	v_add_f32_e32 v140, v20, v16
	v_add_f32_e32 v141, v21, v17
	v_add_f32_e32 v142, v22, v18
	v_add_f32_e32 v143, v23, v19
	v_mul_f32_e32 v140, 0.5, v140
	v_mul_f32_e32 v141, 0.5, v141
	v_mul_f32_e32 v142, 0.5, v142
	v_mul_f32_e32 v143, 0.5, v143
	v_sub_f32_e32 v140, v140, v20
	v_sub_f32_e32 v141, v141, v21
	v_sub_f32_e32 v142, v142, v22
	v_sub_f32_e32 v143, v143, v23
	v_cvt_pk_bf16_f32 v144, v140, v141
	v_cvt_pk_bf16_f32 v145, v142, v143
	global_store_dwordx2 v11, v[144:145], s[24:25]
	s_add_u32 s24, s24, 0x800
	s_addc_u32 s25, s25, 0
	s_waitcnt vmcnt(13)
	v_and_b32_e32 v27, 0xffff0000, v25
	v_lshlrev_b32_e32 v26, 16, v25
	v_and_b32_e32 v25, 0xffff0000, v24
	v_lshlrev_b32_e32 v24, 16, v24
	v_add_f32_e32 v140, v24, v20
	v_add_f32_e32 v141, v25, v21
	v_add_f32_e32 v142, v26, v22
	v_add_f32_e32 v143, v27, v23
	v_add_f32_e32 v140, v140, v16
	v_add_f32_e32 v141, v141, v17
	v_add_f32_e32 v142, v142, v18
	v_add_f32_e32 v143, v143, v19
	v_mov_b32_e32 v151, 0x40400000
	v_div_scale_f32 v146, s[26:27], v151, v151, v140
	v_rcp_f32_e32 v147, v146
	v_div_scale_f32 v148, vcc, v140, v151, v140
	v_fma_f32 v149, -v146, v147, 1.0
	v_fmac_f32_e32 v147, v149, v147
	v_mul_f32_e32 v149, v148, v147
	v_fma_f32 v150, -v146, v149, v148
	v_fmac_f32_e32 v149, v150, v147
	v_fma_f32 v146, -v146, v149, v148
	v_div_fmas_f32 v146, v146, v147, v149
	v_div_fixup_f32 v140, v146, v151, v140
	v_mov_b32_e32 v151, 0x40400000
	v_div_scale_f32 v146, s[26:27], v151, v151, v141
	v_rcp_f32_e32 v147, v146
	v_div_scale_f32 v148, vcc, v141, v151, v141
	v_fma_f32 v149, -v146, v147, 1.0
	v_fmac_f32_e32 v147, v149, v147
	v_mul_f32_e32 v149, v148, v147
	v_fma_f32 v150, -v146, v149, v148
	v_fmac_f32_e32 v149, v150, v147
	v_fma_f32 v146, -v146, v149, v148
	v_div_fmas_f32 v146, v146, v147, v149
	v_div_fixup_f32 v141, v146, v151, v141
	v_mov_b32_e32 v151, 0x40400000
	v_div_scale_f32 v146, s[26:27], v151, v151, v142
	v_rcp_f32_e32 v147, v146
	v_div_scale_f32 v148, vcc, v142, v151, v142
	v_fma_f32 v149, -v146, v147, 1.0
	v_fmac_f32_e32 v147, v149, v147
	v_mul_f32_e32 v149, v148, v147
	v_fma_f32 v150, -v146, v149, v148
	v_fmac_f32_e32 v149, v150, v147
	v_fma_f32 v146, -v146, v149, v148
	v_div_fmas_f32 v146, v146, v147, v149
	v_div_fixup_f32 v142, v146, v151, v142
	v_mov_b32_e32 v151, 0x40400000
	v_div_scale_f32 v146, s[26:27], v151, v151, v143
	v_rcp_f32_e32 v147, v146
	v_div_scale_f32 v148, vcc, v143, v151, v143
	v_fma_f32 v149, -v146, v147, 1.0
	v_fmac_f32_e32 v147, v149, v147
	v_mul_f32_e32 v149, v148, v147
	v_fma_f32 v150, -v146, v149, v148
	v_fmac_f32_e32 v149, v150, v147
	v_fma_f32 v146, -v146, v149, v148
	v_div_fmas_f32 v146, v146, v147, v149
	v_div_fixup_f32 v143, v146, v151, v143
	v_sub_f32_e32 v140, v140, v24
	v_sub_f32_e32 v141, v141, v25
	v_sub_f32_e32 v142, v142, v26
	v_sub_f32_e32 v143, v143, v27
	v_cvt_pk_bf16_f32 v144, v140, v141
	v_cvt_pk_bf16_f32 v145, v142, v143
	global_store_dwordx2 v11, v[144:145], s[24:25]
	s_add_u32 s24, s24, 0x800
	s_addc_u32 s25, s25, 0
	s_waitcnt vmcnt(12)
; DI float bflo(unsigned u) { return __uint_as_float(u << 16); }
; DI float bfhi(unsigned u) { return __uint_as_float(u & 0xffff0000u); }
; template <int WIN>
; DI void pool_elem(const Params& p, int row, int c) {
;     ...
;     if (t >= WIN - 1) {
;       cnt = (float)WIN;
;       unsigned w[WIN - 1];
; #pragma unroll
;       for (int j = 1; j < WIN; ++j) w[j - 1] = *(const unsigned*)(P2 + (size_t)(row - j) * 2048 + c);
; #pragma unroll
;       for (int j = 1; j < WIN; ++j) { s0 += bflo(w[j - 1]); s1 += bfhi(w[j - 1]); }
;     ...
;   *(unsigned*)(p.MIX + (size_t)row * 1024 + c) = pack2(s0 / cnt - u0, s1 / cnt - u1);
	v_and_b32_e32 v31, 0xffff0000, v29
	v_lshlrev_b32_e32 v30, 16, v29
	v_and_b32_e32 v29, 0xffff0000, v28
	v_lshlrev_b32_e32 v28, 16, v28
	v_add_f32_e32 v140, v28, v24
	v_add_f32_e32 v141, v29, v25
	v_add_f32_e32 v142, v30, v26
	v_add_f32_e32 v143, v31, v27
	v_add_f32_e32 v140, v140, v20
	v_add_f32_e32 v141, v141, v21
	v_add_f32_e32 v142, v142, v22
	v_add_f32_e32 v143, v143, v23
	v_add_f32_e32 v140, v140, v16
	v_add_f32_e32 v141, v141, v17
	v_add_f32_e32 v142, v142, v18
	v_add_f32_e32 v143, v143, v19
	v_mul_f32_e32 v140, 0x3e800000, v140
	v_mul_f32_e32 v141, 0x3e800000, v141
	v_mul_f32_e32 v142, 0x3e800000, v142
	v_mul_f32_e32 v143, 0x3e800000, v143
	v_sub_f32_e32 v140, v140, v28
	v_sub_f32_e32 v141, v141, v29
	v_sub_f32_e32 v142, v142, v30
	v_sub_f32_e32 v143, v143, v31
	v_cvt_pk_bf16_f32 v144, v140, v141
	v_cvt_pk_bf16_f32 v145, v142, v143
	global_store_dwordx2 v11, v[144:145], s[24:25]
	s_add_u32 s24, s24, 0x800
	s_addc_u32 s25, s25, 0
	s_waitcnt vmcnt(11)
	v_and_b32_e32 v35, 0xffff0000, v33
	v_lshlrev_b32_e32 v34, 16, v33
	v_and_b32_e32 v33, 0xffff0000, v32
	v_lshlrev_b32_e32 v32, 16, v32
	v_add_f32_e32 v140, v32, v28
	v_add_f32_e32 v141, v33, v29
	v_add_f32_e32 v142, v34, v30
	v_add_f32_e32 v143, v35, v31
	v_add_f32_e32 v140, v140, v24
	v_add_f32_e32 v141, v141, v25
	v_add_f32_e32 v142, v142, v26
	v_add_f32_e32 v143, v143, v27
	v_add_f32_e32 v140, v140, v20
	v_add_f32_e32 v141, v141, v21
	v_add_f32_e32 v142, v142, v22
	v_add_f32_e32 v143, v143, v23
	v_mul_f32_e32 v140, 0x3e800000, v140
	v_mul_f32_e32 v141, 0x3e800000, v141
	v_mul_f32_e32 v142, 0x3e800000, v142
	v_mul_f32_e32 v143, 0x3e800000, v143
	v_sub_f32_e32 v140, v140, v32
	v_sub_f32_e32 v141, v141, v33
	v_sub_f32_e32 v142, v142, v34
	v_sub_f32_e32 v143, v143, v35
	v_cvt_pk_bf16_f32 v144, v140, v141
	v_cvt_pk_bf16_f32 v145, v142, v143
	global_store_dwordx2 v11, v[144:145], s[24:25]
	s_add_u32 s24, s24, 0x800
	s_addc_u32 s25, s25, 0
	s_waitcnt vmcnt(10)
	v_and_b32_e32 v39, 0xffff0000, v37
	v_lshlrev_b32_e32 v38, 16, v37
	v_and_b32_e32 v37, 0xffff0000, v36
	v_lshlrev_b32_e32 v36, 16, v36
	v_add_f32_e32 v140, v36, v32
	v_add_f32_e32 v141, v37, v33
	v_add_f32_e32 v142, v38, v34
	v_add_f32_e32 v143, v39, v35
	v_add_f32_e32 v140, v140, v28
	v_add_f32_e32 v141, v141, v29
	v_add_f32_e32 v142, v142, v30
	v_add_f32_e32 v143, v143, v31
	v_add_f32_e32 v140, v140, v24
	v_add_f32_e32 v141, v141, v25
	v_add_f32_e32 v142, v142, v26
	v_add_f32_e32 v143, v143, v27
	v_mul_f32_e32 v140, 0x3e800000, v140
	v_mul_f32_e32 v141, 0x3e800000, v141
	v_mul_f32_e32 v142, 0x3e800000, v142
	v_mul_f32_e32 v143, 0x3e800000, v143
	v_sub_f32_e32 v140, v140, v36
	v_sub_f32_e32 v141, v141, v37
	v_sub_f32_e32 v142, v142, v38
	v_sub_f32_e32 v143, v143, v39
	v_cvt_pk_bf16_f32 v144, v140, v141
	v_cvt_pk_bf16_f32 v145, v142, v143
	global_store_dwordx2 v11, v[144:145], s[24:25]
	s_add_u32 s24, s24, 0x800
	s_addc_u32 s25, s25, 0
	s_waitcnt vmcnt(9)
	v_and_b32_e32 v43, 0xffff0000, v41
	v_lshlrev_b32_e32 v42, 16, v41
	v_and_b32_e32 v41, 0xffff0000, v40
	v_lshlrev_b32_e32 v40, 16, v40
	v_add_f32_e32 v140, v40, v36
	v_add_f32_e32 v141, v41, v37
	v_add_f32_e32 v142, v42, v38
	v_add_f32_e32 v143, v43, v39
	v_add_f32_e32 v140, v140, v32
	v_add_f32_e32 v141, v141, v33
	v_add_f32_e32 v142, v142, v34
	v_add_f32_e32 v143, v143, v35
	v_add_f32_e32 v140, v140, v28
	v_add_f32_e32 v141, v141, v29
	v_add_f32_e32 v142, v142, v30
	v_add_f32_e32 v143, v143, v31
	v_mul_f32_e32 v140, 0x3e800000, v140
	v_mul_f32_e32 v141, 0x3e800000, v141
	v_mul_f32_e32 v142, 0x3e800000, v142
	v_mul_f32_e32 v143, 0x3e800000, v143
	v_sub_f32_e32 v140, v140, v40
	v_sub_f32_e32 v141, v141, v41
	v_sub_f32_e32 v142, v142, v42
	v_sub_f32_e32 v143, v143, v43
	v_cvt_pk_bf16_f32 v144, v140, v141
	v_cvt_pk_bf16_f32 v145, v142, v143
	global_store_dwordx2 v11, v[144:145], s[24:25]
	s_add_u32 s24, s24, 0x800
	s_addc_u32 s25, s25, 0
	s_waitcnt vmcnt(8)
	v_and_b32_e32 v47, 0xffff0000, v45
	v_lshlrev_b32_e32 v46, 16, v45
	v_and_b32_e32 v45, 0xffff0000, v44
	v_lshlrev_b32_e32 v44, 16, v44
	v_add_f32_e32 v140, v44, v40
	v_add_f32_e32 v141, v45, v41
	v_add_f32_e32 v142, v46, v42
	v_add_f32_e32 v143, v47, v43
	v_add_f32_e32 v140, v140, v36
	v_add_f32_e32 v141, v141, v37
	v_add_f32_e32 v142, v142, v38
	v_add_f32_e32 v143, v143, v39
	v_add_f32_e32 v140, v140, v32
	v_add_f32_e32 v141, v141, v33
	v_add_f32_e32 v142, v142, v34
	v_add_f32_e32 v143, v143, v35
	v_mul_f32_e32 v140, 0x3e800000, v140
	v_mul_f32_e32 v141, 0x3e800000, v141
	v_mul_f32_e32 v142, 0x3e800000, v142
	v_mul_f32_e32 v143, 0x3e800000, v143
	v_sub_f32_e32 v140, v140, v44
	v_sub_f32_e32 v141, v141, v45
	v_sub_f32_e32 v142, v142, v46
	v_sub_f32_e32 v143, v143, v47
	v_cvt_pk_bf16_f32 v144, v140, v141
	v_cvt_pk_bf16_f32 v145, v142, v143
	global_store_dwordx2 v11, v[144:145], s[24:25]
	s_add_u32 s24, s24, 0x800
	s_addc_u32 s25, s25, 0
	s_waitcnt vmcnt(7)
	v_and_b32_e32 v51, 0xffff0000, v49
	v_lshlrev_b32_e32 v50, 16, v49
	v_and_b32_e32 v49, 0xffff0000, v48
	v_lshlrev_b32_e32 v48, 16, v48
	v_add_f32_e32 v140, v48, v44
	v_add_f32_e32 v141, v49, v45
	v_add_f32_e32 v142, v50, v46
	v_add_f32_e32 v143, v51, v47
	v_add_f32_e32 v140, v140, v40
	v_add_f32_e32 v141, v141, v41
	v_add_f32_e32 v142, v142, v42
	v_add_f32_e32 v143, v143, v43
	v_add_f32_e32 v140, v140, v36
	v_add_f32_e32 v141, v141, v37
	v_add_f32_e32 v142, v142, v38
	v_add_f32_e32 v143, v143, v39
	v_mul_f32_e32 v140, 0x3e800000, v140
	v_mul_f32_e32 v141, 0x3e800000, v141
	v_mul_f32_e32 v142, 0x3e800000, v142
	v_mul_f32_e32 v143, 0x3e800000, v143
	v_sub_f32_e32 v140, v140, v48
	v_sub_f32_e32 v141, v141, v49
	v_sub_f32_e32 v142, v142, v50
	v_sub_f32_e32 v143, v143, v51
	v_cvt_pk_bf16_f32 v144, v140, v141
	v_cvt_pk_bf16_f32 v145, v142, v143
	global_store_dwordx2 v11, v[144:145], s[24:25]
	s_add_u32 s24, s24, 0x800
	s_addc_u32 s25, s25, 0
	s_waitcnt vmcnt(6)
; DI float bflo(unsigned u) { return __uint_as_float(u << 16); }
; DI float bfhi(unsigned u) { return __uint_as_float(u & 0xffff0000u); }
; template <int WIN>
; DI void pool_elem(const Params& p, int row, int c) {
;     ...
;     if (t >= WIN - 1) {
;       cnt = (float)WIN;
;       unsigned w[WIN - 1];
; #pragma unroll
;       for (int j = 1; j < WIN; ++j) w[j - 1] = *(const unsigned*)(P2 + (size_t)(row - j) * 2048 + c);
; #pragma unroll
;       for (int j = 1; j < WIN; ++j) { s0 += bflo(w[j - 1]); s1 += bfhi(w[j - 1]); }
;     ...
;   *(unsigned*)(p.MIX + (size_t)row * 1024 + c) = pack2(s0 / cnt - u0, s1 / cnt - u1);
	v_and_b32_e32 v55, 0xffff0000, v53
	v_lshlrev_b32_e32 v54, 16, v53
	v_and_b32_e32 v53, 0xffff0000, v52
	v_lshlrev_b32_e32 v52, 16, v52
	v_add_f32_e32 v140, v52, v48
	v_add_f32_e32 v141, v53, v49
	v_add_f32_e32 v142, v54, v50
	v_add_f32_e32 v143, v55, v51
	v_add_f32_e32 v140, v140, v44
	v_add_f32_e32 v141, v141, v45
	v_add_f32_e32 v142, v142, v46
	v_add_f32_e32 v143, v143, v47
	v_add_f32_e32 v140, v140, v40
	v_add_f32_e32 v141, v141, v41
	v_add_f32_e32 v142, v142, v42
	v_add_f32_e32 v143, v143, v43
	v_mul_f32_e32 v140, 0x3e800000, v140
	v_mul_f32_e32 v141, 0x3e800000, v141
	v_mul_f32_e32 v142, 0x3e800000, v142
	v_mul_f32_e32 v143, 0x3e800000, v143
	v_sub_f32_e32 v140, v140, v52
	v_sub_f32_e32 v141, v141, v53
	v_sub_f32_e32 v142, v142, v54
	v_sub_f32_e32 v143, v143, v55
	v_cvt_pk_bf16_f32 v144, v140, v141
	v_cvt_pk_bf16_f32 v145, v142, v143
	global_store_dwordx2 v11, v[144:145], s[24:25]
	s_add_u32 s24, s24, 0x800
	s_addc_u32 s25, s25, 0
	s_waitcnt vmcnt(5)
	v_and_b32_e32 v59, 0xffff0000, v57
	v_lshlrev_b32_e32 v58, 16, v57
	v_and_b32_e32 v57, 0xffff0000, v56
	v_lshlrev_b32_e32 v56, 16, v56
	v_add_f32_e32 v140, v56, v52
	v_add_f32_e32 v141, v57, v53
	v_add_f32_e32 v142, v58, v54
	v_add_f32_e32 v143, v59, v55
	v_add_f32_e32 v140, v140, v48
	v_add_f32_e32 v141, v141, v49
	v_add_f32_e32 v142, v142, v50
	v_add_f32_e32 v143, v143, v51
	v_add_f32_e32 v140, v140, v44
	v_add_f32_e32 v141, v141, v45
	v_add_f32_e32 v142, v142, v46
	v_add_f32_e32 v143, v143, v47
	v_mul_f32_e32 v140, 0x3e800000, v140
	v_mul_f32_e32 v141, 0x3e800000, v141
	v_mul_f32_e32 v142, 0x3e800000, v142
	v_mul_f32_e32 v143, 0x3e800000, v143
	v_sub_f32_e32 v140, v140, v56
	v_sub_f32_e32 v141, v141, v57
	v_sub_f32_e32 v142, v142, v58
	v_sub_f32_e32 v143, v143, v59
	v_cvt_pk_bf16_f32 v144, v140, v141
	v_cvt_pk_bf16_f32 v145, v142, v143
	global_store_dwordx2 v11, v[144:145], s[24:25]
	s_add_u32 s24, s24, 0x800
	s_addc_u32 s25, s25, 0
	s_waitcnt vmcnt(4)
	v_and_b32_e32 v63, 0xffff0000, v61
	v_lshlrev_b32_e32 v62, 16, v61
	v_and_b32_e32 v61, 0xffff0000, v60
	v_lshlrev_b32_e32 v60, 16, v60
	v_add_f32_e32 v140, v60, v56
	v_add_f32_e32 v141, v61, v57
	v_add_f32_e32 v142, v62, v58
	v_add_f32_e32 v143, v63, v59
	v_add_f32_e32 v140, v140, v52
	v_add_f32_e32 v141, v141, v53
	v_add_f32_e32 v142, v142, v54
	v_add_f32_e32 v143, v143, v55
	v_add_f32_e32 v140, v140, v48
	v_add_f32_e32 v141, v141, v49
	v_add_f32_e32 v142, v142, v50
	v_add_f32_e32 v143, v143, v51
	v_mul_f32_e32 v140, 0x3e800000, v140
	v_mul_f32_e32 v141, 0x3e800000, v141
	v_mul_f32_e32 v142, 0x3e800000, v142
	v_mul_f32_e32 v143, 0x3e800000, v143
	v_sub_f32_e32 v140, v140, v60
	v_sub_f32_e32 v141, v141, v61
	v_sub_f32_e32 v142, v142, v62
	v_sub_f32_e32 v143, v143, v63
	v_cvt_pk_bf16_f32 v144, v140, v141
	v_cvt_pk_bf16_f32 v145, v142, v143
	global_store_dwordx2 v11, v[144:145], s[24:25]
	s_add_u32 s24, s24, 0x800
	s_addc_u32 s25, s25, 0
	s_waitcnt vmcnt(3)
	v_and_b32_e32 v67, 0xffff0000, v65
	v_lshlrev_b32_e32 v66, 16, v65
	v_and_b32_e32 v65, 0xffff0000, v64
	v_lshlrev_b32_e32 v64, 16, v64
	v_add_f32_e32 v140, v64, v60
	v_add_f32_e32 v141, v65, v61
	v_add_f32_e32 v142, v66, v62
	v_add_f32_e32 v143, v67, v63
	v_add_f32_e32 v140, v140, v56
	v_add_f32_e32 v141, v141, v57
	v_add_f32_e32 v142, v142, v58
	v_add_f32_e32 v143, v143, v59
	v_add_f32_e32 v140, v140, v52
	v_add_f32_e32 v141, v141, v53
	v_add_f32_e32 v142, v142, v54
	v_add_f32_e32 v143, v143, v55
	v_mul_f32_e32 v140, 0x3e800000, v140
	v_mul_f32_e32 v141, 0x3e800000, v141
	v_mul_f32_e32 v142, 0x3e800000, v142
	v_mul_f32_e32 v143, 0x3e800000, v143
	v_sub_f32_e32 v140, v140, v64
	v_sub_f32_e32 v141, v141, v65
	v_sub_f32_e32 v142, v142, v66
	v_sub_f32_e32 v143, v143, v67
	v_cvt_pk_bf16_f32 v144, v140, v141
	v_cvt_pk_bf16_f32 v145, v142, v143
	global_store_dwordx2 v11, v[144:145], s[24:25]
	s_add_u32 s24, s24, 0x800
	s_addc_u32 s25, s25, 0
	s_waitcnt vmcnt(2)
	v_and_b32_e32 v71, 0xffff0000, v69
	v_lshlrev_b32_e32 v70, 16, v69
	v_and_b32_e32 v69, 0xffff0000, v68
	v_lshlrev_b32_e32 v68, 16, v68
	v_add_f32_e32 v140, v68, v64
	v_add_f32_e32 v141, v69, v65
	v_add_f32_e32 v142, v70, v66
	v_add_f32_e32 v143, v71, v67
	v_add_f32_e32 v140, v140, v60
	v_add_f32_e32 v141, v141, v61
	v_add_f32_e32 v142, v142, v62
	v_add_f32_e32 v143, v143, v63
	v_add_f32_e32 v140, v140, v56
	v_add_f32_e32 v141, v141, v57
	v_add_f32_e32 v142, v142, v58
	v_add_f32_e32 v143, v143, v59
	v_mul_f32_e32 v140, 0x3e800000, v140
	v_mul_f32_e32 v141, 0x3e800000, v141
	v_mul_f32_e32 v142, 0x3e800000, v142
	v_mul_f32_e32 v143, 0x3e800000, v143
	v_sub_f32_e32 v140, v140, v68
	v_sub_f32_e32 v141, v141, v69
	v_sub_f32_e32 v142, v142, v70
	v_sub_f32_e32 v143, v143, v71
	v_cvt_pk_bf16_f32 v144, v140, v141
	v_cvt_pk_bf16_f32 v145, v142, v143
	global_store_dwordx2 v11, v[144:145], s[24:25]
	s_add_u32 s24, s24, 0x800
	s_addc_u32 s25, s25, 0
	s_waitcnt vmcnt(1)
	v_and_b32_e32 v75, 0xffff0000, v73
	v_lshlrev_b32_e32 v74, 16, v73
	v_and_b32_e32 v73, 0xffff0000, v72
	v_lshlrev_b32_e32 v72, 16, v72
	v_add_f32_e32 v140, v72, v68
	v_add_f32_e32 v141, v73, v69
	v_add_f32_e32 v142, v74, v70
	v_add_f32_e32 v143, v75, v71
	v_add_f32_e32 v140, v140, v64
	v_add_f32_e32 v141, v141, v65
	v_add_f32_e32 v142, v142, v66
	v_add_f32_e32 v143, v143, v67
	v_add_f32_e32 v140, v140, v60
	v_add_f32_e32 v141, v141, v61
	v_add_f32_e32 v142, v142, v62
	v_add_f32_e32 v143, v143, v63
	v_mul_f32_e32 v140, 0x3e800000, v140
	v_mul_f32_e32 v141, 0x3e800000, v141
	v_mul_f32_e32 v142, 0x3e800000, v142
	v_mul_f32_e32 v143, 0x3e800000, v143
	v_sub_f32_e32 v140, v140, v72
	v_sub_f32_e32 v141, v141, v73
	v_sub_f32_e32 v142, v142, v74
	v_sub_f32_e32 v143, v143, v75
	v_cvt_pk_bf16_f32 v144, v140, v141
	v_cvt_pk_bf16_f32 v145, v142, v143
	global_store_dwordx2 v11, v[144:145], s[24:25]
	s_add_u32 s24, s24, 0x800
	s_addc_u32 s25, s25, 0
	s_waitcnt vmcnt(0)
	v_and_b32_e32 v79, 0xffff0000, v77
	v_lshlrev_b32_e32 v78, 16, v77
	v_and_b32_e32 v77, 0xffff0000, v76
	v_lshlrev_b32_e32 v76, 16, v76
	v_add_f32_e32 v140, v76, v72
	v_add_f32_e32 v141, v77, v73
	v_add_f32_e32 v142, v78, v74
	v_add_f32_e32 v143, v79, v75
	v_add_f32_e32 v140, v140, v68
	v_add_f32_e32 v141, v141, v69
	v_add_f32_e32 v142, v142, v70
	v_add_f32_e32 v143, v143, v71
	v_add_f32_e32 v140, v140, v64
	v_add_f32_e32 v141, v141, v65
	v_add_f32_e32 v142, v142, v66
	v_add_f32_e32 v143, v143, v67
	v_mul_f32_e32 v140, 0x3e800000, v140
	v_mul_f32_e32 v141, 0x3e800000, v141
	v_mul_f32_e32 v142, 0x3e800000, v142
	v_mul_f32_e32 v143, 0x3e800000, v143
	v_sub_f32_e32 v140, v140, v76
	v_sub_f32_e32 v141, v141, v77
	v_sub_f32_e32 v142, v142, v78
	v_sub_f32_e32 v143, v143, v79
	v_cvt_pk_bf16_f32 v144, v140, v141
	v_cvt_pk_bf16_f32 v145, v142, v143
	global_store_dwordx2 v11, v[144:145], s[24:25]
	s_add_u32 s24, s24, 0x800
	s_addc_u32 s25, s25, 0
	s_branch .Lp13f_next
; DI float bflo(unsigned u) { return __uint_as_float(u << 16); }
; DI float bfhi(unsigned u) { return __uint_as_float(u & 0xffff0000u); }
; template <int WIN>
; DI void pool_elem(const Params& p, int row, int c) {
;     ...
;     } else {
;       cnt = (float)(t + 1);
;       for (int j = 1; j <= t; ++j) {
;         unsigned w = *(const unsigned*)(P2 + (size_t)(row - j) * 2048 + c);
;         s0 += bflo(w); s1 += bfhi(w);
;       }
;     }
;     ...
;   *(unsigned*)(p.MIX + (size_t)row * 1024 + c) = pack2(s0 / cnt - u0, s1 / cnt - u1);
.Lp13f_f2:
	s_sub_u32 s26, s20, 0
	s_lshl_b32 s27, s26, 12
	s_lshr_b32 s28, s26, 20
	s_add_u32 s22, s8, s27
	s_addc_u32 s23, s9, s28
	global_load_dwordx2 v[16:17], v11, s[22:23]
	s_add_u32 s22, s22, 0x1000
	s_addc_u32 s23, s23, 0
	global_load_dwordx2 v[20:21], v11, s[22:23]
	s_add_u32 s22, s22, 0x1000
	s_addc_u32 s23, s23, 0
	global_load_dwordx2 v[24:25], v11, s[22:23]
	s_add_u32 s22, s22, 0x1000
	s_addc_u32 s23, s23, 0
	global_load_dwordx2 v[28:29], v11, s[22:23]
	s_add_u32 s22, s22, 0x1000
	s_addc_u32 s23, s23, 0
	global_load_dwordx2 v[32:33], v11, s[22:23]
	s_add_u32 s22, s22, 0x1000
	s_addc_u32 s23, s23, 0
	global_load_dwordx2 v[36:37], v11, s[22:23]
	s_add_u32 s22, s22, 0x1000
	s_addc_u32 s23, s23, 0
	global_load_dwordx2 v[40:41], v11, s[22:23]
	s_add_u32 s22, s22, 0x1000
	s_addc_u32 s23, s23, 0
	global_load_dwordx2 v[44:45], v11, s[22:23]
	s_add_u32 s22, s22, 0x1000
	s_addc_u32 s23, s23, 0
	global_load_dwordx2 v[48:49], v11, s[22:23]
	s_add_u32 s22, s22, 0x1000
	s_addc_u32 s23, s23, 0
	global_load_dwordx2 v[52:53], v11, s[22:23]
	s_add_u32 s22, s22, 0x1000
	s_addc_u32 s23, s23, 0
	global_load_dwordx2 v[56:57], v11, s[22:23]
	s_add_u32 s22, s22, 0x1000
	s_addc_u32 s23, s23, 0
	global_load_dwordx2 v[60:61], v11, s[22:23]
	s_add_u32 s22, s22, 0x1000
	s_addc_u32 s23, s23, 0
	global_load_dwordx2 v[64:65], v11, s[22:23]
	s_add_u32 s22, s22, 0x1000
	s_addc_u32 s23, s23, 0
	global_load_dwordx2 v[68:69], v11, s[22:23]
	s_add_u32 s22, s22, 0x1000
	s_addc_u32 s23, s23, 0
	global_load_dwordx2 v[72:73], v11, s[22:23]
	s_add_u32 s22, s22, 0x1000
	s_addc_u32 s23, s23, 0
	global_load_dwordx2 v[76:77], v11, s[22:23]
	s_add_u32 s22, s22, 0x1000
	s_addc_u32 s23, s23, 0
	s_waitcnt vmcnt(15)
	v_and_b32_e32 v19, 0xffff0000, v17
	v_lshlrev_b32_e32 v18, 16, v17
	v_and_b32_e32 v17, 0xffff0000, v16
	v_lshlrev_b32_e32 v16, 16, v16
	v_mov_b32_e32 v140, v16
	v_mov_b32_e32 v141, v17
	v_mov_b32_e32 v142, v18
	v_mov_b32_e32 v143, v19
	v_mul_f32_e32 v140, 1.0, v140
	v_mul_f32_e32 v141, 1.0, v141
	v_mul_f32_e32 v142, 1.0, v142
	v_mul_f32_e32 v143, 1.0, v143
	v_sub_f32_e32 v140, v140, v16
	v_sub_f32_e32 v141, v141, v17
	v_sub_f32_e32 v142, v142, v18
	v_sub_f32_e32 v143, v143, v19
	v_cvt_pk_bf16_f32 v144, v140, v141
	v_cvt_pk_bf16_f32 v145, v142, v143
	global_store_dwordx2 v11, v[144:145], s[24:25]
	s_add_u32 s24, s24, 0x800
	s_addc_u32 s25, s25, 0
	s_waitcnt vmcnt(14)
	v_and_b32_e32 v23, 0xffff0000, v21
	v_lshlrev_b32_e32 v22, 16, v21
	v_and_b32_e32 v21, 0xffff0000, v20
	v_lshlrev_b32_e32 v20, 16, v20
	v_add_f32_e32 v140, v20, v16
	v_add_f32_e32 v141, v21, v17
	v_add_f32_e32 v142, v22, v18
	v_add_f32_e32 v143, v23, v19
	v_mul_f32_e32 v140, 0.5, v140
	v_mul_f32_e32 v141, 0.5, v141
	v_mul_f32_e32 v142, 0.5, v142
	v_mul_f32_e32 v143, 0.5, v143
	v_sub_f32_e32 v140, v140, v20
	v_sub_f32_e32 v141, v141, v21
	v_sub_f32_e32 v142, v142, v22
	v_sub_f32_e32 v143, v143, v23
	v_cvt_pk_bf16_f32 v144, v140, v141
	v_cvt_pk_bf16_f32 v145, v142, v143
	global_store_dwordx2 v11, v[144:145], s[24:25]
	s_add_u32 s24, s24, 0x800
	s_addc_u32 s25, s25, 0
	s_waitcnt vmcnt(13)
	v_and_b32_e32 v27, 0xffff0000, v25
	v_lshlrev_b32_e32 v26, 16, v25
	v_and_b32_e32 v25, 0xffff0000, v24
	v_lshlrev_b32_e32 v24, 16, v24
	v_add_f32_e32 v140, v24, v20
	v_add_f32_e32 v141, v25, v21
	v_add_f32_e32 v142, v26, v22
	v_add_f32_e32 v143, v27, v23
	v_add_f32_e32 v140, v140, v16
	v_add_f32_e32 v141, v141, v17
	v_add_f32_e32 v142, v142, v18
	v_add_f32_e32 v143, v143, v19
	v_mov_b32_e32 v151, 0x40400000
	v_div_scale_f32 v146, s[26:27], v151, v151, v140
	v_rcp_f32_e32 v147, v146
	v_div_scale_f32 v148, vcc, v140, v151, v140
	v_fma_f32 v149, -v146, v147, 1.0
	v_fmac_f32_e32 v147, v149, v147
	v_mul_f32_e32 v149, v148, v147
	v_fma_f32 v150, -v146, v149, v148
	v_fmac_f32_e32 v149, v150, v147
	v_fma_f32 v146, -v146, v149, v148
	v_div_fmas_f32 v146, v146, v147, v149
	v_div_fixup_f32 v140, v146, v151, v140
	v_mov_b32_e32 v151, 0x40400000
	v_div_scale_f32 v146, s[26:27], v151, v151, v141
	v_rcp_f32_e32 v147, v146
	v_div_scale_f32 v148, vcc, v141, v151, v141
	v_fma_f32 v149, -v146, v147, 1.0
	v_fmac_f32_e32 v147, v149, v147
	v_mul_f32_e32 v149, v148, v147
	v_fma_f32 v150, -v146, v149, v148
	v_fmac_f32_e32 v149, v150, v147
	v_fma_f32 v146, -v146, v149, v148
	v_div_fmas_f32 v146, v146, v147, v149
	v_div_fixup_f32 v141, v146, v151, v141
	v_mov_b32_e32 v151, 0x40400000
	v_div_scale_f32 v146, s[26:27], v151, v151, v142
	v_rcp_f32_e32 v147, v146
	v_div_scale_f32 v148, vcc, v142, v151, v142
	v_fma_f32 v149, -v146, v147, 1.0
	v_fmac_f32_e32 v147, v149, v147
	v_mul_f32_e32 v149, v148, v147
	v_fma_f32 v150, -v146, v149, v148
	v_fmac_f32_e32 v149, v150, v147
	v_fma_f32 v146, -v146, v149, v148
	v_div_fmas_f32 v146, v146, v147, v149
	v_div_fixup_f32 v142, v146, v151, v142
	v_mov_b32_e32 v151, 0x40400000
	v_div_scale_f32 v146, s[26:27], v151, v151, v143
	v_rcp_f32_e32 v147, v146
	v_div_scale_f32 v148, vcc, v143, v151, v143
	v_fma_f32 v149, -v146, v147, 1.0
	v_fmac_f32_e32 v147, v149, v147
	v_mul_f32_e32 v149, v148, v147
	v_fma_f32 v150, -v146, v149, v148
	v_fmac_f32_e32 v149, v150, v147
	v_fma_f32 v146, -v146, v149, v148
	v_div_fmas_f32 v146, v146, v147, v149
	v_div_fixup_f32 v143, v146, v151, v143
	v_sub_f32_e32 v140, v140, v24
	v_sub_f32_e32 v141, v141, v25
	v_sub_f32_e32 v142, v142, v26
	v_sub_f32_e32 v143, v143, v27
	v_cvt_pk_bf16_f32 v144, v140, v141
	v_cvt_pk_bf16_f32 v145, v142, v143
	global_store_dwordx2 v11, v[144:145], s[24:25]
	s_add_u32 s24, s24, 0x800
	s_addc_u32 s25, s25, 0
	s_waitcnt vmcnt(12)
; DI float bflo(unsigned u) { return __uint_as_float(u << 16); }
; DI float bfhi(unsigned u) { return __uint_as_float(u & 0xffff0000u); }
; template <int WIN>
; DI void pool_elem(const Params& p, int row, int c) {
;     ...
;     } else {
;       cnt = (float)(t + 1);
;       for (int j = 1; j <= t; ++j) {
;         unsigned w = *(const unsigned*)(P2 + (size_t)(row - j) * 2048 + c);
;         s0 += bflo(w); s1 += bfhi(w);
;       }
;     }
;     ...
;   *(unsigned*)(p.MIX + (size_t)row * 1024 + c) = pack2(s0 / cnt - u0, s1 / cnt - u1);
	v_and_b32_e32 v31, 0xffff0000, v29
	v_lshlrev_b32_e32 v30, 16, v29
	v_and_b32_e32 v29, 0xffff0000, v28
	v_lshlrev_b32_e32 v28, 16, v28
	v_add_f32_e32 v140, v28, v24
	v_add_f32_e32 v141, v29, v25
	v_add_f32_e32 v142, v30, v26
	v_add_f32_e32 v143, v31, v27
	v_add_f32_e32 v140, v140, v20
	v_add_f32_e32 v141, v141, v21
	v_add_f32_e32 v142, v142, v22
	v_add_f32_e32 v143, v143, v23
	v_add_f32_e32 v140, v140, v16
	v_add_f32_e32 v141, v141, v17
	v_add_f32_e32 v142, v142, v18
	v_add_f32_e32 v143, v143, v19
	v_mul_f32_e32 v140, 0x3e800000, v140
	v_mul_f32_e32 v141, 0x3e800000, v141
	v_mul_f32_e32 v142, 0x3e800000, v142
	v_mul_f32_e32 v143, 0x3e800000, v143
	v_sub_f32_e32 v140, v140, v28
	v_sub_f32_e32 v141, v141, v29
	v_sub_f32_e32 v142, v142, v30
	v_sub_f32_e32 v143, v143, v31
	v_cvt_pk_bf16_f32 v144, v140, v141
	v_cvt_pk_bf16_f32 v145, v142, v143
	global_store_dwordx2 v11, v[144:145], s[24:25]
	s_add_u32 s24, s24, 0x800
	s_addc_u32 s25, s25, 0
	s_waitcnt vmcnt(11)
	v_and_b32_e32 v35, 0xffff0000, v33
	v_lshlrev_b32_e32 v34, 16, v33
	v_and_b32_e32 v33, 0xffff0000, v32
	v_lshlrev_b32_e32 v32, 16, v32
	v_add_f32_e32 v140, v32, v28
	v_add_f32_e32 v141, v33, v29
	v_add_f32_e32 v142, v34, v30
	v_add_f32_e32 v143, v35, v31
	v_add_f32_e32 v140, v140, v24
	v_add_f32_e32 v141, v141, v25
	v_add_f32_e32 v142, v142, v26
	v_add_f32_e32 v143, v143, v27
	v_add_f32_e32 v140, v140, v20
	v_add_f32_e32 v141, v141, v21
	v_add_f32_e32 v142, v142, v22
	v_add_f32_e32 v143, v143, v23
	v_add_f32_e32 v140, v140, v16
	v_add_f32_e32 v141, v141, v17
	v_add_f32_e32 v142, v142, v18
	v_add_f32_e32 v143, v143, v19
	v_mov_b32_e32 v151, 0x40a00000
	v_div_scale_f32 v146, s[26:27], v151, v151, v140
	v_rcp_f32_e32 v147, v146
	v_div_scale_f32 v148, vcc, v140, v151, v140
	v_fma_f32 v149, -v146, v147, 1.0
	v_fmac_f32_e32 v147, v149, v147
	v_mul_f32_e32 v149, v148, v147
	v_fma_f32 v150, -v146, v149, v148
	v_fmac_f32_e32 v149, v150, v147
	v_fma_f32 v146, -v146, v149, v148
	v_div_fmas_f32 v146, v146, v147, v149
	v_div_fixup_f32 v140, v146, v151, v140
	v_mov_b32_e32 v151, 0x40a00000
	v_div_scale_f32 v146, s[26:27], v151, v151, v141
	v_rcp_f32_e32 v147, v146
	v_div_scale_f32 v148, vcc, v141, v151, v141
	v_fma_f32 v149, -v146, v147, 1.0
	v_fmac_f32_e32 v147, v149, v147
	v_mul_f32_e32 v149, v148, v147
	v_fma_f32 v150, -v146, v149, v148
	v_fmac_f32_e32 v149, v150, v147
	v_fma_f32 v146, -v146, v149, v148
	v_div_fmas_f32 v146, v146, v147, v149
	v_div_fixup_f32 v141, v146, v151, v141
	v_mov_b32_e32 v151, 0x40a00000
	v_div_scale_f32 v146, s[26:27], v151, v151, v142
	v_rcp_f32_e32 v147, v146
	v_div_scale_f32 v148, vcc, v142, v151, v142
	v_fma_f32 v149, -v146, v147, 1.0
	v_fmac_f32_e32 v147, v149, v147
	v_mul_f32_e32 v149, v148, v147
	v_fma_f32 v150, -v146, v149, v148
	v_fmac_f32_e32 v149, v150, v147
	v_fma_f32 v146, -v146, v149, v148
	v_div_fmas_f32 v146, v146, v147, v149
	v_div_fixup_f32 v142, v146, v151, v142
	v_mov_b32_e32 v151, 0x40a00000
	v_div_scale_f32 v146, s[26:27], v151, v151, v143
	v_rcp_f32_e32 v147, v146
	v_div_scale_f32 v148, vcc, v143, v151, v143
	v_fma_f32 v149, -v146, v147, 1.0
	v_fmac_f32_e32 v147, v149, v147
	v_mul_f32_e32 v149, v148, v147
	v_fma_f32 v150, -v146, v149, v148
	v_fmac_f32_e32 v149, v150, v147
	v_fma_f32 v146, -v146, v149, v148
	v_div_fmas_f32 v146, v146, v147, v149
	v_div_fixup_f32 v143, v146, v151, v143
	v_sub_f32_e32 v140, v140, v32
	v_sub_f32_e32 v141, v141, v33
	v_sub_f32_e32 v142, v142, v34
	v_sub_f32_e32 v143, v143, v35
	v_cvt_pk_bf16_f32 v144, v140, v141
	v_cvt_pk_bf16_f32 v145, v142, v143
	global_store_dwordx2 v11, v[144:145], s[24:25]
	s_add_u32 s24, s24, 0x800
	s_addc_u32 s25, s25, 0
	s_waitcnt vmcnt(10)
	v_and_b32_e32 v39, 0xffff0000, v37
	v_lshlrev_b32_e32 v38, 16, v37
	v_and_b32_e32 v37, 0xffff0000, v36
	v_lshlrev_b32_e32 v36, 16, v36
	v_add_f32_e32 v140, v36, v32
	v_add_f32_e32 v141, v37, v33
	v_add_f32_e32 v142, v38, v34
	v_add_f32_e32 v143, v39, v35
	v_add_f32_e32 v140, v140, v28
	v_add_f32_e32 v141, v141, v29
	v_add_f32_e32 v142, v142, v30
	v_add_f32_e32 v143, v143, v31
	v_add_f32_e32 v140, v140, v24
	v_add_f32_e32 v141, v141, v25
	v_add_f32_e32 v142, v142, v26
	v_add_f32_e32 v143, v143, v27
	v_add_f32_e32 v140, v140, v20
	v_add_f32_e32 v141, v141, v21
	v_add_f32_e32 v142, v142, v22
	v_add_f32_e32 v143, v143, v23
	v_add_f32_e32 v140, v140, v16
	v_add_f32_e32 v141, v141, v17
	v_add_f32_e32 v142, v142, v18
	v_add_f32_e32 v143, v143, v19
	v_mov_b32_e32 v151, 0x40c00000
	v_div_scale_f32 v146, s[26:27], v151, v151, v140
	v_rcp_f32_e32 v147, v146
	v_div_scale_f32 v148, vcc, v140, v151, v140
	v_fma_f32 v149, -v146, v147, 1.0
	v_fmac_f32_e32 v147, v149, v147
	v_mul_f32_e32 v149, v148, v147
	v_fma_f32 v150, -v146, v149, v148
	v_fmac_f32_e32 v149, v150, v147
	v_fma_f32 v146, -v146, v149, v148
	v_div_fmas_f32 v146, v146, v147, v149
	v_div_fixup_f32 v140, v146, v151, v140
	v_mov_b32_e32 v151, 0x40c00000
	v_div_scale_f32 v146, s[26:27], v151, v151, v141
	v_rcp_f32_e32 v147, v146
	v_div_scale_f32 v148, vcc, v141, v151, v141
	v_fma_f32 v149, -v146, v147, 1.0
	v_fmac_f32_e32 v147, v149, v147
	v_mul_f32_e32 v149, v148, v147
	v_fma_f32 v150, -v146, v149, v148
	v_fmac_f32_e32 v149, v150, v147
	v_fma_f32 v146, -v146, v149, v148
	v_div_fmas_f32 v146, v146, v147, v149
	v_div_fixup_f32 v141, v146, v151, v141
	v_mov_b32_e32 v151, 0x40c00000
	v_div_scale_f32 v146, s[26:27], v151, v151, v142
	v_rcp_f32_e32 v147, v146
	v_div_scale_f32 v148, vcc, v142, v151, v142
	v_fma_f32 v149, -v146, v147, 1.0
	v_fmac_f32_e32 v147, v149, v147
	v_mul_f32_e32 v149, v148, v147
	v_fma_f32 v150, -v146, v149, v148
	v_fmac_f32_e32 v149, v150, v147
	v_fma_f32 v146, -v146, v149, v148
	v_div_fmas_f32 v146, v146, v147, v149
	v_div_fixup_f32 v142, v146, v151, v142
	v_mov_b32_e32 v151, 0x40c00000
	v_div_scale_f32 v146, s[26:27], v151, v151, v143
	v_rcp_f32_e32 v147, v146
	v_div_scale_f32 v148, vcc, v143, v151, v143
	v_fma_f32 v149, -v146, v147, 1.0
	v_fmac_f32_e32 v147, v149, v147
	v_mul_f32_e32 v149, v148, v147
	v_fma_f32 v150, -v146, v149, v148
	v_fmac_f32_e32 v149, v150, v147
	v_fma_f32 v146, -v146, v149, v148
	v_div_fmas_f32 v146, v146, v147, v149
	v_div_fixup_f32 v143, v146, v151, v143
	v_sub_f32_e32 v140, v140, v36
	v_sub_f32_e32 v141, v141, v37
	v_sub_f32_e32 v142, v142, v38
	v_sub_f32_e32 v143, v143, v39
	v_cvt_pk_bf16_f32 v144, v140, v141
	v_cvt_pk_bf16_f32 v145, v142, v143
	global_store_dwordx2 v11, v[144:145], s[24:25]
	s_add_u32 s24, s24, 0x800
	s_addc_u32 s25, s25, 0
	s_waitcnt vmcnt(9)
; DI float bflo(unsigned u) { return __uint_as_float(u << 16); }
; DI float bfhi(unsigned u) { return __uint_as_float(u & 0xffff0000u); }
; template <int WIN>
; DI void pool_elem(const Params& p, int row, int c) {
;     ...
;   unsigned uu = *(const unsigned*)(P2 + (size_t)row * 2048 + c);
;   const float u0 = bflo(uu), u1 = bfhi(uu);
;   float s0 = u0, s1 = u1, cnt;
;   if (row < NPR) {
;     const int t = row & 2047, b = row >> 11;
;     if (t >= WIN - 1) {
;       cnt = (float)WIN;
;       unsigned w[WIN - 1];
; #pragma unroll
;       for (int j = 1; j < WIN; ++j) w[j - 1] = *(const unsigned*)(P2 + (size_t)(row - j) * 2048 + c);
; #pragma unroll
;       for (int j = 1; j < WIN; ++j) { s0 += bflo(w[j - 1]); s1 += bfhi(w[j - 1]); }
;     } else {
;       cnt = (float)(t + 1);
;       for (int j = 1; j <= t; ++j) {
;         unsigned w = *(const unsigned*)(P2 + (size_t)(row - j) * 2048 + c);
;         s0 += bflo(w); s1 += bfhi(w);
;       }
;     ...
;   *(unsigned*)(p.MIX + (size_t)row * 1024 + c) = pack2(s0 / cnt - u0, s1 / cnt - u1);
	v_and_b32_e32 v43, 0xffff0000, v41
	v_lshlrev_b32_e32 v42, 16, v41
	v_and_b32_e32 v41, 0xffff0000, v40
	v_lshlrev_b32_e32 v40, 16, v40
	v_add_f32_e32 v140, v40, v36
	v_add_f32_e32 v141, v41, v37
	v_add_f32_e32 v142, v42, v38
	v_add_f32_e32 v143, v43, v39
	v_add_f32_e32 v140, v140, v32
	v_add_f32_e32 v141, v141, v33
	v_add_f32_e32 v142, v142, v34
	v_add_f32_e32 v143, v143, v35
	v_add_f32_e32 v140, v140, v28
	v_add_f32_e32 v141, v141, v29
	v_add_f32_e32 v142, v142, v30
	v_add_f32_e32 v143, v143, v31
	v_add_f32_e32 v140, v140, v24
	v_add_f32_e32 v141, v141, v25
	v_add_f32_e32 v142, v142, v26
	v_add_f32_e32 v143, v143, v27
	v_add_f32_e32 v140, v140, v20
	v_add_f32_e32 v141, v141, v21
	v_add_f32_e32 v142, v142, v22
	v_add_f32_e32 v143, v143, v23
	v_add_f32_e32 v140, v140, v16
	v_add_f32_e32 v141, v141, v17
	v_add_f32_e32 v142, v142, v18
	v_add_f32_e32 v143, v143, v19
	v_mov_b32_e32 v151, 0x40e00000
	v_div_scale_f32 v146, s[26:27], v151, v151, v140
	v_rcp_f32_e32 v147, v146
	v_div_scale_f32 v148, vcc, v140, v151, v140
	v_fma_f32 v149, -v146, v147, 1.0
	v_fmac_f32_e32 v147, v149, v147
	v_mul_f32_e32 v149, v148, v147
	v_fma_f32 v150, -v146, v149, v148
	v_fmac_f32_e32 v149, v150, v147
	v_fma_f32 v146, -v146, v149, v148
	v_div_fmas_f32 v146, v146, v147, v149
	v_div_fixup_f32 v140, v146, v151, v140
	v_mov_b32_e32 v151, 0x40e00000
	v_div_scale_f32 v146, s[26:27], v151, v151, v141
	v_rcp_f32_e32 v147, v146
	v_div_scale_f32 v148, vcc, v141, v151, v141
	v_fma_f32 v149, -v146, v147, 1.0
	v_fmac_f32_e32 v147, v149, v147
	v_mul_f32_e32 v149, v148, v147
	v_fma_f32 v150, -v146, v149, v148
	v_fmac_f32_e32 v149, v150, v147
	v_fma_f32 v146, -v146, v149, v148
	v_div_fmas_f32 v146, v146, v147, v149
	v_div_fixup_f32 v141, v146, v151, v141
	v_mov_b32_e32 v151, 0x40e00000
	v_div_scale_f32 v146, s[26:27], v151, v151, v142
	v_rcp_f32_e32 v147, v146
	v_div_scale_f32 v148, vcc, v142, v151, v142
	v_fma_f32 v149, -v146, v147, 1.0
	v_fmac_f32_e32 v147, v149, v147
	v_mul_f32_e32 v149, v148, v147
	v_fma_f32 v150, -v146, v149, v148
	v_fmac_f32_e32 v149, v150, v147
	v_fma_f32 v146, -v146, v149, v148
	v_div_fmas_f32 v146, v146, v147, v149
	v_div_fixup_f32 v142, v146, v151, v142
	v_mov_b32_e32 v151, 0x40e00000
	v_div_scale_f32 v146, s[26:27], v151, v151, v143
	v_rcp_f32_e32 v147, v146
	v_div_scale_f32 v148, vcc, v143, v151, v143
	v_fma_f32 v149, -v146, v147, 1.0
	v_fmac_f32_e32 v147, v149, v147
	v_mul_f32_e32 v149, v148, v147
	v_fma_f32 v150, -v146, v149, v148
	v_fmac_f32_e32 v149, v150, v147
	v_fma_f32 v146, -v146, v149, v148
	v_div_fmas_f32 v146, v146, v147, v149
	v_div_fixup_f32 v143, v146, v151, v143
	v_sub_f32_e32 v140, v140, v40
	v_sub_f32_e32 v141, v141, v41
	v_sub_f32_e32 v142, v142, v42
	v_sub_f32_e32 v143, v143, v43
	v_cvt_pk_bf16_f32 v144, v140, v141
	v_cvt_pk_bf16_f32 v145, v142, v143
	global_store_dwordx2 v11, v[144:145], s[24:25]
	s_add_u32 s24, s24, 0x800
	s_addc_u32 s25, s25, 0
	s_waitcnt vmcnt(8)
	v_and_b32_e32 v47, 0xffff0000, v45
	v_lshlrev_b32_e32 v46, 16, v45
	v_and_b32_e32 v45, 0xffff0000, v44
	v_lshlrev_b32_e32 v44, 16, v44
	v_add_f32_e32 v140, v44, v40
	v_add_f32_e32 v141, v45, v41
	v_add_f32_e32 v142, v46, v42
	v_add_f32_e32 v143, v47, v43
	v_add_f32_e32 v140, v140, v36
	v_add_f32_e32 v141, v141, v37
	v_add_f32_e32 v142, v142, v38
	v_add_f32_e32 v143, v143, v39
	v_add_f32_e32 v140, v140, v32
	v_add_f32_e32 v141, v141, v33
	v_add_f32_e32 v142, v142, v34
	v_add_f32_e32 v143, v143, v35
	v_add_f32_e32 v140, v140, v28
	v_add_f32_e32 v141, v141, v29
	v_add_f32_e32 v142, v142, v30
	v_add_f32_e32 v143, v143, v31
	v_add_f32_e32 v140, v140, v24
	v_add_f32_e32 v141, v141, v25
	v_add_f32_e32 v142, v142, v26
	v_add_f32_e32 v143, v143, v27
	v_add_f32_e32 v140, v140, v20
	v_add_f32_e32 v141, v141, v21
	v_add_f32_e32 v142, v142, v22
	v_add_f32_e32 v143, v143, v23
	v_add_f32_e32 v140, v140, v16
	v_add_f32_e32 v141, v141, v17
	v_add_f32_e32 v142, v142, v18
	v_add_f32_e32 v143, v143, v19
	v_mul_f32_e32 v140, 0x3e000000, v140
	v_mul_f32_e32 v141, 0x3e000000, v141
	v_mul_f32_e32 v142, 0x3e000000, v142
	v_mul_f32_e32 v143, 0x3e000000, v143
	v_sub_f32_e32 v140, v140, v44
	v_sub_f32_e32 v141, v141, v45
	v_sub_f32_e32 v142, v142, v46
	v_sub_f32_e32 v143, v143, v47
	v_cvt_pk_bf16_f32 v144, v140, v141
	v_cvt_pk_bf16_f32 v145, v142, v143
	global_store_dwordx2 v11, v[144:145], s[24:25]
	s_add_u32 s24, s24, 0x800
	s_addc_u32 s25, s25, 0
	s_waitcnt vmcnt(7)
	v_and_b32_e32 v51, 0xffff0000, v49
	v_lshlrev_b32_e32 v50, 16, v49
	v_and_b32_e32 v49, 0xffff0000, v48
	v_lshlrev_b32_e32 v48, 16, v48
	v_add_f32_e32 v140, v48, v44
	v_add_f32_e32 v141, v49, v45
	v_add_f32_e32 v142, v50, v46
	v_add_f32_e32 v143, v51, v47
	v_add_f32_e32 v140, v140, v40
	v_add_f32_e32 v141, v141, v41
	v_add_f32_e32 v142, v142, v42
	v_add_f32_e32 v143, v143, v43
	v_add_f32_e32 v140, v140, v36
	v_add_f32_e32 v141, v141, v37
	v_add_f32_e32 v142, v142, v38
	v_add_f32_e32 v143, v143, v39
	v_add_f32_e32 v140, v140, v32
	v_add_f32_e32 v141, v141, v33
	v_add_f32_e32 v142, v142, v34
	v_add_f32_e32 v143, v143, v35
	v_add_f32_e32 v140, v140, v28
	v_add_f32_e32 v141, v141, v29
	v_add_f32_e32 v142, v142, v30
	v_add_f32_e32 v143, v143, v31
	v_add_f32_e32 v140, v140, v24
	v_add_f32_e32 v141, v141, v25
	v_add_f32_e32 v142, v142, v26
	v_add_f32_e32 v143, v143, v27
	v_add_f32_e32 v140, v140, v20
	v_add_f32_e32 v141, v141, v21
	v_add_f32_e32 v142, v142, v22
	v_add_f32_e32 v143, v143, v23
	v_mul_f32_e32 v140, 0x3e000000, v140
	v_mul_f32_e32 v141, 0x3e000000, v141
	v_mul_f32_e32 v142, 0x3e000000, v142
	v_mul_f32_e32 v143, 0x3e000000, v143
	v_sub_f32_e32 v140, v140, v48
	v_sub_f32_e32 v141, v141, v49
	v_sub_f32_e32 v142, v142, v50
	v_sub_f32_e32 v143, v143, v51
	v_cvt_pk_bf16_f32 v144, v140, v141
	v_cvt_pk_bf16_f32 v145, v142, v143
	global_store_dwordx2 v11, v[144:145], s[24:25]
	s_add_u32 s24, s24, 0x800
	s_addc_u32 s25, s25, 0
	s_waitcnt vmcnt(6)
; DI float bflo(unsigned u) { return __uint_as_float(u << 16); }
; DI float bfhi(unsigned u) { return __uint_as_float(u & 0xffff0000u); }
; template <int WIN>
; DI void pool_elem(const Params& p, int row, int c) {
;     ...
;     if (t >= WIN - 1) {
;       cnt = (float)WIN;
;       unsigned w[WIN - 1];
; #pragma unroll
;       for (int j = 1; j < WIN; ++j) w[j - 1] = *(const unsigned*)(P2 + (size_t)(row - j) * 2048 + c);
; #pragma unroll
;       for (int j = 1; j < WIN; ++j) { s0 += bflo(w[j - 1]); s1 += bfhi(w[j - 1]); }
;     ...
;   *(unsigned*)(p.MIX + (size_t)row * 1024 + c) = pack2(s0 / cnt - u0, s1 / cnt - u1);
	v_and_b32_e32 v55, 0xffff0000, v53
	v_lshlrev_b32_e32 v54, 16, v53
	v_and_b32_e32 v53, 0xffff0000, v52
	v_lshlrev_b32_e32 v52, 16, v52
	v_add_f32_e32 v140, v52, v48
	v_add_f32_e32 v141, v53, v49
	v_add_f32_e32 v142, v54, v50
	v_add_f32_e32 v143, v55, v51
	v_add_f32_e32 v140, v140, v44
	v_add_f32_e32 v141, v141, v45
	v_add_f32_e32 v142, v142, v46
	v_add_f32_e32 v143, v143, v47
	v_add_f32_e32 v140, v140, v40
	v_add_f32_e32 v141, v141, v41
	v_add_f32_e32 v142, v142, v42
	v_add_f32_e32 v143, v143, v43
	v_add_f32_e32 v140, v140, v36
	v_add_f32_e32 v141, v141, v37
	v_add_f32_e32 v142, v142, v38
	v_add_f32_e32 v143, v143, v39
	v_add_f32_e32 v140, v140, v32
	v_add_f32_e32 v141, v141, v33
	v_add_f32_e32 v142, v142, v34
	v_add_f32_e32 v143, v143, v35
	v_add_f32_e32 v140, v140, v28
	v_add_f32_e32 v141, v141, v29
	v_add_f32_e32 v142, v142, v30
	v_add_f32_e32 v143, v143, v31
	v_add_f32_e32 v140, v140, v24
	v_add_f32_e32 v141, v141, v25
	v_add_f32_e32 v142, v142, v26
	v_add_f32_e32 v143, v143, v27
	v_mul_f32_e32 v140, 0x3e000000, v140
	v_mul_f32_e32 v141, 0x3e000000, v141
	v_mul_f32_e32 v142, 0x3e000000, v142
	v_mul_f32_e32 v143, 0x3e000000, v143
	v_sub_f32_e32 v140, v140, v52
	v_sub_f32_e32 v141, v141, v53
	v_sub_f32_e32 v142, v142, v54
	v_sub_f32_e32 v143, v143, v55
	v_cvt_pk_bf16_f32 v144, v140, v141
	v_cvt_pk_bf16_f32 v145, v142, v143
	global_store_dwordx2 v11, v[144:145], s[24:25]
	s_add_u32 s24, s24, 0x800
	s_addc_u32 s25, s25, 0
	s_waitcnt vmcnt(5)
	v_and_b32_e32 v59, 0xffff0000, v57
	v_lshlrev_b32_e32 v58, 16, v57
	v_and_b32_e32 v57, 0xffff0000, v56
	v_lshlrev_b32_e32 v56, 16, v56
	v_add_f32_e32 v140, v56, v52
	v_add_f32_e32 v141, v57, v53
	v_add_f32_e32 v142, v58, v54
	v_add_f32_e32 v143, v59, v55
	v_add_f32_e32 v140, v140, v48
	v_add_f32_e32 v141, v141, v49
	v_add_f32_e32 v142, v142, v50
	v_add_f32_e32 v143, v143, v51
	v_add_f32_e32 v140, v140, v44
	v_add_f32_e32 v141, v141, v45
	v_add_f32_e32 v142, v142, v46
	v_add_f32_e32 v143, v143, v47
	v_add_f32_e32 v140, v140, v40
	v_add_f32_e32 v141, v141, v41
	v_add_f32_e32 v142, v142, v42
	v_add_f32_e32 v143, v143, v43
	v_add_f32_e32 v140, v140, v36
	v_add_f32_e32 v141, v141, v37
	v_add_f32_e32 v142, v142, v38
	v_add_f32_e32 v143, v143, v39
	v_add_f32_e32 v140, v140, v32
	v_add_f32_e32 v141, v141, v33
	v_add_f32_e32 v142, v142, v34
	v_add_f32_e32 v143, v143, v35
	v_add_f32_e32 v140, v140, v28
	v_add_f32_e32 v141, v141, v29
	v_add_f32_e32 v142, v142, v30
	v_add_f32_e32 v143, v143, v31
	v_mul_f32_e32 v140, 0x3e000000, v140
	v_mul_f32_e32 v141, 0x3e000000, v141
	v_mul_f32_e32 v142, 0x3e000000, v142
	v_mul_f32_e32 v143, 0x3e000000, v143
	v_sub_f32_e32 v140, v140, v56
	v_sub_f32_e32 v141, v141, v57
	v_sub_f32_e32 v142, v142, v58
	v_sub_f32_e32 v143, v143, v59
	v_cvt_pk_bf16_f32 v144, v140, v141
	v_cvt_pk_bf16_f32 v145, v142, v143
	global_store_dwordx2 v11, v[144:145], s[24:25]
	s_add_u32 s24, s24, 0x800
	s_addc_u32 s25, s25, 0
	s_waitcnt vmcnt(4)
	v_and_b32_e32 v63, 0xffff0000, v61
	v_lshlrev_b32_e32 v62, 16, v61
	v_and_b32_e32 v61, 0xffff0000, v60
	v_lshlrev_b32_e32 v60, 16, v60
	v_add_f32_e32 v140, v60, v56
	v_add_f32_e32 v141, v61, v57
	v_add_f32_e32 v142, v62, v58
	v_add_f32_e32 v143, v63, v59
	v_add_f32_e32 v140, v140, v52
	v_add_f32_e32 v141, v141, v53
	v_add_f32_e32 v142, v142, v54
	v_add_f32_e32 v143, v143, v55
	v_add_f32_e32 v140, v140, v48
	v_add_f32_e32 v141, v141, v49
	v_add_f32_e32 v142, v142, v50
	v_add_f32_e32 v143, v143, v51
	v_add_f32_e32 v140, v140, v44
	v_add_f32_e32 v141, v141, v45
	v_add_f32_e32 v142, v142, v46
	v_add_f32_e32 v143, v143, v47
	v_add_f32_e32 v140, v140, v40
	v_add_f32_e32 v141, v141, v41
	v_add_f32_e32 v142, v142, v42
	v_add_f32_e32 v143, v143, v43
	v_add_f32_e32 v140, v140, v36
	v_add_f32_e32 v141, v141, v37
	v_add_f32_e32 v142, v142, v38
	v_add_f32_e32 v143, v143, v39
	v_add_f32_e32 v140, v140, v32
	v_add_f32_e32 v141, v141, v33
	v_add_f32_e32 v142, v142, v34
	v_add_f32_e32 v143, v143, v35
	v_mul_f32_e32 v140, 0x3e000000, v140
	v_mul_f32_e32 v141, 0x3e000000, v141
	v_mul_f32_e32 v142, 0x3e000000, v142
	v_mul_f32_e32 v143, 0x3e000000, v143
	v_sub_f32_e32 v140, v140, v60
	v_sub_f32_e32 v141, v141, v61
	v_sub_f32_e32 v142, v142, v62
	v_sub_f32_e32 v143, v143, v63
	v_cvt_pk_bf16_f32 v144, v140, v141
	v_cvt_pk_bf16_f32 v145, v142, v143
	global_store_dwordx2 v11, v[144:145], s[24:25]
	s_add_u32 s24, s24, 0x800
	s_addc_u32 s25, s25, 0
	s_waitcnt vmcnt(3)
	v_and_b32_e32 v67, 0xffff0000, v65
	v_lshlrev_b32_e32 v66, 16, v65
	v_and_b32_e32 v65, 0xffff0000, v64
	v_lshlrev_b32_e32 v64, 16, v64
	v_add_f32_e32 v140, v64, v60
	v_add_f32_e32 v141, v65, v61
	v_add_f32_e32 v142, v66, v62
	v_add_f32_e32 v143, v67, v63
	v_add_f32_e32 v140, v140, v56
	v_add_f32_e32 v141, v141, v57
	v_add_f32_e32 v142, v142, v58
	v_add_f32_e32 v143, v143, v59
	v_add_f32_e32 v140, v140, v52
	v_add_f32_e32 v141, v141, v53
	v_add_f32_e32 v142, v142, v54
	v_add_f32_e32 v143, v143, v55
	v_add_f32_e32 v140, v140, v48
	v_add_f32_e32 v141, v141, v49
	v_add_f32_e32 v142, v142, v50
	v_add_f32_e32 v143, v143, v51
	v_add_f32_e32 v140, v140, v44
	v_add_f32_e32 v141, v141, v45
	v_add_f32_e32 v142, v142, v46
	v_add_f32_e32 v143, v143, v47
	v_add_f32_e32 v140, v140, v40
	v_add_f32_e32 v141, v141, v41
	v_add_f32_e32 v142, v142, v42
	v_add_f32_e32 v143, v143, v43
	v_add_f32_e32 v140, v140, v36
	v_add_f32_e32 v141, v141, v37
	v_add_f32_e32 v142, v142, v38
	v_add_f32_e32 v143, v143, v39
	v_mul_f32_e32 v140, 0x3e000000, v140
	v_mul_f32_e32 v141, 0x3e000000, v141
	v_mul_f32_e32 v142, 0x3e000000, v142
	v_mul_f32_e32 v143, 0x3e000000, v143
	v_sub_f32_e32 v140, v140, v64
	v_sub_f32_e32 v141, v141, v65
	v_sub_f32_e32 v142, v142, v66
	v_sub_f32_e32 v143, v143, v67
	v_cvt_pk_bf16_f32 v144, v140, v141
	v_cvt_pk_bf16_f32 v145, v142, v143
	global_store_dwordx2 v11, v[144:145], s[24:25]
	s_add_u32 s24, s24, 0x800
	s_addc_u32 s25, s25, 0
	s_waitcnt vmcnt(2)
; DI float bflo(unsigned u) { return __uint_as_float(u << 16); }
; DI float bfhi(unsigned u) { return __uint_as_float(u & 0xffff0000u); }
; template <int WIN>
; DI void pool_elem(const Params& p, int row, int c) {
;     ...
;     if (t >= WIN - 1) {
;       cnt = (float)WIN;
;       unsigned w[WIN - 1];
; #pragma unroll
;       for (int j = 1; j < WIN; ++j) w[j - 1] = *(const unsigned*)(P2 + (size_t)(row - j) * 2048 + c);
; #pragma unroll
;       for (int j = 1; j < WIN; ++j) { s0 += bflo(w[j - 1]); s1 += bfhi(w[j - 1]); }
;     ...
;   *(unsigned*)(p.MIX + (size_t)row * 1024 + c) = pack2(s0 / cnt - u0, s1 / cnt - u1);
; DI void phase_pool(const Params& p) {
;   for (int idx = blockIdx.x * 256 + threadIdx.x; idx < NROW * 512; idx += gridDim.x * 256) {
;     const int row = idx >> 9, c = (idx & 511) * 2;
;     const int gi = c >> 8;
;     if (gi == 0) pool_elem<2>(p, row, c);
;     else if (gi == 1) pool_elem<4>(p, row, c);
;     else if (gi == 2) pool_elem<8>(p, row, c);
;     else pool_elem<16>(p, row, c);
;   }
	v_and_b32_e32 v71, 0xffff0000, v69
	v_lshlrev_b32_e32 v70, 16, v69
	v_and_b32_e32 v69, 0xffff0000, v68
	v_lshlrev_b32_e32 v68, 16, v68
	v_add_f32_e32 v140, v68, v64
	v_add_f32_e32 v141, v69, v65
	v_add_f32_e32 v142, v70, v66
	v_add_f32_e32 v143, v71, v67
	v_add_f32_e32 v140, v140, v60
	v_add_f32_e32 v141, v141, v61
	v_add_f32_e32 v142, v142, v62
	v_add_f32_e32 v143, v143, v63
	v_add_f32_e32 v140, v140, v56
	v_add_f32_e32 v141, v141, v57
	v_add_f32_e32 v142, v142, v58
	v_add_f32_e32 v143, v143, v59
	v_add_f32_e32 v140, v140, v52
	v_add_f32_e32 v141, v141, v53
	v_add_f32_e32 v142, v142, v54
	v_add_f32_e32 v143, v143, v55
	v_add_f32_e32 v140, v140, v48
	v_add_f32_e32 v141, v141, v49
	v_add_f32_e32 v142, v142, v50
	v_add_f32_e32 v143, v143, v51
	v_add_f32_e32 v140, v140, v44
	v_add_f32_e32 v141, v141, v45
	v_add_f32_e32 v142, v142, v46
	v_add_f32_e32 v143, v143, v47
	v_add_f32_e32 v140, v140, v40
	v_add_f32_e32 v141, v141, v41
	v_add_f32_e32 v142, v142, v42
	v_add_f32_e32 v143, v143, v43
	v_mul_f32_e32 v140, 0x3e000000, v140
	v_mul_f32_e32 v141, 0x3e000000, v141
	v_mul_f32_e32 v142, 0x3e000000, v142
	v_mul_f32_e32 v143, 0x3e000000, v143
	v_sub_f32_e32 v140, v140, v68
	v_sub_f32_e32 v141, v141, v69
	v_sub_f32_e32 v142, v142, v70
	v_sub_f32_e32 v143, v143, v71
	v_cvt_pk_bf16_f32 v144, v140, v141
	v_cvt_pk_bf16_f32 v145, v142, v143
	global_store_dwordx2 v11, v[144:145], s[24:25]
	s_add_u32 s24, s24, 0x800
	s_addc_u32 s25, s25, 0
	s_waitcnt vmcnt(1)
	v_and_b32_e32 v75, 0xffff0000, v73
	v_lshlrev_b32_e32 v74, 16, v73
	v_and_b32_e32 v73, 0xffff0000, v72
	v_lshlrev_b32_e32 v72, 16, v72
	v_add_f32_e32 v140, v72, v68
	v_add_f32_e32 v141, v73, v69
	v_add_f32_e32 v142, v74, v70
	v_add_f32_e32 v143, v75, v71
	v_add_f32_e32 v140, v140, v64
	v_add_f32_e32 v141, v141, v65
	v_add_f32_e32 v142, v142, v66
	v_add_f32_e32 v143, v143, v67
	v_add_f32_e32 v140, v140, v60
	v_add_f32_e32 v141, v141, v61
	v_add_f32_e32 v142, v142, v62
	v_add_f32_e32 v143, v143, v63
	v_add_f32_e32 v140, v140, v56
	v_add_f32_e32 v141, v141, v57
	v_add_f32_e32 v142, v142, v58
	v_add_f32_e32 v143, v143, v59
	v_add_f32_e32 v140, v140, v52
	v_add_f32_e32 v141, v141, v53
	v_add_f32_e32 v142, v142, v54
	v_add_f32_e32 v143, v143, v55
	v_add_f32_e32 v140, v140, v48
	v_add_f32_e32 v141, v141, v49
	v_add_f32_e32 v142, v142, v50
	v_add_f32_e32 v143, v143, v51
	v_add_f32_e32 v140, v140, v44
	v_add_f32_e32 v141, v141, v45
	v_add_f32_e32 v142, v142, v46
	v_add_f32_e32 v143, v143, v47
	v_mul_f32_e32 v140, 0x3e000000, v140
	v_mul_f32_e32 v141, 0x3e000000, v141
	v_mul_f32_e32 v142, 0x3e000000, v142
	v_mul_f32_e32 v143, 0x3e000000, v143
	v_sub_f32_e32 v140, v140, v72
	v_sub_f32_e32 v141, v141, v73
	v_sub_f32_e32 v142, v142, v74
	v_sub_f32_e32 v143, v143, v75
	v_cvt_pk_bf16_f32 v144, v140, v141
	v_cvt_pk_bf16_f32 v145, v142, v143
	global_store_dwordx2 v11, v[144:145], s[24:25]
	s_add_u32 s24, s24, 0x800
	s_addc_u32 s25, s25, 0
	s_waitcnt vmcnt(0)
	v_and_b32_e32 v79, 0xffff0000, v77
	v_lshlrev_b32_e32 v78, 16, v77
	v_and_b32_e32 v77, 0xffff0000, v76
	v_lshlrev_b32_e32 v76, 16, v76
	v_add_f32_e32 v140, v76, v72
	v_add_f32_e32 v141, v77, v73
	v_add_f32_e32 v142, v78, v74
	v_add_f32_e32 v143, v79, v75
	v_add_f32_e32 v140, v140, v68
	v_add_f32_e32 v141, v141, v69
	v_add_f32_e32 v142, v142, v70
	v_add_f32_e32 v143, v143, v71
	v_add_f32_e32 v140, v140, v64
	v_add_f32_e32 v141, v141, v65
	v_add_f32_e32 v142, v142, v66
	v_add_f32_e32 v143, v143, v67
	v_add_f32_e32 v140, v140, v60
	v_add_f32_e32 v141, v141, v61
	v_add_f32_e32 v142, v142, v62
	v_add_f32_e32 v143, v143, v63
	v_add_f32_e32 v140, v140, v56
	v_add_f32_e32 v141, v141, v57
	v_add_f32_e32 v142, v142, v58
	v_add_f32_e32 v143, v143, v59
	v_add_f32_e32 v140, v140, v52
	v_add_f32_e32 v141, v141, v53
	v_add_f32_e32 v142, v142, v54
	v_add_f32_e32 v143, v143, v55
	v_add_f32_e32 v140, v140, v48
	v_add_f32_e32 v141, v141, v49
	v_add_f32_e32 v142, v142, v50
	v_add_f32_e32 v143, v143, v51
	v_mul_f32_e32 v140, 0x3e000000, v140
	v_mul_f32_e32 v141, 0x3e000000, v141
	v_mul_f32_e32 v142, 0x3e000000, v142
	v_mul_f32_e32 v143, 0x3e000000, v143
	v_sub_f32_e32 v140, v140, v76
	v_sub_f32_e32 v141, v141, v77
	v_sub_f32_e32 v142, v142, v78
	v_sub_f32_e32 v143, v143, v79
	v_cvt_pk_bf16_f32 v144, v140, v141
	v_cvt_pk_bf16_f32 v145, v142, v143
	global_store_dwordx2 v11, v[144:145], s[24:25]
	s_add_u32 s24, s24, 0x800
	s_addc_u32 s25, s25, 0
	s_branch .Lp13f_next
; DI float bflo(unsigned u) { return __uint_as_float(u << 16); }
; DI float bfhi(unsigned u) { return __uint_as_float(u & 0xffff0000u); }
; template <int WIN>
; DI void pool_elem(const Params& p, int row, int c) {
;     ...
;     } else {
;       cnt = (float)(t + 1);
;       for (int j = 1; j <= t; ++j) {
;         unsigned w = *(const unsigned*)(P2 + (size_t)(row - j) * 2048 + c);
;         s0 += bflo(w); s1 += bfhi(w);
;       }
;     ...
;   *(unsigned*)(p.MIX + (size_t)row * 1024 + c) = pack2(s0 / cnt - u0, s1 / cnt - u1);
.Lp13f_f3:
	s_sub_u32 s26, s20, 0
	s_lshl_b32 s27, s26, 12
	s_lshr_b32 s28, s26, 20
	s_add_u32 s22, s8, s27
	s_addc_u32 s23, s9, s28
	global_load_dwordx2 v[16:17], v11, s[22:23]
	s_add_u32 s22, s22, 0x1000
	s_addc_u32 s23, s23, 0
	global_load_dwordx2 v[20:21], v11, s[22:23]
	s_add_u32 s22, s22, 0x1000
	s_addc_u32 s23, s23, 0
	global_load_dwordx2 v[24:25], v11, s[22:23]
	s_add_u32 s22, s22, 0x1000
	s_addc_u32 s23, s23, 0
	global_load_dwordx2 v[28:29], v11, s[22:23]
	s_add_u32 s22, s22, 0x1000
	s_addc_u32 s23, s23, 0
	global_load_dwordx2 v[32:33], v11, s[22:23]
	s_add_u32 s22, s22, 0x1000
	s_addc_u32 s23, s23, 0
	global_load_dwordx2 v[36:37], v11, s[22:23]
	s_add_u32 s22, s22, 0x1000
	s_addc_u32 s23, s23, 0
	global_load_dwordx2 v[40:41], v11, s[22:23]
	s_add_u32 s22, s22, 0x1000
	s_addc_u32 s23, s23, 0
	global_load_dwordx2 v[44:45], v11, s[22:23]
	s_add_u32 s22, s22, 0x1000
	s_addc_u32 s23, s23, 0
	global_load_dwordx2 v[48:49], v11, s[22:23]
	s_add_u32 s22, s22, 0x1000
	s_addc_u32 s23, s23, 0
	global_load_dwordx2 v[52:53], v11, s[22:23]
	s_add_u32 s22, s22, 0x1000
	s_addc_u32 s23, s23, 0
	global_load_dwordx2 v[56:57], v11, s[22:23]
	s_add_u32 s22, s22, 0x1000
	s_addc_u32 s23, s23, 0
	global_load_dwordx2 v[60:61], v11, s[22:23]
	s_add_u32 s22, s22, 0x1000
	s_addc_u32 s23, s23, 0
	global_load_dwordx2 v[64:65], v11, s[22:23]
	s_add_u32 s22, s22, 0x1000
	s_addc_u32 s23, s23, 0
	global_load_dwordx2 v[68:69], v11, s[22:23]
	s_add_u32 s22, s22, 0x1000
	s_addc_u32 s23, s23, 0
	global_load_dwordx2 v[72:73], v11, s[22:23]
	s_add_u32 s22, s22, 0x1000
	s_addc_u32 s23, s23, 0
	global_load_dwordx2 v[76:77], v11, s[22:23]
	s_add_u32 s22, s22, 0x1000
	s_addc_u32 s23, s23, 0
	s_waitcnt vmcnt(15)
	v_and_b32_e32 v19, 0xffff0000, v17
	v_lshlrev_b32_e32 v18, 16, v17
	v_and_b32_e32 v17, 0xffff0000, v16
	v_lshlrev_b32_e32 v16, 16, v16
	v_mov_b32_e32 v140, v16
	v_mov_b32_e32 v141, v17
	v_mov_b32_e32 v142, v18
	v_mov_b32_e32 v143, v19
	v_mul_f32_e32 v140, 1.0, v140
	v_mul_f32_e32 v141, 1.0, v141
	v_mul_f32_e32 v142, 1.0, v142
	v_mul_f32_e32 v143, 1.0, v143
	v_sub_f32_e32 v140, v140, v16
	v_sub_f32_e32 v141, v141, v17
	v_sub_f32_e32 v142, v142, v18
	v_sub_f32_e32 v143, v143, v19
	v_cvt_pk_bf16_f32 v144, v140, v141
	v_cvt_pk_bf16_f32 v145, v142, v143
	global_store_dwordx2 v11, v[144:145], s[24:25]
	s_add_u32 s24, s24, 0x800
	s_addc_u32 s25, s25, 0
	s_waitcnt vmcnt(14)
	v_and_b32_e32 v23, 0xffff0000, v21
	v_lshlrev_b32_e32 v22, 16, v21
	v_and_b32_e32 v21, 0xffff0000, v20
	v_lshlrev_b32_e32 v20, 16, v20
	v_add_f32_e32 v140, v20, v16
	v_add_f32_e32 v141, v21, v17
	v_add_f32_e32 v142, v22, v18
	v_add_f32_e32 v143, v23, v19
	v_mul_f32_e32 v140, 0.5, v140
	v_mul_f32_e32 v141, 0.5, v141
	v_mul_f32_e32 v142, 0.5, v142
	v_mul_f32_e32 v143, 0.5, v143
	v_sub_f32_e32 v140, v140, v20
	v_sub_f32_e32 v141, v141, v21
	v_sub_f32_e32 v142, v142, v22
	v_sub_f32_e32 v143, v143, v23
	v_cvt_pk_bf16_f32 v144, v140, v141
	v_cvt_pk_bf16_f32 v145, v142, v143
	global_store_dwordx2 v11, v[144:145], s[24:25]
	s_add_u32 s24, s24, 0x800
	s_addc_u32 s25, s25, 0
	s_waitcnt vmcnt(13)
	v_and_b32_e32 v27, 0xffff0000, v25
	v_lshlrev_b32_e32 v26, 16, v25
	v_and_b32_e32 v25, 0xffff0000, v24
	v_lshlrev_b32_e32 v24, 16, v24
	v_add_f32_e32 v140, v24, v20
	v_add_f32_e32 v141, v25, v21
	v_add_f32_e32 v142, v26, v22
	v_add_f32_e32 v143, v27, v23
	v_add_f32_e32 v140, v140, v16
	v_add_f32_e32 v141, v141, v17
	v_add_f32_e32 v142, v142, v18
	v_add_f32_e32 v143, v143, v19
	v_mov_b32_e32 v151, 0x40400000
	v_div_scale_f32 v146, s[26:27], v151, v151, v140
	v_rcp_f32_e32 v147, v146
	v_div_scale_f32 v148, vcc, v140, v151, v140
	v_fma_f32 v149, -v146, v147, 1.0
	v_fmac_f32_e32 v147, v149, v147
	v_mul_f32_e32 v149, v148, v147
	v_fma_f32 v150, -v146, v149, v148
	v_fmac_f32_e32 v149, v150, v147
	v_fma_f32 v146, -v146, v149, v148
	v_div_fmas_f32 v146, v146, v147, v149
	v_div_fixup_f32 v140, v146, v151, v140
	v_mov_b32_e32 v151, 0x40400000
	v_div_scale_f32 v146, s[26:27], v151, v151, v141
	v_rcp_f32_e32 v147, v146
	v_div_scale_f32 v148, vcc, v141, v151, v141
	v_fma_f32 v149, -v146, v147, 1.0
	v_fmac_f32_e32 v147, v149, v147
	v_mul_f32_e32 v149, v148, v147
	v_fma_f32 v150, -v146, v149, v148
	v_fmac_f32_e32 v149, v150, v147
	v_fma_f32 v146, -v146, v149, v148
	v_div_fmas_f32 v146, v146, v147, v149
	v_div_fixup_f32 v141, v146, v151, v141
	v_mov_b32_e32 v151, 0x40400000
	v_div_scale_f32 v146, s[26:27], v151, v151, v142
	v_rcp_f32_e32 v147, v146
	v_div_scale_f32 v148, vcc, v142, v151, v142
	v_fma_f32 v149, -v146, v147, 1.0
	v_fmac_f32_e32 v147, v149, v147
	v_mul_f32_e32 v149, v148, v147
	v_fma_f32 v150, -v146, v149, v148
	v_fmac_f32_e32 v149, v150, v147
	v_fma_f32 v146, -v146, v149, v148
	v_div_fmas_f32 v146, v146, v147, v149
	v_div_fixup_f32 v142, v146, v151, v142
	v_mov_b32_e32 v151, 0x40400000
	v_div_scale_f32 v146, s[26:27], v151, v151, v143
	v_rcp_f32_e32 v147, v146
	v_div_scale_f32 v148, vcc, v143, v151, v143
	v_fma_f32 v149, -v146, v147, 1.0
	v_fmac_f32_e32 v147, v149, v147
	v_mul_f32_e32 v149, v148, v147
	v_fma_f32 v150, -v146, v149, v148
	v_fmac_f32_e32 v149, v150, v147
	v_fma_f32 v146, -v146, v149, v148
	v_div_fmas_f32 v146, v146, v147, v149
	v_div_fixup_f32 v143, v146, v151, v143
	v_sub_f32_e32 v140, v140, v24
	v_sub_f32_e32 v141, v141, v25
	v_sub_f32_e32 v142, v142, v26
	v_sub_f32_e32 v143, v143, v27
	v_cvt_pk_bf16_f32 v144, v140, v141
	v_cvt_pk_bf16_f32 v145, v142, v143
	global_store_dwordx2 v11, v[144:145], s[24:25]
	s_add_u32 s24, s24, 0x800
	s_addc_u32 s25, s25, 0
	s_waitcnt vmcnt(12)
; DI float bflo(unsigned u) { return __uint_as_float(u << 16); }
; DI float bfhi(unsigned u) { return __uint_as_float(u & 0xffff0000u); }
; template <int WIN>
; DI void pool_elem(const Params& p, int row, int c) {
;     ...
;     } else {
;       cnt = (float)(t + 1);
;       for (int j = 1; j <= t; ++j) {
;         unsigned w = *(const unsigned*)(P2 + (size_t)(row - j) * 2048 + c);
;         s0 += bflo(w); s1 += bfhi(w);
;       }
;     ...
;   *(unsigned*)(p.MIX + (size_t)row * 1024 + c) = pack2(s0 / cnt - u0, s1 / cnt - u1);
	v_and_b32_e32 v31, 0xffff0000, v29
	v_lshlrev_b32_e32 v30, 16, v29
	v_and_b32_e32 v29, 0xffff0000, v28
	v_lshlrev_b32_e32 v28, 16, v28
	v_add_f32_e32 v140, v28, v24
	v_add_f32_e32 v141, v29, v25
	v_add_f32_e32 v142, v30, v26
	v_add_f32_e32 v143, v31, v27
	v_add_f32_e32 v140, v140, v20
	v_add_f32_e32 v141, v141, v21
	v_add_f32_e32 v142, v142, v22
	v_add_f32_e32 v143, v143, v23
	v_add_f32_e32 v140, v140, v16
	v_add_f32_e32 v141, v141, v17
	v_add_f32_e32 v142, v142, v18
	v_add_f32_e32 v143, v143, v19
	v_mul_f32_e32 v140, 0x3e800000, v140
	v_mul_f32_e32 v141, 0x3e800000, v141
	v_mul_f32_e32 v142, 0x3e800000, v142
	v_mul_f32_e32 v143, 0x3e800000, v143
	v_sub_f32_e32 v140, v140, v28
	v_sub_f32_e32 v141, v141, v29
	v_sub_f32_e32 v142, v142, v30
	v_sub_f32_e32 v143, v143, v31
	v_cvt_pk_bf16_f32 v144, v140, v141
	v_cvt_pk_bf16_f32 v145, v142, v143
	global_store_dwordx2 v11, v[144:145], s[24:25]
	s_add_u32 s24, s24, 0x800
	s_addc_u32 s25, s25, 0
	s_waitcnt vmcnt(11)
	v_and_b32_e32 v35, 0xffff0000, v33
	v_lshlrev_b32_e32 v34, 16, v33
	v_and_b32_e32 v33, 0xffff0000, v32
	v_lshlrev_b32_e32 v32, 16, v32
	v_add_f32_e32 v140, v32, v28
	v_add_f32_e32 v141, v33, v29
	v_add_f32_e32 v142, v34, v30
	v_add_f32_e32 v143, v35, v31
	v_add_f32_e32 v140, v140, v24
	v_add_f32_e32 v141, v141, v25
	v_add_f32_e32 v142, v142, v26
	v_add_f32_e32 v143, v143, v27
	v_add_f32_e32 v140, v140, v20
	v_add_f32_e32 v141, v141, v21
	v_add_f32_e32 v142, v142, v22
	v_add_f32_e32 v143, v143, v23
	v_add_f32_e32 v140, v140, v16
	v_add_f32_e32 v141, v141, v17
	v_add_f32_e32 v142, v142, v18
	v_add_f32_e32 v143, v143, v19
	v_mov_b32_e32 v151, 0x40a00000
	v_div_scale_f32 v146, s[26:27], v151, v151, v140
	v_rcp_f32_e32 v147, v146
	v_div_scale_f32 v148, vcc, v140, v151, v140
	v_fma_f32 v149, -v146, v147, 1.0
	v_fmac_f32_e32 v147, v149, v147
	v_mul_f32_e32 v149, v148, v147
	v_fma_f32 v150, -v146, v149, v148
	v_fmac_f32_e32 v149, v150, v147
	v_fma_f32 v146, -v146, v149, v148
	v_div_fmas_f32 v146, v146, v147, v149
	v_div_fixup_f32 v140, v146, v151, v140
	v_mov_b32_e32 v151, 0x40a00000
	v_div_scale_f32 v146, s[26:27], v151, v151, v141
	v_rcp_f32_e32 v147, v146
	v_div_scale_f32 v148, vcc, v141, v151, v141
	v_fma_f32 v149, -v146, v147, 1.0
	v_fmac_f32_e32 v147, v149, v147
	v_mul_f32_e32 v149, v148, v147
	v_fma_f32 v150, -v146, v149, v148
	v_fmac_f32_e32 v149, v150, v147
	v_fma_f32 v146, -v146, v149, v148
	v_div_fmas_f32 v146, v146, v147, v149
	v_div_fixup_f32 v141, v146, v151, v141
	v_mov_b32_e32 v151, 0x40a00000
	v_div_scale_f32 v146, s[26:27], v151, v151, v142
	v_rcp_f32_e32 v147, v146
	v_div_scale_f32 v148, vcc, v142, v151, v142
	v_fma_f32 v149, -v146, v147, 1.0
	v_fmac_f32_e32 v147, v149, v147
	v_mul_f32_e32 v149, v148, v147
	v_fma_f32 v150, -v146, v149, v148
	v_fmac_f32_e32 v149, v150, v147
	v_fma_f32 v146, -v146, v149, v148
	v_div_fmas_f32 v146, v146, v147, v149
	v_div_fixup_f32 v142, v146, v151, v142
	v_mov_b32_e32 v151, 0x40a00000
	v_div_scale_f32 v146, s[26:27], v151, v151, v143
	v_rcp_f32_e32 v147, v146
	v_div_scale_f32 v148, vcc, v143, v151, v143
	v_fma_f32 v149, -v146, v147, 1.0
	v_fmac_f32_e32 v147, v149, v147
	v_mul_f32_e32 v149, v148, v147
	v_fma_f32 v150, -v146, v149, v148
	v_fmac_f32_e32 v149, v150, v147
	v_fma_f32 v146, -v146, v149, v148
	v_div_fmas_f32 v146, v146, v147, v149
	v_div_fixup_f32 v143, v146, v151, v143
	v_sub_f32_e32 v140, v140, v32
	v_sub_f32_e32 v141, v141, v33
	v_sub_f32_e32 v142, v142, v34
	v_sub_f32_e32 v143, v143, v35
	v_cvt_pk_bf16_f32 v144, v140, v141
	v_cvt_pk_bf16_f32 v145, v142, v143
	global_store_dwordx2 v11, v[144:145], s[24:25]
	s_add_u32 s24, s24, 0x800
	s_addc_u32 s25, s25, 0
	s_waitcnt vmcnt(10)
	v_and_b32_e32 v39, 0xffff0000, v37
	v_lshlrev_b32_e32 v38, 16, v37
	v_and_b32_e32 v37, 0xffff0000, v36
	v_lshlrev_b32_e32 v36, 16, v36
	v_add_f32_e32 v140, v36, v32
	v_add_f32_e32 v141, v37, v33
	v_add_f32_e32 v142, v38, v34
	v_add_f32_e32 v143, v39, v35
	v_add_f32_e32 v140, v140, v28
	v_add_f32_e32 v141, v141, v29
	v_add_f32_e32 v142, v142, v30
	v_add_f32_e32 v143, v143, v31
	v_add_f32_e32 v140, v140, v24
	v_add_f32_e32 v141, v141, v25
	v_add_f32_e32 v142, v142, v26
	v_add_f32_e32 v143, v143, v27
	v_add_f32_e32 v140, v140, v20
	v_add_f32_e32 v141, v141, v21
	v_add_f32_e32 v142, v142, v22
	v_add_f32_e32 v143, v143, v23
	v_add_f32_e32 v140, v140, v16
	v_add_f32_e32 v141, v141, v17
	v_add_f32_e32 v142, v142, v18
	v_add_f32_e32 v143, v143, v19
	v_mov_b32_e32 v151, 0x40c00000
	v_div_scale_f32 v146, s[26:27], v151, v151, v140
	v_rcp_f32_e32 v147, v146
	v_div_scale_f32 v148, vcc, v140, v151, v140
	v_fma_f32 v149, -v146, v147, 1.0
	v_fmac_f32_e32 v147, v149, v147
	v_mul_f32_e32 v149, v148, v147
	v_fma_f32 v150, -v146, v149, v148
	v_fmac_f32_e32 v149, v150, v147
	v_fma_f32 v146, -v146, v149, v148
	v_div_fmas_f32 v146, v146, v147, v149
	v_div_fixup_f32 v140, v146, v151, v140
	v_mov_b32_e32 v151, 0x40c00000
	v_div_scale_f32 v146, s[26:27], v151, v151, v141
	v_rcp_f32_e32 v147, v146
	v_div_scale_f32 v148, vcc, v141, v151, v141
	v_fma_f32 v149, -v146, v147, 1.0
	v_fmac_f32_e32 v147, v149, v147
	v_mul_f32_e32 v149, v148, v147
	v_fma_f32 v150, -v146, v149, v148
	v_fmac_f32_e32 v149, v150, v147
	v_fma_f32 v146, -v146, v149, v148
	v_div_fmas_f32 v146, v146, v147, v149
	v_div_fixup_f32 v141, v146, v151, v141
	v_mov_b32_e32 v151, 0x40c00000
	v_div_scale_f32 v146, s[26:27], v151, v151, v142
	v_rcp_f32_e32 v147, v146
	v_div_scale_f32 v148, vcc, v142, v151, v142
	v_fma_f32 v149, -v146, v147, 1.0
	v_fmac_f32_e32 v147, v149, v147
	v_mul_f32_e32 v149, v148, v147
	v_fma_f32 v150, -v146, v149, v148
	v_fmac_f32_e32 v149, v150, v147
	v_fma_f32 v146, -v146, v149, v148
	v_div_fmas_f32 v146, v146, v147, v149
	v_div_fixup_f32 v142, v146, v151, v142
	v_mov_b32_e32 v151, 0x40c00000
	v_div_scale_f32 v146, s[26:27], v151, v151, v143
	v_rcp_f32_e32 v147, v146
	v_div_scale_f32 v148, vcc, v143, v151, v143
	v_fma_f32 v149, -v146, v147, 1.0
	v_fmac_f32_e32 v147, v149, v147
	v_mul_f32_e32 v149, v148, v147
	v_fma_f32 v150, -v146, v149, v148
	v_fmac_f32_e32 v149, v150, v147
	v_fma_f32 v146, -v146, v149, v148
	v_div_fmas_f32 v146, v146, v147, v149
	v_div_fixup_f32 v143, v146, v151, v143
	v_sub_f32_e32 v140, v140, v36
	v_sub_f32_e32 v141, v141, v37
	v_sub_f32_e32 v142, v142, v38
	v_sub_f32_e32 v143, v143, v39
	v_cvt_pk_bf16_f32 v144, v140, v141
	v_cvt_pk_bf16_f32 v145, v142, v143
	global_store_dwordx2 v11, v[144:145], s[24:25]
	s_add_u32 s24, s24, 0x800
	s_addc_u32 s25, s25, 0
	s_waitcnt vmcnt(9)
; DI float bflo(unsigned u) { return __uint_as_float(u << 16); }
; DI float bfhi(unsigned u) { return __uint_as_float(u & 0xffff0000u); }
; template <int WIN>
; DI void pool_elem(const Params& p, int row, int c) {
;     ...
;     } else {
;       cnt = (float)(t + 1);
;       for (int j = 1; j <= t; ++j) {
;         unsigned w = *(const unsigned*)(P2 + (size_t)(row - j) * 2048 + c);
;         s0 += bflo(w); s1 += bfhi(w);
;       }
;     ...
;   *(unsigned*)(p.MIX + (size_t)row * 1024 + c) = pack2(s0 / cnt - u0, s1 / cnt - u1);
	v_and_b32_e32 v43, 0xffff0000, v41
	v_lshlrev_b32_e32 v42, 16, v41
	v_and_b32_e32 v41, 0xffff0000, v40
	v_lshlrev_b32_e32 v40, 16, v40
	v_add_f32_e32 v140, v40, v36
	v_add_f32_e32 v141, v41, v37
	v_add_f32_e32 v142, v42, v38
	v_add_f32_e32 v143, v43, v39
	v_add_f32_e32 v140, v140, v32
	v_add_f32_e32 v141, v141, v33
	v_add_f32_e32 v142, v142, v34
	v_add_f32_e32 v143, v143, v35
	v_add_f32_e32 v140, v140, v28
	v_add_f32_e32 v141, v141, v29
	v_add_f32_e32 v142, v142, v30
	v_add_f32_e32 v143, v143, v31
	v_add_f32_e32 v140, v140, v24
	v_add_f32_e32 v141, v141, v25
	v_add_f32_e32 v142, v142, v26
	v_add_f32_e32 v143, v143, v27
	v_add_f32_e32 v140, v140, v20
	v_add_f32_e32 v141, v141, v21
	v_add_f32_e32 v142, v142, v22
	v_add_f32_e32 v143, v143, v23
	v_add_f32_e32 v140, v140, v16
	v_add_f32_e32 v141, v141, v17
	v_add_f32_e32 v142, v142, v18
	v_add_f32_e32 v143, v143, v19
	v_mov_b32_e32 v151, 0x40e00000
	v_div_scale_f32 v146, s[26:27], v151, v151, v140
	v_rcp_f32_e32 v147, v146
	v_div_scale_f32 v148, vcc, v140, v151, v140
	v_fma_f32 v149, -v146, v147, 1.0
	v_fmac_f32_e32 v147, v149, v147
	v_mul_f32_e32 v149, v148, v147
	v_fma_f32 v150, -v146, v149, v148
	v_fmac_f32_e32 v149, v150, v147
	v_fma_f32 v146, -v146, v149, v148
	v_div_fmas_f32 v146, v146, v147, v149
	v_div_fixup_f32 v140, v146, v151, v140
	v_mov_b32_e32 v151, 0x40e00000
	v_div_scale_f32 v146, s[26:27], v151, v151, v141
	v_rcp_f32_e32 v147, v146
	v_div_scale_f32 v148, vcc, v141, v151, v141
	v_fma_f32 v149, -v146, v147, 1.0
	v_fmac_f32_e32 v147, v149, v147
	v_mul_f32_e32 v149, v148, v147
	v_fma_f32 v150, -v146, v149, v148
	v_fmac_f32_e32 v149, v150, v147
	v_fma_f32 v146, -v146, v149, v148
	v_div_fmas_f32 v146, v146, v147, v149
	v_div_fixup_f32 v141, v146, v151, v141
	v_mov_b32_e32 v151, 0x40e00000
	v_div_scale_f32 v146, s[26:27], v151, v151, v142
	v_rcp_f32_e32 v147, v146
	v_div_scale_f32 v148, vcc, v142, v151, v142
	v_fma_f32 v149, -v146, v147, 1.0
	v_fmac_f32_e32 v147, v149, v147
	v_mul_f32_e32 v149, v148, v147
	v_fma_f32 v150, -v146, v149, v148
	v_fmac_f32_e32 v149, v150, v147
	v_fma_f32 v146, -v146, v149, v148
	v_div_fmas_f32 v146, v146, v147, v149
	v_div_fixup_f32 v142, v146, v151, v142
	v_mov_b32_e32 v151, 0x40e00000
	v_div_scale_f32 v146, s[26:27], v151, v151, v143
	v_rcp_f32_e32 v147, v146
	v_div_scale_f32 v148, vcc, v143, v151, v143
	v_fma_f32 v149, -v146, v147, 1.0
	v_fmac_f32_e32 v147, v149, v147
	v_mul_f32_e32 v149, v148, v147
	v_fma_f32 v150, -v146, v149, v148
	v_fmac_f32_e32 v149, v150, v147
	v_fma_f32 v146, -v146, v149, v148
	v_div_fmas_f32 v146, v146, v147, v149
	v_div_fixup_f32 v143, v146, v151, v143
	v_sub_f32_e32 v140, v140, v40
	v_sub_f32_e32 v141, v141, v41
	v_sub_f32_e32 v142, v142, v42
	v_sub_f32_e32 v143, v143, v43
	v_cvt_pk_bf16_f32 v144, v140, v141
	v_cvt_pk_bf16_f32 v145, v142, v143
	global_store_dwordx2 v11, v[144:145], s[24:25]
	s_add_u32 s24, s24, 0x800
	s_addc_u32 s25, s25, 0
	s_waitcnt vmcnt(8)
	v_and_b32_e32 v47, 0xffff0000, v45
	v_lshlrev_b32_e32 v46, 16, v45
	v_and_b32_e32 v45, 0xffff0000, v44
	v_lshlrev_b32_e32 v44, 16, v44
	v_add_f32_e32 v140, v44, v40
	v_add_f32_e32 v141, v45, v41
	v_add_f32_e32 v142, v46, v42
	v_add_f32_e32 v143, v47, v43
	v_add_f32_e32 v140, v140, v36
	v_add_f32_e32 v141, v141, v37
	v_add_f32_e32 v142, v142, v38
	v_add_f32_e32 v143, v143, v39
	v_add_f32_e32 v140, v140, v32
	v_add_f32_e32 v141, v141, v33
	v_add_f32_e32 v142, v142, v34
	v_add_f32_e32 v143, v143, v35
	v_add_f32_e32 v140, v140, v28
	v_add_f32_e32 v141, v141, v29
	v_add_f32_e32 v142, v142, v30
	v_add_f32_e32 v143, v143, v31
	v_add_f32_e32 v140, v140, v24
	v_add_f32_e32 v141, v141, v25
	v_add_f32_e32 v142, v142, v26
	v_add_f32_e32 v143, v143, v27
	v_add_f32_e32 v140, v140, v20
	v_add_f32_e32 v141, v141, v21
	v_add_f32_e32 v142, v142, v22
	v_add_f32_e32 v143, v143, v23
	v_add_f32_e32 v140, v140, v16
	v_add_f32_e32 v141, v141, v17
	v_add_f32_e32 v142, v142, v18
	v_add_f32_e32 v143, v143, v19
	v_mul_f32_e32 v140, 0x3e000000, v140
	v_mul_f32_e32 v141, 0x3e000000, v141
	v_mul_f32_e32 v142, 0x3e000000, v142
	v_mul_f32_e32 v143, 0x3e000000, v143
	v_sub_f32_e32 v140, v140, v44
	v_sub_f32_e32 v141, v141, v45
	v_sub_f32_e32 v142, v142, v46
	v_sub_f32_e32 v143, v143, v47
	v_cvt_pk_bf16_f32 v144, v140, v141
	v_cvt_pk_bf16_f32 v145, v142, v143
	global_store_dwordx2 v11, v[144:145], s[24:25]
	s_add_u32 s24, s24, 0x800
	s_addc_u32 s25, s25, 0
	s_waitcnt vmcnt(7)
; DI float bflo(unsigned u) { return __uint_as_float(u << 16); }
; DI float bfhi(unsigned u) { return __uint_as_float(u & 0xffff0000u); }
; template <int WIN>
; DI void pool_elem(const Params& p, int row, int c) {
;     ...
;     } else {
;       cnt = (float)(t + 1);
;       for (int j = 1; j <= t; ++j) {
;         unsigned w = *(const unsigned*)(P2 + (size_t)(row - j) * 2048 + c);
;         s0 += bflo(w); s1 += bfhi(w);
;       }
;     ...
;   *(unsigned*)(p.MIX + (size_t)row * 1024 + c) = pack2(s0 / cnt - u0, s1 / cnt - u1);
	v_and_b32_e32 v51, 0xffff0000, v49
	v_lshlrev_b32_e32 v50, 16, v49
	v_and_b32_e32 v49, 0xffff0000, v48
	v_lshlrev_b32_e32 v48, 16, v48
	v_add_f32_e32 v140, v48, v44
	v_add_f32_e32 v141, v49, v45
	v_add_f32_e32 v142, v50, v46
	v_add_f32_e32 v143, v51, v47
	v_add_f32_e32 v140, v140, v40
	v_add_f32_e32 v141, v141, v41
	v_add_f32_e32 v142, v142, v42
	v_add_f32_e32 v143, v143, v43
	v_add_f32_e32 v140, v140, v36
	v_add_f32_e32 v141, v141, v37
	v_add_f32_e32 v142, v142, v38
	v_add_f32_e32 v143, v143, v39
	v_add_f32_e32 v140, v140, v32
	v_add_f32_e32 v141, v141, v33
	v_add_f32_e32 v142, v142, v34
	v_add_f32_e32 v143, v143, v35
	v_add_f32_e32 v140, v140, v28
	v_add_f32_e32 v141, v141, v29
	v_add_f32_e32 v142, v142, v30
	v_add_f32_e32 v143, v143, v31
	v_add_f32_e32 v140, v140, v24
	v_add_f32_e32 v141, v141, v25
	v_add_f32_e32 v142, v142, v26
	v_add_f32_e32 v143, v143, v27
	v_add_f32_e32 v140, v140, v20
	v_add_f32_e32 v141, v141, v21
	v_add_f32_e32 v142, v142, v22
	v_add_f32_e32 v143, v143, v23
	v_add_f32_e32 v140, v140, v16
	v_add_f32_e32 v141, v141, v17
	v_add_f32_e32 v142, v142, v18
	v_add_f32_e32 v143, v143, v19
	v_mov_b32_e32 v151, 0x41100000
	v_div_scale_f32 v146, s[26:27], v151, v151, v140
	v_rcp_f32_e32 v147, v146
	v_div_scale_f32 v148, vcc, v140, v151, v140
	v_fma_f32 v149, -v146, v147, 1.0
	v_fmac_f32_e32 v147, v149, v147
	v_mul_f32_e32 v149, v148, v147
	v_fma_f32 v150, -v146, v149, v148
	v_fmac_f32_e32 v149, v150, v147
	v_fma_f32 v146, -v146, v149, v148
	v_div_fmas_f32 v146, v146, v147, v149
	v_div_fixup_f32 v140, v146, v151, v140
	v_mov_b32_e32 v151, 0x41100000
	v_div_scale_f32 v146, s[26:27], v151, v151, v141
	v_rcp_f32_e32 v147, v146
	v_div_scale_f32 v148, vcc, v141, v151, v141
	v_fma_f32 v149, -v146, v147, 1.0
	v_fmac_f32_e32 v147, v149, v147
	v_mul_f32_e32 v149, v148, v147
	v_fma_f32 v150, -v146, v149, v148
	v_fmac_f32_e32 v149, v150, v147
	v_fma_f32 v146, -v146, v149, v148
	v_div_fmas_f32 v146, v146, v147, v149
	v_div_fixup_f32 v141, v146, v151, v141
	v_mov_b32_e32 v151, 0x41100000
	v_div_scale_f32 v146, s[26:27], v151, v151, v142
	v_rcp_f32_e32 v147, v146
	v_div_scale_f32 v148, vcc, v142, v151, v142
	v_fma_f32 v149, -v146, v147, 1.0
	v_fmac_f32_e32 v147, v149, v147
	v_mul_f32_e32 v149, v148, v147
	v_fma_f32 v150, -v146, v149, v148
	v_fmac_f32_e32 v149, v150, v147
	v_fma_f32 v146, -v146, v149, v148
	v_div_fmas_f32 v146, v146, v147, v149
	v_div_fixup_f32 v142, v146, v151, v142
	v_mov_b32_e32 v151, 0x41100000
	v_div_scale_f32 v146, s[26:27], v151, v151, v143
	v_rcp_f32_e32 v147, v146
	v_div_scale_f32 v148, vcc, v143, v151, v143
	v_fma_f32 v149, -v146, v147, 1.0
	v_fmac_f32_e32 v147, v149, v147
	v_mul_f32_e32 v149, v148, v147
	v_fma_f32 v150, -v146, v149, v148
	v_fmac_f32_e32 v149, v150, v147
	v_fma_f32 v146, -v146, v149, v148
	v_div_fmas_f32 v146, v146, v147, v149
	v_div_fixup_f32 v143, v146, v151, v143
	v_sub_f32_e32 v140, v140, v48
	v_sub_f32_e32 v141, v141, v49
	v_sub_f32_e32 v142, v142, v50
	v_sub_f32_e32 v143, v143, v51
	v_cvt_pk_bf16_f32 v144, v140, v141
	v_cvt_pk_bf16_f32 v145, v142, v143
	global_store_dwordx2 v11, v[144:145], s[24:25]
	s_add_u32 s24, s24, 0x800
	s_addc_u32 s25, s25, 0
	s_waitcnt vmcnt(6)
	v_and_b32_e32 v55, 0xffff0000, v53
	v_lshlrev_b32_e32 v54, 16, v53
	v_and_b32_e32 v53, 0xffff0000, v52
	v_lshlrev_b32_e32 v52, 16, v52
	v_add_f32_e32 v140, v52, v48
	v_add_f32_e32 v141, v53, v49
	v_add_f32_e32 v142, v54, v50
	v_add_f32_e32 v143, v55, v51
	v_add_f32_e32 v140, v140, v44
	v_add_f32_e32 v141, v141, v45
	v_add_f32_e32 v142, v142, v46
	v_add_f32_e32 v143, v143, v47
	v_add_f32_e32 v140, v140, v40
	v_add_f32_e32 v141, v141, v41
	v_add_f32_e32 v142, v142, v42
	v_add_f32_e32 v143, v143, v43
	v_add_f32_e32 v140, v140, v36
	v_add_f32_e32 v141, v141, v37
	v_add_f32_e32 v142, v142, v38
	v_add_f32_e32 v143, v143, v39
	v_add_f32_e32 v140, v140, v32
	v_add_f32_e32 v141, v141, v33
	v_add_f32_e32 v142, v142, v34
	v_add_f32_e32 v143, v143, v35
	v_add_f32_e32 v140, v140, v28
	v_add_f32_e32 v141, v141, v29
	v_add_f32_e32 v142, v142, v30
	v_add_f32_e32 v143, v143, v31
	v_add_f32_e32 v140, v140, v24
	v_add_f32_e32 v141, v141, v25
	v_add_f32_e32 v142, v142, v26
	v_add_f32_e32 v143, v143, v27
	v_add_f32_e32 v140, v140, v20
	v_add_f32_e32 v141, v141, v21
	v_add_f32_e32 v142, v142, v22
	v_add_f32_e32 v143, v143, v23
	v_add_f32_e32 v140, v140, v16
	v_add_f32_e32 v141, v141, v17
	v_add_f32_e32 v142, v142, v18
	v_add_f32_e32 v143, v143, v19
	v_mov_b32_e32 v151, 0x41200000
	v_div_scale_f32 v146, s[26:27], v151, v151, v140
	v_rcp_f32_e32 v147, v146
	v_div_scale_f32 v148, vcc, v140, v151, v140
	v_fma_f32 v149, -v146, v147, 1.0
	v_fmac_f32_e32 v147, v149, v147
	v_mul_f32_e32 v149, v148, v147
	v_fma_f32 v150, -v146, v149, v148
	v_fmac_f32_e32 v149, v150, v147
	v_fma_f32 v146, -v146, v149, v148
	v_div_fmas_f32 v146, v146, v147, v149
	v_div_fixup_f32 v140, v146, v151, v140
	v_mov_b32_e32 v151, 0x41200000
	v_div_scale_f32 v146, s[26:27], v151, v151, v141
	v_rcp_f32_e32 v147, v146
	v_div_scale_f32 v148, vcc, v141, v151, v141
	v_fma_f32 v149, -v146, v147, 1.0
	v_fmac_f32_e32 v147, v149, v147
	v_mul_f32_e32 v149, v148, v147
	v_fma_f32 v150, -v146, v149, v148
	v_fmac_f32_e32 v149, v150, v147
	v_fma_f32 v146, -v146, v149, v148
	v_div_fmas_f32 v146, v146, v147, v149
	v_div_fixup_f32 v141, v146, v151, v141
	v_mov_b32_e32 v151, 0x41200000
	v_div_scale_f32 v146, s[26:27], v151, v151, v142
	v_rcp_f32_e32 v147, v146
	v_div_scale_f32 v148, vcc, v142, v151, v142
	v_fma_f32 v149, -v146, v147, 1.0
	v_fmac_f32_e32 v147, v149, v147
	v_mul_f32_e32 v149, v148, v147
	v_fma_f32 v150, -v146, v149, v148
	v_fmac_f32_e32 v149, v150, v147
	v_fma_f32 v146, -v146, v149, v148
	v_div_fmas_f32 v146, v146, v147, v149
	v_div_fixup_f32 v142, v146, v151, v142
	v_mov_b32_e32 v151, 0x41200000
	v_div_scale_f32 v146, s[26:27], v151, v151, v143
	v_rcp_f32_e32 v147, v146
	v_div_scale_f32 v148, vcc, v143, v151, v143
	v_fma_f32 v149, -v146, v147, 1.0
	v_fmac_f32_e32 v147, v149, v147
	v_mul_f32_e32 v149, v148, v147
	v_fma_f32 v150, -v146, v149, v148
	v_fmac_f32_e32 v149, v150, v147
	v_fma_f32 v146, -v146, v149, v148
	v_div_fmas_f32 v146, v146, v147, v149
	v_div_fixup_f32 v143, v146, v151, v143
	v_sub_f32_e32 v140, v140, v52
	v_sub_f32_e32 v141, v141, v53
	v_sub_f32_e32 v142, v142, v54
	v_sub_f32_e32 v143, v143, v55
	v_cvt_pk_bf16_f32 v144, v140, v141
	v_cvt_pk_bf16_f32 v145, v142, v143
	global_store_dwordx2 v11, v[144:145], s[24:25]
	s_add_u32 s24, s24, 0x800
	s_addc_u32 s25, s25, 0
	s_waitcnt vmcnt(5)
; DI float bflo(unsigned u) { return __uint_as_float(u << 16); }
; DI float bfhi(unsigned u) { return __uint_as_float(u & 0xffff0000u); }
; template <int WIN>
; DI void pool_elem(const Params& p, int row, int c) {
;     ...
;     } else {
;       cnt = (float)(t + 1);
;       for (int j = 1; j <= t; ++j) {
;         unsigned w = *(const unsigned*)(P2 + (size_t)(row - j) * 2048 + c);
;         s0 += bflo(w); s1 += bfhi(w);
;       }
;     ...
;   *(unsigned*)(p.MIX + (size_t)row * 1024 + c) = pack2(s0 / cnt - u0, s1 / cnt - u1);
	v_and_b32_e32 v59, 0xffff0000, v57
	v_lshlrev_b32_e32 v58, 16, v57
	v_and_b32_e32 v57, 0xffff0000, v56
	v_lshlrev_b32_e32 v56, 16, v56
	v_add_f32_e32 v140, v56, v52
	v_add_f32_e32 v141, v57, v53
	v_add_f32_e32 v142, v58, v54
	v_add_f32_e32 v143, v59, v55
	v_add_f32_e32 v140, v140, v48
	v_add_f32_e32 v141, v141, v49
	v_add_f32_e32 v142, v142, v50
	v_add_f32_e32 v143, v143, v51
	v_add_f32_e32 v140, v140, v44
	v_add_f32_e32 v141, v141, v45
	v_add_f32_e32 v142, v142, v46
	v_add_f32_e32 v143, v143, v47
	v_add_f32_e32 v140, v140, v40
	v_add_f32_e32 v141, v141, v41
	v_add_f32_e32 v142, v142, v42
	v_add_f32_e32 v143, v143, v43
	v_add_f32_e32 v140, v140, v36
	v_add_f32_e32 v141, v141, v37
	v_add_f32_e32 v142, v142, v38
	v_add_f32_e32 v143, v143, v39
	v_add_f32_e32 v140, v140, v32
	v_add_f32_e32 v141, v141, v33
	v_add_f32_e32 v142, v142, v34
	v_add_f32_e32 v143, v143, v35
	v_add_f32_e32 v140, v140, v28
	v_add_f32_e32 v141, v141, v29
	v_add_f32_e32 v142, v142, v30
	v_add_f32_e32 v143, v143, v31
	v_add_f32_e32 v140, v140, v24
	v_add_f32_e32 v141, v141, v25
	v_add_f32_e32 v142, v142, v26
	v_add_f32_e32 v143, v143, v27
	v_add_f32_e32 v140, v140, v20
	v_add_f32_e32 v141, v141, v21
	v_add_f32_e32 v142, v142, v22
	v_add_f32_e32 v143, v143, v23
	v_add_f32_e32 v140, v140, v16
	v_add_f32_e32 v141, v141, v17
	v_add_f32_e32 v142, v142, v18
	v_add_f32_e32 v143, v143, v19
	v_mov_b32_e32 v151, 0x41300000
	v_div_scale_f32 v146, s[26:27], v151, v151, v140
	v_rcp_f32_e32 v147, v146
	v_div_scale_f32 v148, vcc, v140, v151, v140
	v_fma_f32 v149, -v146, v147, 1.0
	v_fmac_f32_e32 v147, v149, v147
	v_mul_f32_e32 v149, v148, v147
	v_fma_f32 v150, -v146, v149, v148
	v_fmac_f32_e32 v149, v150, v147
	v_fma_f32 v146, -v146, v149, v148
	v_div_fmas_f32 v146, v146, v147, v149
	v_div_fixup_f32 v140, v146, v151, v140
	v_mov_b32_e32 v151, 0x41300000
	v_div_scale_f32 v146, s[26:27], v151, v151, v141
	v_rcp_f32_e32 v147, v146
	v_div_scale_f32 v148, vcc, v141, v151, v141
	v_fma_f32 v149, -v146, v147, 1.0
	v_fmac_f32_e32 v147, v149, v147
	v_mul_f32_e32 v149, v148, v147
	v_fma_f32 v150, -v146, v149, v148
	v_fmac_f32_e32 v149, v150, v147
	v_fma_f32 v146, -v146, v149, v148
	v_div_fmas_f32 v146, v146, v147, v149
	v_div_fixup_f32 v141, v146, v151, v141
	v_mov_b32_e32 v151, 0x41300000
	v_div_scale_f32 v146, s[26:27], v151, v151, v142
	v_rcp_f32_e32 v147, v146
	v_div_scale_f32 v148, vcc, v142, v151, v142
	v_fma_f32 v149, -v146, v147, 1.0
	v_fmac_f32_e32 v147, v149, v147
	v_mul_f32_e32 v149, v148, v147
	v_fma_f32 v150, -v146, v149, v148
	v_fmac_f32_e32 v149, v150, v147
	v_fma_f32 v146, -v146, v149, v148
	v_div_fmas_f32 v146, v146, v147, v149
	v_div_fixup_f32 v142, v146, v151, v142
	v_mov_b32_e32 v151, 0x41300000
	v_div_scale_f32 v146, s[26:27], v151, v151, v143
	v_rcp_f32_e32 v147, v146
	v_div_scale_f32 v148, vcc, v143, v151, v143
	v_fma_f32 v149, -v146, v147, 1.0
	v_fmac_f32_e32 v147, v149, v147
	v_mul_f32_e32 v149, v148, v147
	v_fma_f32 v150, -v146, v149, v148
	v_fmac_f32_e32 v149, v150, v147
	v_fma_f32 v146, -v146, v149, v148
	v_div_fmas_f32 v146, v146, v147, v149
	v_div_fixup_f32 v143, v146, v151, v143
	v_sub_f32_e32 v140, v140, v56
	v_sub_f32_e32 v141, v141, v57
	v_sub_f32_e32 v142, v142, v58
	v_sub_f32_e32 v143, v143, v59
	v_cvt_pk_bf16_f32 v144, v140, v141
	v_cvt_pk_bf16_f32 v145, v142, v143
	global_store_dwordx2 v11, v[144:145], s[24:25]
	s_add_u32 s24, s24, 0x800
	s_addc_u32 s25, s25, 0
	s_waitcnt vmcnt(4)
	v_and_b32_e32 v63, 0xffff0000, v61
	v_lshlrev_b32_e32 v62, 16, v61
	v_and_b32_e32 v61, 0xffff0000, v60
	v_lshlrev_b32_e32 v60, 16, v60
	v_add_f32_e32 v140, v60, v56
	v_add_f32_e32 v141, v61, v57
	v_add_f32_e32 v142, v62, v58
	v_add_f32_e32 v143, v63, v59
	v_add_f32_e32 v140, v140, v52
	v_add_f32_e32 v141, v141, v53
	v_add_f32_e32 v142, v142, v54
	v_add_f32_e32 v143, v143, v55
	v_add_f32_e32 v140, v140, v48
	v_add_f32_e32 v141, v141, v49
	v_add_f32_e32 v142, v142, v50
	v_add_f32_e32 v143, v143, v51
	v_add_f32_e32 v140, v140, v44
	v_add_f32_e32 v141, v141, v45
	v_add_f32_e32 v142, v142, v46
	v_add_f32_e32 v143, v143, v47
	v_add_f32_e32 v140, v140, v40
	v_add_f32_e32 v141, v141, v41
	v_add_f32_e32 v142, v142, v42
	v_add_f32_e32 v143, v143, v43
	v_add_f32_e32 v140, v140, v36
	v_add_f32_e32 v141, v141, v37
	v_add_f32_e32 v142, v142, v38
	v_add_f32_e32 v143, v143, v39
	v_add_f32_e32 v140, v140, v32
	v_add_f32_e32 v141, v141, v33
	v_add_f32_e32 v142, v142, v34
	v_add_f32_e32 v143, v143, v35
	v_add_f32_e32 v140, v140, v28
	v_add_f32_e32 v141, v141, v29
	v_add_f32_e32 v142, v142, v30
	v_add_f32_e32 v143, v143, v31
	v_add_f32_e32 v140, v140, v24
	v_add_f32_e32 v141, v141, v25
	v_add_f32_e32 v142, v142, v26
	v_add_f32_e32 v143, v143, v27
	v_add_f32_e32 v140, v140, v20
	v_add_f32_e32 v141, v141, v21
	v_add_f32_e32 v142, v142, v22
	v_add_f32_e32 v143, v143, v23
	v_add_f32_e32 v140, v140, v16
	v_add_f32_e32 v141, v141, v17
	v_add_f32_e32 v142, v142, v18
	v_add_f32_e32 v143, v143, v19
	v_mov_b32_e32 v151, 0x41400000
	v_div_scale_f32 v146, s[26:27], v151, v151, v140
	v_rcp_f32_e32 v147, v146
	v_div_scale_f32 v148, vcc, v140, v151, v140
	v_fma_f32 v149, -v146, v147, 1.0
	v_fmac_f32_e32 v147, v149, v147
	v_mul_f32_e32 v149, v148, v147
	v_fma_f32 v150, -v146, v149, v148
	v_fmac_f32_e32 v149, v150, v147
	v_fma_f32 v146, -v146, v149, v148
	v_div_fmas_f32 v146, v146, v147, v149
	v_div_fixup_f32 v140, v146, v151, v140
	v_mov_b32_e32 v151, 0x41400000
	v_div_scale_f32 v146, s[26:27], v151, v151, v141
	v_rcp_f32_e32 v147, v146
	v_div_scale_f32 v148, vcc, v141, v151, v141
	v_fma_f32 v149, -v146, v147, 1.0
	v_fmac_f32_e32 v147, v149, v147
	v_mul_f32_e32 v149, v148, v147
	v_fma_f32 v150, -v146, v149, v148
	v_fmac_f32_e32 v149, v150, v147
	v_fma_f32 v146, -v146, v149, v148
	v_div_fmas_f32 v146, v146, v147, v149
	v_div_fixup_f32 v141, v146, v151, v141
	v_mov_b32_e32 v151, 0x41400000
	v_div_scale_f32 v146, s[26:27], v151, v151, v142
	v_rcp_f32_e32 v147, v146
	v_div_scale_f32 v148, vcc, v142, v151, v142
	v_fma_f32 v149, -v146, v147, 1.0
	v_fmac_f32_e32 v147, v149, v147
	v_mul_f32_e32 v149, v148, v147
	v_fma_f32 v150, -v146, v149, v148
	v_fmac_f32_e32 v149, v150, v147
	v_fma_f32 v146, -v146, v149, v148
	v_div_fmas_f32 v146, v146, v147, v149
	v_div_fixup_f32 v142, v146, v151, v142
	v_mov_b32_e32 v151, 0x41400000
	v_div_scale_f32 v146, s[26:27], v151, v151, v143
	v_rcp_f32_e32 v147, v146
	v_div_scale_f32 v148, vcc, v143, v151, v143
	v_fma_f32 v149, -v146, v147, 1.0
	v_fmac_f32_e32 v147, v149, v147
	v_mul_f32_e32 v149, v148, v147
	v_fma_f32 v150, -v146, v149, v148
	v_fmac_f32_e32 v149, v150, v147
	v_fma_f32 v146, -v146, v149, v148
	v_div_fmas_f32 v146, v146, v147, v149
	v_div_fixup_f32 v143, v146, v151, v143
	v_sub_f32_e32 v140, v140, v60
	v_sub_f32_e32 v141, v141, v61
	v_sub_f32_e32 v142, v142, v62
	v_sub_f32_e32 v143, v143, v63
	v_cvt_pk_bf16_f32 v144, v140, v141
	v_cvt_pk_bf16_f32 v145, v142, v143
	global_store_dwordx2 v11, v[144:145], s[24:25]
	s_add_u32 s24, s24, 0x800
	s_addc_u32 s25, s25, 0
	s_waitcnt vmcnt(3)
; DI float bflo(unsigned u) { return __uint_as_float(u << 16); }
; DI float bfhi(unsigned u) { return __uint_as_float(u & 0xffff0000u); }
; template <int WIN>
; DI void pool_elem(const Params& p, int row, int c) {
;     ...
;     } else {
;       cnt = (float)(t + 1);
;       for (int j = 1; j <= t; ++j) {
;         unsigned w = *(const unsigned*)(P2 + (size_t)(row - j) * 2048 + c);
;         s0 += bflo(w); s1 += bfhi(w);
;       }
;     ...
;   *(unsigned*)(p.MIX + (size_t)row * 1024 + c) = pack2(s0 / cnt - u0, s1 / cnt - u1);
	v_and_b32_e32 v67, 0xffff0000, v65
	v_lshlrev_b32_e32 v66, 16, v65
	v_and_b32_e32 v65, 0xffff0000, v64
	v_lshlrev_b32_e32 v64, 16, v64
	v_add_f32_e32 v140, v64, v60
	v_add_f32_e32 v141, v65, v61
	v_add_f32_e32 v142, v66, v62
	v_add_f32_e32 v143, v67, v63
	v_add_f32_e32 v140, v140, v56
	v_add_f32_e32 v141, v141, v57
	v_add_f32_e32 v142, v142, v58
	v_add_f32_e32 v143, v143, v59
	v_add_f32_e32 v140, v140, v52
	v_add_f32_e32 v141, v141, v53
	v_add_f32_e32 v142, v142, v54
	v_add_f32_e32 v143, v143, v55
	v_add_f32_e32 v140, v140, v48
	v_add_f32_e32 v141, v141, v49
	v_add_f32_e32 v142, v142, v50
	v_add_f32_e32 v143, v143, v51
	v_add_f32_e32 v140, v140, v44
	v_add_f32_e32 v141, v141, v45
	v_add_f32_e32 v142, v142, v46
	v_add_f32_e32 v143, v143, v47
	v_add_f32_e32 v140, v140, v40
	v_add_f32_e32 v141, v141, v41
	v_add_f32_e32 v142, v142, v42
	v_add_f32_e32 v143, v143, v43
	v_add_f32_e32 v140, v140, v36
	v_add_f32_e32 v141, v141, v37
	v_add_f32_e32 v142, v142, v38
	v_add_f32_e32 v143, v143, v39
	v_add_f32_e32 v140, v140, v32
	v_add_f32_e32 v141, v141, v33
	v_add_f32_e32 v142, v142, v34
	v_add_f32_e32 v143, v143, v35
	v_add_f32_e32 v140, v140, v28
	v_add_f32_e32 v141, v141, v29
	v_add_f32_e32 v142, v142, v30
	v_add_f32_e32 v143, v143, v31
	v_add_f32_e32 v140, v140, v24
	v_add_f32_e32 v141, v141, v25
	v_add_f32_e32 v142, v142, v26
	v_add_f32_e32 v143, v143, v27
	v_add_f32_e32 v140, v140, v20
	v_add_f32_e32 v141, v141, v21
	v_add_f32_e32 v142, v142, v22
	v_add_f32_e32 v143, v143, v23
	v_add_f32_e32 v140, v140, v16
	v_add_f32_e32 v141, v141, v17
	v_add_f32_e32 v142, v142, v18
	v_add_f32_e32 v143, v143, v19
	v_mov_b32_e32 v151, 0x41500000
	v_div_scale_f32 v146, s[26:27], v151, v151, v140
	v_rcp_f32_e32 v147, v146
	v_div_scale_f32 v148, vcc, v140, v151, v140
	v_fma_f32 v149, -v146, v147, 1.0
	v_fmac_f32_e32 v147, v149, v147
	v_mul_f32_e32 v149, v148, v147
	v_fma_f32 v150, -v146, v149, v148
	v_fmac_f32_e32 v149, v150, v147
	v_fma_f32 v146, -v146, v149, v148
	v_div_fmas_f32 v146, v146, v147, v149
	v_div_fixup_f32 v140, v146, v151, v140
	v_mov_b32_e32 v151, 0x41500000
	v_div_scale_f32 v146, s[26:27], v151, v151, v141
	v_rcp_f32_e32 v147, v146
	v_div_scale_f32 v148, vcc, v141, v151, v141
	v_fma_f32 v149, -v146, v147, 1.0
	v_fmac_f32_e32 v147, v149, v147
	v_mul_f32_e32 v149, v148, v147
	v_fma_f32 v150, -v146, v149, v148
	v_fmac_f32_e32 v149, v150, v147
	v_fma_f32 v146, -v146, v149, v148
	v_div_fmas_f32 v146, v146, v147, v149
	v_div_fixup_f32 v141, v146, v151, v141
	v_mov_b32_e32 v151, 0x41500000
	v_div_scale_f32 v146, s[26:27], v151, v151, v142
	v_rcp_f32_e32 v147, v146
	v_div_scale_f32 v148, vcc, v142, v151, v142
	v_fma_f32 v149, -v146, v147, 1.0
	v_fmac_f32_e32 v147, v149, v147
	v_mul_f32_e32 v149, v148, v147
	v_fma_f32 v150, -v146, v149, v148
	v_fmac_f32_e32 v149, v150, v147
	v_fma_f32 v146, -v146, v149, v148
	v_div_fmas_f32 v146, v146, v147, v149
	v_div_fixup_f32 v142, v146, v151, v142
	v_mov_b32_e32 v151, 0x41500000
	v_div_scale_f32 v146, s[26:27], v151, v151, v143
	v_rcp_f32_e32 v147, v146
	v_div_scale_f32 v148, vcc, v143, v151, v143
	v_fma_f32 v149, -v146, v147, 1.0
	v_fmac_f32_e32 v147, v149, v147
	v_mul_f32_e32 v149, v148, v147
	v_fma_f32 v150, -v146, v149, v148
	v_fmac_f32_e32 v149, v150, v147
	v_fma_f32 v146, -v146, v149, v148
	v_div_fmas_f32 v146, v146, v147, v149
	v_div_fixup_f32 v143, v146, v151, v143
	v_sub_f32_e32 v140, v140, v64
	v_sub_f32_e32 v141, v141, v65
	v_sub_f32_e32 v142, v142, v66
	v_sub_f32_e32 v143, v143, v67
	v_cvt_pk_bf16_f32 v144, v140, v141
	v_cvt_pk_bf16_f32 v145, v142, v143
	global_store_dwordx2 v11, v[144:145], s[24:25]
	s_add_u32 s24, s24, 0x800
	s_addc_u32 s25, s25, 0
	s_waitcnt vmcnt(2)
	v_and_b32_e32 v71, 0xffff0000, v69
	v_lshlrev_b32_e32 v70, 16, v69
	v_and_b32_e32 v69, 0xffff0000, v68
	v_lshlrev_b32_e32 v68, 16, v68
	v_add_f32_e32 v140, v68, v64
	v_add_f32_e32 v141, v69, v65
	v_add_f32_e32 v142, v70, v66
	v_add_f32_e32 v143, v71, v67
	v_add_f32_e32 v140, v140, v60
	v_add_f32_e32 v141, v141, v61
	v_add_f32_e32 v142, v142, v62
	v_add_f32_e32 v143, v143, v63
	v_add_f32_e32 v140, v140, v56
	v_add_f32_e32 v141, v141, v57
	v_add_f32_e32 v142, v142, v58
	v_add_f32_e32 v143, v143, v59
	v_add_f32_e32 v140, v140, v52
	v_add_f32_e32 v141, v141, v53
	v_add_f32_e32 v142, v142, v54
	v_add_f32_e32 v143, v143, v55
	v_add_f32_e32 v140, v140, v48
	v_add_f32_e32 v141, v141, v49
	v_add_f32_e32 v142, v142, v50
	v_add_f32_e32 v143, v143, v51
	v_add_f32_e32 v140, v140, v44
	v_add_f32_e32 v141, v141, v45
	v_add_f32_e32 v142, v142, v46
	v_add_f32_e32 v143, v143, v47
	v_add_f32_e32 v140, v140, v40
	v_add_f32_e32 v141, v141, v41
	v_add_f32_e32 v142, v142, v42
	v_add_f32_e32 v143, v143, v43
	v_add_f32_e32 v140, v140, v36
	v_add_f32_e32 v141, v141, v37
	v_add_f32_e32 v142, v142, v38
	v_add_f32_e32 v143, v143, v39
	v_add_f32_e32 v140, v140, v32
	v_add_f32_e32 v141, v141, v33
	v_add_f32_e32 v142, v142, v34
	v_add_f32_e32 v143, v143, v35
	v_add_f32_e32 v140, v140, v28
	v_add_f32_e32 v141, v141, v29
	v_add_f32_e32 v142, v142, v30
	v_add_f32_e32 v143, v143, v31
	v_add_f32_e32 v140, v140, v24
	v_add_f32_e32 v141, v141, v25
	v_add_f32_e32 v142, v142, v26
	v_add_f32_e32 v143, v143, v27
	v_add_f32_e32 v140, v140, v20
	v_add_f32_e32 v141, v141, v21
	v_add_f32_e32 v142, v142, v22
	v_add_f32_e32 v143, v143, v23
	v_add_f32_e32 v140, v140, v16
	v_add_f32_e32 v141, v141, v17
	v_add_f32_e32 v142, v142, v18
	v_add_f32_e32 v143, v143, v19
	v_mov_b32_e32 v151, 0x41600000
	v_div_scale_f32 v146, s[26:27], v151, v151, v140
	v_rcp_f32_e32 v147, v146
	v_div_scale_f32 v148, vcc, v140, v151, v140
	v_fma_f32 v149, -v146, v147, 1.0
	v_fmac_f32_e32 v147, v149, v147
; DI float bflo(unsigned u) { return __uint_as_float(u << 16); }
; DI float bfhi(unsigned u) { return __uint_as_float(u & 0xffff0000u); }
; template <int WIN>
; DI void pool_elem(const Params& p, int row, int c) {
;     ...
;     } else {
;       cnt = (float)(t + 1);
;       for (int j = 1; j <= t; ++j) {
;         unsigned w = *(const unsigned*)(P2 + (size_t)(row - j) * 2048 + c);
;         s0 += bflo(w); s1 += bfhi(w);
;       }
;     ...
;   *(unsigned*)(p.MIX + (size_t)row * 1024 + c) = pack2(s0 / cnt - u0, s1 / cnt - u1);
	v_mul_f32_e32 v149, v148, v147
	v_fma_f32 v150, -v146, v149, v148
	v_fmac_f32_e32 v149, v150, v147
	v_fma_f32 v146, -v146, v149, v148
	v_div_fmas_f32 v146, v146, v147, v149
	v_div_fixup_f32 v140, v146, v151, v140
	v_mov_b32_e32 v151, 0x41600000
	v_div_scale_f32 v146, s[26:27], v151, v151, v141
	v_rcp_f32_e32 v147, v146
	v_div_scale_f32 v148, vcc, v141, v151, v141
	v_fma_f32 v149, -v146, v147, 1.0
	v_fmac_f32_e32 v147, v149, v147
	v_mul_f32_e32 v149, v148, v147
	v_fma_f32 v150, -v146, v149, v148
	v_fmac_f32_e32 v149, v150, v147
	v_fma_f32 v146, -v146, v149, v148
	v_div_fmas_f32 v146, v146, v147, v149
	v_div_fixup_f32 v141, v146, v151, v141
	v_mov_b32_e32 v151, 0x41600000
	v_div_scale_f32 v146, s[26:27], v151, v151, v142
	v_rcp_f32_e32 v147, v146
	v_div_scale_f32 v148, vcc, v142, v151, v142
	v_fma_f32 v149, -v146, v147, 1.0
	v_fmac_f32_e32 v147, v149, v147
	v_mul_f32_e32 v149, v148, v147
	v_fma_f32 v150, -v146, v149, v148
	v_fmac_f32_e32 v149, v150, v147
	v_fma_f32 v146, -v146, v149, v148
	v_div_fmas_f32 v146, v146, v147, v149
	v_div_fixup_f32 v142, v146, v151, v142
	v_mov_b32_e32 v151, 0x41600000
	v_div_scale_f32 v146, s[26:27], v151, v151, v143
	v_rcp_f32_e32 v147, v146
	v_div_scale_f32 v148, vcc, v143, v151, v143
	v_fma_f32 v149, -v146, v147, 1.0
	v_fmac_f32_e32 v147, v149, v147
	v_mul_f32_e32 v149, v148, v147
	v_fma_f32 v150, -v146, v149, v148
	v_fmac_f32_e32 v149, v150, v147
	v_fma_f32 v146, -v146, v149, v148
	v_div_fmas_f32 v146, v146, v147, v149
	v_div_fixup_f32 v143, v146, v151, v143
	v_sub_f32_e32 v140, v140, v68
	v_sub_f32_e32 v141, v141, v69
	v_sub_f32_e32 v142, v142, v70
	v_sub_f32_e32 v143, v143, v71
	v_cvt_pk_bf16_f32 v144, v140, v141
	v_cvt_pk_bf16_f32 v145, v142, v143
	global_store_dwordx2 v11, v[144:145], s[24:25]
	s_add_u32 s24, s24, 0x800
	s_addc_u32 s25, s25, 0
	s_waitcnt vmcnt(1)
	v_and_b32_e32 v75, 0xffff0000, v73
	v_lshlrev_b32_e32 v74, 16, v73
	v_and_b32_e32 v73, 0xffff0000, v72
	v_lshlrev_b32_e32 v72, 16, v72
	v_add_f32_e32 v140, v72, v68
	v_add_f32_e32 v141, v73, v69
	v_add_f32_e32 v142, v74, v70
	v_add_f32_e32 v143, v75, v71
	v_add_f32_e32 v140, v140, v64
	v_add_f32_e32 v141, v141, v65
	v_add_f32_e32 v142, v142, v66
	v_add_f32_e32 v143, v143, v67
	v_add_f32_e32 v140, v140, v60
	v_add_f32_e32 v141, v141, v61
	v_add_f32_e32 v142, v142, v62
	v_add_f32_e32 v143, v143, v63
	v_add_f32_e32 v140, v140, v56
	v_add_f32_e32 v141, v141, v57
	v_add_f32_e32 v142, v142, v58
	v_add_f32_e32 v143, v143, v59
	v_add_f32_e32 v140, v140, v52
	v_add_f32_e32 v141, v141, v53
	v_add_f32_e32 v142, v142, v54
	v_add_f32_e32 v143, v143, v55
	v_add_f32_e32 v140, v140, v48
	v_add_f32_e32 v141, v141, v49
	v_add_f32_e32 v142, v142, v50
	v_add_f32_e32 v143, v143, v51
	v_add_f32_e32 v140, v140, v44
	v_add_f32_e32 v141, v141, v45
	v_add_f32_e32 v142, v142, v46
	v_add_f32_e32 v143, v143, v47
	v_add_f32_e32 v140, v140, v40
	v_add_f32_e32 v141, v141, v41
	v_add_f32_e32 v142, v142, v42
	v_add_f32_e32 v143, v143, v43
	v_add_f32_e32 v140, v140, v36
	v_add_f32_e32 v141, v141, v37
	v_add_f32_e32 v142, v142, v38
	v_add_f32_e32 v143, v143, v39
	v_add_f32_e32 v140, v140, v32
	v_add_f32_e32 v141, v141, v33
	v_add_f32_e32 v142, v142, v34
	v_add_f32_e32 v143, v143, v35
	v_add_f32_e32 v140, v140, v28
	v_add_f32_e32 v141, v141, v29
	v_add_f32_e32 v142, v142, v30
	v_add_f32_e32 v143, v143, v31
	v_add_f32_e32 v140, v140, v24
	v_add_f32_e32 v141, v141, v25
	v_add_f32_e32 v142, v142, v26
	v_add_f32_e32 v143, v143, v27
	v_add_f32_e32 v140, v140, v20
	v_add_f32_e32 v141, v141, v21
	v_add_f32_e32 v142, v142, v22
	v_add_f32_e32 v143, v143, v23
	v_add_f32_e32 v140, v140, v16
	v_add_f32_e32 v141, v141, v17
	v_add_f32_e32 v142, v142, v18
	v_add_f32_e32 v143, v143, v19
	v_mov_b32_e32 v151, 0x41700000
	v_div_scale_f32 v146, s[26:27], v151, v151, v140
	v_rcp_f32_e32 v147, v146
	v_div_scale_f32 v148, vcc, v140, v151, v140
	v_fma_f32 v149, -v146, v147, 1.0
	v_fmac_f32_e32 v147, v149, v147
	v_mul_f32_e32 v149, v148, v147
	v_fma_f32 v150, -v146, v149, v148
	v_fmac_f32_e32 v149, v150, v147
	v_fma_f32 v146, -v146, v149, v148
	v_div_fmas_f32 v146, v146, v147, v149
	v_div_fixup_f32 v140, v146, v151, v140
	v_mov_b32_e32 v151, 0x41700000
	v_div_scale_f32 v146, s[26:27], v151, v151, v141
	v_rcp_f32_e32 v147, v146
	v_div_scale_f32 v148, vcc, v141, v151, v141
	v_fma_f32 v149, -v146, v147, 1.0
	v_fmac_f32_e32 v147, v149, v147
	v_mul_f32_e32 v149, v148, v147
	v_fma_f32 v150, -v146, v149, v148
	v_fmac_f32_e32 v149, v150, v147
	v_fma_f32 v146, -v146, v149, v148
	v_div_fmas_f32 v146, v146, v147, v149
	v_div_fixup_f32 v141, v146, v151, v141
	v_mov_b32_e32 v151, 0x41700000
	v_div_scale_f32 v146, s[26:27], v151, v151, v142
	v_rcp_f32_e32 v147, v146
	v_div_scale_f32 v148, vcc, v142, v151, v142
	v_fma_f32 v149, -v146, v147, 1.0
	v_fmac_f32_e32 v147, v149, v147
	v_mul_f32_e32 v149, v148, v147
	v_fma_f32 v150, -v146, v149, v148
	v_fmac_f32_e32 v149, v150, v147
	v_fma_f32 v146, -v146, v149, v148
	v_div_fmas_f32 v146, v146, v147, v149
	v_div_fixup_f32 v142, v146, v151, v142
	v_mov_b32_e32 v151, 0x41700000
	v_div_scale_f32 v146, s[26:27], v151, v151, v143
	v_rcp_f32_e32 v147, v146
	v_div_scale_f32 v148, vcc, v143, v151, v143
	v_fma_f32 v149, -v146, v147, 1.0
	v_fmac_f32_e32 v147, v149, v147
	v_mul_f32_e32 v149, v148, v147
	v_fma_f32 v150, -v146, v149, v148
	v_fmac_f32_e32 v149, v150, v147
	v_fma_f32 v146, -v146, v149, v148
	v_div_fmas_f32 v146, v146, v147, v149
	v_div_fixup_f32 v143, v146, v151, v143
	v_sub_f32_e32 v140, v140, v72
	v_sub_f32_e32 v141, v141, v73
	v_sub_f32_e32 v142, v142, v74
	v_sub_f32_e32 v143, v143, v75
	v_cvt_pk_bf16_f32 v144, v140, v141
	v_cvt_pk_bf16_f32 v145, v142, v143
	global_store_dwordx2 v11, v[144:145], s[24:25]
	s_add_u32 s24, s24, 0x800
	s_addc_u32 s25, s25, 0
	s_waitcnt vmcnt(0)
; DI float bflo(unsigned u) { return __uint_as_float(u << 16); }
; DI float bfhi(unsigned u) { return __uint_as_float(u & 0xffff0000u); }
; template <int WIN>
; DI void pool_elem(const Params& p, int row, int c) {
;     ...
;     } else {
;       cnt = (float)(t + 1);
;       for (int j = 1; j <= t; ++j) {
;         unsigned w = *(const unsigned*)(P2 + (size_t)(row - j) * 2048 + c);
;         s0 += bflo(w); s1 += bfhi(w);
;       }
;     ...
;   *(unsigned*)(p.MIX + (size_t)row * 1024 + c) = pack2(s0 / cnt - u0, s1 / cnt - u1);
; DI void phase_pool(const Params& p) {
;   for (int idx = blockIdx.x * 256 + threadIdx.x; idx < NROW * 512; idx += gridDim.x * 256) {
;     const int row = idx >> 9, c = (idx & 511) * 2;
;     const int gi = c >> 8;
;     if (gi == 0) pool_elem<2>(p, row, c);
;     else if (gi == 1) pool_elem<4>(p, row, c);
;     else if (gi == 2) pool_elem<8>(p, row, c);
;     else pool_elem<16>(p, row, c);
;   }
	v_and_b32_e32 v79, 0xffff0000, v77
	v_lshlrev_b32_e32 v78, 16, v77
	v_and_b32_e32 v77, 0xffff0000, v76
	v_lshlrev_b32_e32 v76, 16, v76
	v_add_f32_e32 v140, v76, v72
	v_add_f32_e32 v141, v77, v73
	v_add_f32_e32 v142, v78, v74
	v_add_f32_e32 v143, v79, v75
	v_add_f32_e32 v140, v140, v68
	v_add_f32_e32 v141, v141, v69
	v_add_f32_e32 v142, v142, v70
	v_add_f32_e32 v143, v143, v71
	v_add_f32_e32 v140, v140, v64
	v_add_f32_e32 v141, v141, v65
	v_add_f32_e32 v142, v142, v66
	v_add_f32_e32 v143, v143, v67
	v_add_f32_e32 v140, v140, v60
	v_add_f32_e32 v141, v141, v61
	v_add_f32_e32 v142, v142, v62
	v_add_f32_e32 v143, v143, v63
	v_add_f32_e32 v140, v140, v56
	v_add_f32_e32 v141, v141, v57
	v_add_f32_e32 v142, v142, v58
	v_add_f32_e32 v143, v143, v59
	v_add_f32_e32 v140, v140, v52
	v_add_f32_e32 v141, v141, v53
	v_add_f32_e32 v142, v142, v54
	v_add_f32_e32 v143, v143, v55
	v_add_f32_e32 v140, v140, v48
	v_add_f32_e32 v141, v141, v49
	v_add_f32_e32 v142, v142, v50
	v_add_f32_e32 v143, v143, v51
	v_add_f32_e32 v140, v140, v44
	v_add_f32_e32 v141, v141, v45
	v_add_f32_e32 v142, v142, v46
	v_add_f32_e32 v143, v143, v47
	v_add_f32_e32 v140, v140, v40
	v_add_f32_e32 v141, v141, v41
	v_add_f32_e32 v142, v142, v42
	v_add_f32_e32 v143, v143, v43
	v_add_f32_e32 v140, v140, v36
	v_add_f32_e32 v141, v141, v37
	v_add_f32_e32 v142, v142, v38
	v_add_f32_e32 v143, v143, v39
	v_add_f32_e32 v140, v140, v32
	v_add_f32_e32 v141, v141, v33
	v_add_f32_e32 v142, v142, v34
	v_add_f32_e32 v143, v143, v35
	v_add_f32_e32 v140, v140, v28
	v_add_f32_e32 v141, v141, v29
	v_add_f32_e32 v142, v142, v30
	v_add_f32_e32 v143, v143, v31
	v_add_f32_e32 v140, v140, v24
	v_add_f32_e32 v141, v141, v25
	v_add_f32_e32 v142, v142, v26
	v_add_f32_e32 v143, v143, v27
	v_add_f32_e32 v140, v140, v20
	v_add_f32_e32 v141, v141, v21
	v_add_f32_e32 v142, v142, v22
	v_add_f32_e32 v143, v143, v23
	v_add_f32_e32 v140, v140, v16
	v_add_f32_e32 v141, v141, v17
	v_add_f32_e32 v142, v142, v18
	v_add_f32_e32 v143, v143, v19
	v_mul_f32_e32 v140, 0x3d800000, v140
	v_mul_f32_e32 v141, 0x3d800000, v141
	v_mul_f32_e32 v142, 0x3d800000, v142
	v_mul_f32_e32 v143, 0x3d800000, v143
	v_sub_f32_e32 v140, v140, v76
	v_sub_f32_e32 v141, v141, v77
	v_sub_f32_e32 v142, v142, v78
	v_sub_f32_e32 v143, v143, v79
	v_cvt_pk_bf16_f32 v144, v140, v141
	v_cvt_pk_bf16_f32 v145, v142, v143
	global_store_dwordx2 v11, v[144:145], s[24:25]
	s_add_u32 s24, s24, 0x800
	s_addc_u32 s25, s25, 0
	s_branch .Lp13f_next
.Lp13f_next:
	s_add_u32 s15, s15, s34
	s_xor_b32 s14, s14, 3
	s_branch .Lp13f_loop

; template <int WIN>
; DI void pool_elem(const Params& p, int row, int c) {
;     ...
;   } else {
;     const int s = row - NPR;
;     cnt = (float)WIN;
;     const float* sp = p.state_pool + (size_t)s * 15 * 1024 + c;
;     float2 st[15];
; #pragma unroll
;     for (int j = 0; j < 15; ++j) st[j] = *(const float2*)(sp + (size_t)j * 1024);
; #pragma unroll
;     for (int j = 1; j < WIN; ++j) { s0 += st[15 - j].x; s1 += st[15 - j].y; }
;     float* op = p.out + O_POOLS + (size_t)s * 15 * 1024 + c;
; #pragma unroll
;     for (int j = 0; j < 14; ++j) *(float2*)(op + (size_t)j * 1024) = st[j + 1];
;     float2 o = {u0, u1};
;     *(float2*)(op + (size_t)14 * 1024) = o;
;   }
; DI void phase_pool(const Params& p) {
;   for (int idx = blockIdx.x * 256 + threadIdx.x; idx < NROW * 512; idx += gridDim.x * 256) {
;     const int row = idx >> 9, c = (idx & 511) * 2;
;     const int gi = c >> 8;
;     if (gi == 0) pool_elem<2>(p, row, c);
;     else if (gi == 1) pool_elem<4>(p, row, c);
;     else if (gi == 2) pool_elem<8>(p, row, c);
;     else pool_elem<16>(p, row, c);
;   }
.LBB0_1252:
	v_readfirstlane_b32 s98, v14
	s_nop 3
	s_lshr_b32 s99, s98, 9
	s_cmp_lt_u32 s99, 0x4000
	s_cbranch_scc1 .Lp13_skip
	v_lshlrev_b32_e32 v0, 1, v14
	v_and_b32_e32 v0, 0x3fe, v0
	v_ashrrev_i32_e32 v2, 9, v14
	v_cmp_lt_u32_e32 vcc, s48, v0
	s_and_saveexec_b64 s[0:1], vcc
	s_xor_b64 s[38:39], exec, s[0:1]
	s_cbranch_execz .LBB0_1286
	v_ashrrev_i32_e32 v3, 31, v2
	v_lshlrev_b64 v[8:9], 12, v[2:3]
	v_lshl_add_u64 v[4:5], s[20:21], 0, v[8:9]
	v_lshlrev_b32_e32 v6, 1, v0
	v_mov_b32_e32 v7, v1
	v_lshl_add_u64 v[4:5], v[4:5], 0, v[6:7]
	global_load_dword v5, v[4:5], off
	v_lshrrev_b32_e32 v7, 8, v0
	v_lshlrev_b32_e32 v4, 1, v15
	v_cmp_lt_i32_e64 s[0:1], s49, v2
	v_mov_b32_e32 v11, v1
	v_and_b32_e32 v10, 0x7fc, v4
	v_cmp_lt_i32_e32 vcc, 1, v7
	s_waitcnt vmcnt(0)
	v_lshlrev_b32_e32 v4, 16, v5
	v_and_b32_e32 v5, 0xffff0000, v5
	s_and_saveexec_b64 s[4:5], vcc
	s_xor_b64 s[40:41], exec, s[4:5]
	s_cbranch_execz .LBB0_1275
	v_cmp_ne_u32_e32 vcc, 2, v7
	s_and_saveexec_b64 s[4:5], vcc
	s_xor_b64 s[42:43], exec, s[4:5]
	s_cbranch_execz .LBB0_1264
	s_and_saveexec_b64 s[4:5], s[0:1]
	s_xor_b64 s[44:45], exec, s[4:5]
	s_cbranch_execz .LBB0_1257
	v_add_u32_e32 v42, 0xffffc000, v2
	v_mov_b64_e32 v[6:7], s[18:19]
	v_mad_u64_u32 v[6:7], s[4:5], v42, s51, v[6:7]
	v_lshlrev_b32_e32 v8, 2, v0
	v_mov_b32_e32 v9, v1
	v_lshl_add_u64 v[6:7], v[6:7], 0, v[8:9]
	v_add_co_u32_e32 v10, vcc, 0x1000, v6
	v_mov_b64_e32 v[40:41], s[24:25]
	s_nop 0
	v_addc_co_u32_e32 v11, vcc, 0, v7, vcc
	v_add_co_u32_e32 v12, vcc, 0x2000, v6
	s_mov_b64 s[4:5], vcc
	v_add_co_u32_e32 v16, vcc, 0x3000, v6
	s_mov_b64 s[6:7], vcc
	v_add_co_u32_e32 v18, vcc, 0x4000, v6
	s_mov_b64 s[8:9], vcc
	v_add_co_u32_e32 v20, vcc, 0x5000, v6
	s_mov_b64 s[10:11], vcc
	v_add_co_u32_e32 v22, vcc, 0x6000, v6
	s_mov_b64 s[12:13], vcc
	v_add_co_u32_e32 v24, vcc, 0x7000, v6
	s_mov_b64 s[14:15], vcc
	v_add_co_u32_e32 v26, vcc, 0x8000, v6
	global_load_dwordx2 v[10:11], v[10:11], off
	s_nop 0
	v_addc_co_u32_e32 v27, vcc, 0, v7, vcc
	v_add_co_u32_e32 v28, vcc, 0x9000, v6
	s_nop 1
	v_addc_co_u32_e32 v29, vcc, 0, v7, vcc
	v_add_co_u32_e32 v30, vcc, 0xa000, v6
	s_nop 1
	v_addc_co_u32_e32 v31, vcc, 0, v7, vcc
	v_add_co_u32_e32 v32, vcc, 0xb000, v6
	s_mov_b64 s[16:17], vcc
	v_add_co_u32_e32 v34, vcc, 0xc000, v6
	s_nop 1
	v_addc_co_u32_e32 v35, vcc, 0, v7, vcc
	v_add_co_u32_e32 v36, vcc, 0xd000, v6
	s_nop 1
	v_addc_co_u32_e32 v37, vcc, 0, v7, vcc
	v_add_co_u32_e32 v38, vcc, 0xe000, v6
	s_nop 1
	v_addc_co_u32_e32 v39, vcc, 0, v7, vcc
	global_load_dwordx2 v[34:35], v[34:35], off
	s_nop 0
	global_load_dwordx2 v[36:37], v[36:37], off
	s_nop 0
	global_load_dwordx2 v[38:39], v[38:39], off
	v_addc_co_u32_e64 v33, vcc, 0, v7, s[16:17]
	v_addc_co_u32_e64 v13, vcc, 0, v7, s[4:5]
	v_addc_co_u32_e64 v17, vcc, 0, v7, s[6:7]
	global_load_dwordx2 v[32:33], v[32:33], off
	s_nop 0
	global_load_dwordx2 v[30:31], v[30:31], off
	s_nop 0
	global_load_dwordx2 v[28:29], v[28:29], off
	s_nop 0
	global_load_dwordx2 v[26:27], v[26:27], off
	s_nop 0
	global_load_dwordx2 v[12:13], v[12:13], off
	s_nop 0
	global_load_dwordx2 v[16:17], v[16:17], off
	v_addc_co_u32_e64 v19, vcc, 0, v7, s[8:9]
	v_addc_co_u32_e64 v21, vcc, 0, v7, s[10:11]
	global_load_dwordx2 v[18:19], v[18:19], off
	s_nop 0
	global_load_dwordx2 v[20:21], v[20:21], off
	v_addc_co_u32_e64 v23, vcc, 0, v7, s[12:13]
	v_addc_co_u32_e64 v25, vcc, 0, v7, s[14:15]
	global_load_dwordx2 v[22:23], v[22:23], off
	s_nop 0
	global_load_dwordx2 v[24:25], v[24:25], off
	s_nop 0
	global_load_dwordx2 v[6:7], v[6:7], off
	v_mad_u64_u32 v[40:41], s[4:5], v42, s51, v[40:41]
	v_lshl_add_u64 v[8:9], v[40:41], 0, v[8:9]
	v_add_co_u32_e32 v42, vcc, s52, v8
	s_waitcnt vmcnt(14)
	global_store_dwordx2 v[8:9], v[10:11], off
	v_addc_co_u32_e32 v43, vcc, 0, v9, vcc
	s_waitcnt vmcnt(7)
	global_store_dwordx2 v[42:43], v[12:13], off offset:-4096
	s_waitcnt vmcnt(7)
	global_store_dwordx2 v[42:43], v[16:17], off
	v_pk_add_f32 v[40:41], v[4:5], v[38:39]
	v_add_co_u32_e32 v42, vcc, s53, v8
	v_pk_add_f32 v[40:41], v[40:41], v[36:37]
	s_nop 0
	v_addc_co_u32_e32 v43, vcc, 0, v9, vcc
	v_pk_add_f32 v[40:41], v[40:41], v[34:35]
	s_waitcnt vmcnt(7)
	global_store_dwordx2 v[42:43], v[18:19], off offset:-4096
	s_waitcnt vmcnt(7)
	global_store_dwordx2 v[42:43], v[20:21], off
	v_pk_add_f32 v[40:41], v[40:41], v[32:33]
	v_add_co_u32_e32 v42, vcc, s54, v8
	v_pk_add_f32 v[40:41], v[40:41], v[30:31]
	s_nop 0
	v_addc_co_u32_e32 v43, vcc, 0, v9, vcc
	v_pk_add_f32 v[40:41], v[40:41], v[28:29]
	s_waitcnt vmcnt(7)
	global_store_dwordx2 v[42:43], v[22:23], off offset:-4096
	s_waitcnt vmcnt(7)
	global_store_dwordx2 v[42:43], v[24:25], off
	v_pk_add_f32 v[40:41], v[40:41], v[26:27]
	v_add_co_u32_e32 v42, vcc, s55, v8
	v_pk_add_f32 v[24:25], v[40:41], v[24:25]
	s_nop 0
	v_addc_co_u32_e32 v43, vcc, 0, v9, vcc
	global_store_dwordx2 v[42:43], v[26:27], off offset:-4096
	global_store_dwordx2 v[42:43], v[28:29], off
	v_add_co_u32_e32 v26, vcc, s56, v8
	v_pk_add_f32 v[22:23], v[24:25], v[22:23]
	s_nop 0
	v_addc_co_u32_e32 v27, vcc, 0, v9, vcc
	v_pk_add_f32 v[20:21], v[22:23], v[20:21]
	global_store_dwordx2 v[26:27], v[30:31], off offset:-4096
	global_store_dwordx2 v[26:27], v[32:33], off
	v_add_co_u32_e32 v26, vcc, s58, v8
	v_pk_add_f32 v[18:19], v[20:21], v[18:19]
	s_nop 0
	v_addc_co_u32_e32 v27, vcc, 0, v9, vcc
	v_pk_add_f32 v[16:17], v[18:19], v[16:17]
	global_store_dwordx2 v[26:27], v[34:35], off offset:-4096
	global_store_dwordx2 v[26:27], v[36:37], off
	v_add_co_u32_e32 v26, vcc, s59, v8
	v_pk_add_f32 v[12:13], v[16:17], v[12:13]
	s_nop 0
	v_addc_co_u32_e32 v27, vcc, 0, v9, vcc
	v_pk_add_f32 v[10:11], v[12:13], v[10:11]
	global_store_dwordx2 v[26:27], v[38:39], off
	s_waitcnt vmcnt(14)
	v_pk_add_f32 v[12:13], v[6:7], v[10:11]
	v_add_co_u32_e32 v6, vcc, 0xe000, v8
	s_nop 1
	v_addc_co_u32_e32 v7, vcc, 0, v9, vcc
	global_store_dwordx2 v[6:7], v[4:5], off
